# attention fixref loops: m0 save/restore around LDS-DMA removed, x+0 adds removed; plus hyena prologue prefetch
# speedup vs baseline: 1.0071x; 1.0055x over previous
; __device__ __forceinline__ int fresh_tid() { int t = threadIdx.x; asm volatile("" : "+v"(t)); return t; }
; #define WAIT_BAR(N) asm volatile("s_waitcnt vmcnt(" #N ") lgkmcnt(0)\n\ts_barrier":::"memory")
;   #define CMASK(P0,P1,t) do{}while(0)
; template<int THRL,bool FIXREF,bool HALFK> __device__ __forceinline__ void attn_unit(float mref,long rowbase,int q0,const bf16*Qh,int PQ,const bf16*__restrict__ Kh_,int PK,const bf16*__restrict__ Vh_,int PV,bf16*Oh,int PO,const bf16*Gh,int PG,u32x4(&okeep)[4],int omode,float lam,float oml,const float ...
;   const int tid=fresh_tid(),lane=tid&63,r32=lane&31,hi=lane>>5; const int wid=__builtin_amdgcn_readfirstlane(tid>>6);
;   const bf16*Qw=Qh+(rowbase+q0+wid*QBLK)*PQ;
;   const bf16*Kh=Kh_+rowbase*PK,*Vh=Vh_+rowbase*PV;
;   const unsigned lds0=(unsigned)(uintptr_t)shm;
;   float*wsf=(float*)(shm+LDS_WS)+wid*64;
;   const bf16*ksrc=Kh+(long)lane*PK+wid*8;
;   const bf16*vsrc=Vh+(long)(16*(wid&3)+(lane>>2))*PV+(wid>>2)*32+(lane&3)*8;
;   const unsigned kdst=lds0+LDS_K+wid*1024, vdst=lds0+LDS_V+wid*1024;
;     ...
;   const int vb0=(int)(lds0+LDS_V)+((lane>>4)&1)*32+(lane&3)*8+(4*hi+((lane&15)>>2))*64;
;   const char*Kbase=shm+LDS_K; bf16x8 kf[8];
;   const lds_cptr shm3=(lds_cptr)shm; const lds_cptr kp0=shm3+LDS_K+hi*1024+r32*16; const lds_cptr vp0=shm3+LDS_V+((lane>>4)&1)*32+(lane&3)*8+(4*hi+((lane&15)>>2))*64;
;   constexpr int NT=SEQ/KVBLK;
;   if(Gh){ const bf16*Gw=Gh+(rowbase+q0+wid*QBLK)*PG;
;     #pragma unroll
;     for(int i=0;i<4;++i) glds16(Gw+(long)(i*8+(lane>>3))*PG+(lane&7)*8,(unsigned)__builtin_amdgcn_readfirstlane(lds0+LDS_GST+wid*4096+i*1024)); }
;   DMA_K(0,0);DMA_V(0,0);DMA_K(1,SLOTB);
;   bf16x8 qr[4];
;   #pragma unroll
;   for(int d0=0;d0<4;++d0)qr[d0]=*reinterpret_cast<const bf16x8*>(&Qw[(long)r32*PQ+d0*16+hi*8]);
;   float mhat=0.f,l_reg=0.f;f32x16 o[2];o[0]=f32x16{};o[1]=f32x16{};f32x16 negm=f32x16{};
;   if constexpr(FIXREF){ mhat=mref; _Pragma("unroll") for(int r=0;r<16;++r)negm[r]=-mref; }
;   asm volatile("":"+v"(negm));
;     ...
;   bool resc=false;
;     ...
;   f32x16 pA0,pA1,pB0,pB1;
;   int sl_prev=0,sl_cur=0,sl_next=SLOTB;
;     ...
;   DMA_K(2,2*SLOTB);
;   WAIT_BAR(3);
;   qkt<HALFK?2:4>(pA0,pA1,Kbase,qr,negm,r32,hi);asm volatile("s_nop 15\n\ts_nop 7":"+v"(pA0),"+v"(pA1));CMASK(pA0,pA1,0);
;   START(pA0,pA1);
;   _Pragma("unroll") for(int r=0;r<16;++r)pA1[r]=__builtin_amdgcn_exp2f(pA1[r]);
;   WAIT_BAR(0);
.LBB0_450:
	s_bfe_u32 s16, s58, 0x20004
	s_lshl_b32 s59, s16, 6
	s_and_b32 s67, s59, 0x80
	s_ashr_i32 s42, s58, 6
	s_lshl_b32 s16, s16, 7
	s_add_u32 s46, s2, s16
	s_addc_u32 s47, s3, 0
	s_lshl_b32 s17, s58, 2
	s_and_b32 s17, s17, 0x80
	s_add_u32 s60, s14, s17
	s_addc_u32 s61, s15, 0
	s_add_u32 s62, s20, s17
	s_addc_u32 s63, s28, 0
	s_add_u32 s65, s34, s16
	v_mov_b32_e32 v104, v218
	s_addc_u32 s66, s35, 0
	s_ashr_i32 s43, s42, 31
	s_lshl_b32 s40, s58, 8
	s_lshl_b64 s[16:17], s[42:43], 12
	v_readfirstlane_b32 s64, v104
	s_and_b32 s40, s40, 0xf00
	s_ashr_i32 s73, s64, 6
	s_or_b32 s16, s16, s40
	s_lshl_b32 s40, s73, 5
	s_ashr_i32 s41, s40, 31
	s_add_u32 s16, s16, s40
	s_addc_u32 s17, s17, s41
	s_lshl_b64 s[40:41], s[16:17], 9
	s_add_u32 s48, s46, s40
	s_addc_u32 s49, s47, s41
	s_lshl_b64 s[40:41], s[42:43], 20
	s_add_u32 s46, s60, s40
	s_addc_u32 s47, s61, s41
	s_mul_i32 s69, s42, 0x1e00000
	s_mul_hi_i32 s68, s42, 0x1e00000
	s_add_u32 s60, s62, s69
	v_and_b32_e32 v205, 63, v104
	s_addc_u32 s61, s63, s68
	s_lshl_b32 s42, s73, 3
	v_lshlrev_b32_e32 v0, 8, v205
	s_ashr_i32 s43, s42, 31
	v_lshl_add_u64 v[18:19], s[46:47], 0, v[0:1]
	s_lshl_b64 s[42:43], s[42:43], 1
	v_lshl_add_u64 v[210:211], v[18:19], 0, s[42:43]
	s_lshl_b32 s46, s73, 4
	v_bfe_u32 v18, v104, 2, 4
	v_and_or_b32 v18, s46, 48, v18
	s_ashr_i32 s46, s64, 3
	s_andn2_b32 s46, s46, 31
	s_ashr_i32 s47, s46, 31
	s_lshl_b64 s[46:47], s[46:47], 1
	s_lshl_b32 s63, s73, 10
	v_mul_u32_u24_e32 v18, 0xf00, v18
	s_cmp_lg_u32 0, -1
	v_lshlrev_b32_e32 v102, 1, v18
	v_mov_b32_e32 v103, v1
	s_cselect_b32 s75, 0, 0
	v_lshl_add_u64 v[18:19], s[60:61], 0, v[102:103]
	v_lshlrev_b32_e32 v22, 3, v104
	s_add_i32 s62, s63, s75
	s_mul_i32 s60, s17, 0x1e00
	s_mul_hi_u32 s70, s16, 0x1e00
	v_and_b32_e32 v229, 24, v22
	s_add_i32 s61, s62, 0x6000
	s_add_i32 s60, s70, s60
	s_mul_i32 s70, s16, 0x1e00
	v_lshl_add_u64 v[18:19], v[18:19], 0, s[46:47]
	v_lshlrev_b32_e32 v20, 1, v229
	v_mov_b32_e32 v21, v1
	s_add_u32 s70, s65, s70
	v_bfe_u32 v203, v104, 3, 3
	v_and_b32_e32 v206, 56, v22
	v_lshl_add_u64 v[208:209], v[18:19], 0, v[20:21]
	s_addc_u32 s71, s66, s60
	v_lshlrev_b32_e32 v18, 1, v206
	v_mov_b32_e32 v19, v1
	s_lshl_b32 s60, s73, 12
	v_mul_u32_u24_e32 v20, 0xf00, v203
	v_lshl_add_u64 v[18:19], s[70:71], 0, v[18:19]
	v_lshlrev_b32_e32 v20, 1, v20
	s_add_i32 s65, s75, s60
	v_lshl_add_u64 v[18:19], v[18:19], 0, v[20:21]
	s_add_i32 s66, s65, 0x14800
	s_mov_b32 m0, s66
	s_nop 0
	global_load_lds_dwordx4 v[18:19], off
	v_lshl_add_u64 v[20:21], v[18:19], 0, s[30:31]
	s_add_i32 s66, s65, 0x14c00
	s_mov_b32 m0, s66
	s_nop 0
	global_load_lds_dwordx4 v[20:21], off
	v_lshl_add_u64 v[20:21], v[18:19], 0, s[56:57]
	s_add_i32 s66, s65, 0x15000
	s_mov_b32 m0, s66
	s_nop 0
	global_load_lds_dwordx4 v[20:21], off
	v_lshl_add_u64 v[18:19], v[18:19], 0, s[8:9]
	s_add_i32 s65, s65, 0x15400
	s_mov_b32 m0, s65
	s_nop 0
	global_load_lds_dwordx4 v[18:19], off
	s_mov_b32 m0, s62
	s_nop 0
	global_load_lds_dwordx4 v[210:211], off
	s_mov_b64 s[70:71], 0x4000
	v_and_b32_e32 v216, 31, v104
	s_mov_b32 m0, s61
	s_nop 0
	global_load_lds_dwordx4 v[208:209], off
	v_lshl_add_u64 v[18:19], v[210:211], 0, s[70:71]
	v_bfe_u32 v217, v104, 5, 1
	s_add_i32 s65, s62, 0x2000
	s_mov_b32 m0, s65
	s_nop 0
	global_load_lds_dwordx4 v[18:19], off
	v_lshlrev_b32_e32 v18, 9, v216
	v_lshl_or_b32 v18, v217, 4, v18
	global_load_dwordx4 v[174:177], v18, s[48:49]
	global_load_dwordx4 v[170:173], v18, s[48:49] offset:32
	global_load_dwordx4 v[162:165], v18, s[48:49] offset:64
	global_load_dwordx4 v[154:157], v18, s[48:49] offset:96
	v_mov_b64_e32 v[64:65], v[16:17]
	v_lshlrev_b32_e32 v18, 10, v217
	v_lshlrev_b32_e32 v19, 4, v216
	v_mov_b64_e32 v[62:63], v[14:15]
	v_mov_b64_e32 v[60:61], v[12:13]
	v_mov_b64_e32 v[58:59], v[10:11]
	v_mov_b64_e32 v[56:57], v[8:9]
	v_mov_b64_e32 v[54:55], v[6:7]
	v_mov_b64_e32 v[52:53], v[4:5]
	v_mov_b64_e32 v[50:51], v[2:3]
	v_add3_u32 v228, 0, v18, v19
	v_lshl_add_u64 v[18:19], v[210:211], 0, s[10:11]
	s_add_i32 s48, s62, 0x4000
	s_mov_b32 m0, s48
	s_nop 0
	global_load_lds_dwordx4 v[18:19], off
	s_waitcnt vmcnt(3) lgkmcnt(0)
	s_barrier
	ds_read_b128 v[18:21], v228
	ds_read_b128 v[66:69], v228 offset:512
	s_or_b32 s69, s69, s67
	s_waitcnt vmcnt(3) lgkmcnt(1)
	v_mfma_f32_32x32x16_bf16 v[34:49], v[18:21], v[174:177], v[50:65]
	v_mov_b32_e32 v232, 0
	s_mov_b32 s48, -1
	s_mov_b32 s66, 0
	s_movk_i32 s65, 0x2000
	s_movk_i32 s49, 0x4000
	s_waitcnt lgkmcnt(0)
	v_mfma_f32_32x32x16_bf16 v[18:33], v[66:69], v[174:177], v[50:65]
	ds_read_b128 v[66:69], v228 offset:2048
	ds_read_b128 v[70:73], v228 offset:2560
	s_waitcnt vmcnt(2) lgkmcnt(1)
	v_mfma_f32_32x32x16_bf16 v[34:49], v[66:69], v[170:173], v[34:49]
	s_waitcnt lgkmcnt(0)
	v_mfma_f32_32x32x16_bf16 v[18:33], v[70:73], v[170:173], v[18:33]
	ds_read_b128 v[66:69], v228 offset:4096
	ds_read_b128 v[70:73], v228 offset:4608
	s_waitcnt vmcnt(1) lgkmcnt(1)
	v_mfma_f32_32x32x16_bf16 v[34:49], v[66:69], v[162:165], v[34:49]
	ds_read_b128 v[66:69], v228 offset:6144
	s_waitcnt lgkmcnt(1)
	v_mfma_f32_32x32x16_bf16 v[18:33], v[70:73], v[162:165], v[18:33]
	ds_read_b128 v[70:73], v228 offset:6656
	s_waitcnt vmcnt(0) lgkmcnt(1)
	v_mfma_f32_32x32x16_bf16 v[34:49], v[66:69], v[154:157], v[34:49]
	v_lshlrev_b32_e32 v66, 1, v104
	v_lshlrev_b32_e32 v67, 4, v104
	v_and_b32_e32 v231, 32, v66
	v_and_b32_e32 v66, 0xc0, v67
	v_lshl_or_b32 v230, v217, 8, v66
	v_add_u32_e32 v66, 0, v231
	v_add3_u32 v227, v66, v229, v230
	s_waitcnt lgkmcnt(0)
	v_mfma_f32_32x32x16_bf16 v[18:33], v[70:73], v[154:157], v[18:33]
	s_nop 15
	s_nop 7
	s_waitcnt vmcnt(0) lgkmcnt(0)
	s_barrier
; #define WAIT_BAR(N) asm volatile("s_waitcnt vmcnt(" #N ") lgkmcnt(0)\n\ts_barrier":::"memory")
; __device__ __forceinline__ void kload2(bf16x8*kf,lds_cptr kp,int j){ kf[2*j]=*(const __attribute__((address_space(3))) bf16x8*)(kp+j*2048); kf[2*j+1]=*(const __attribute__((address_space(3))) bf16x8*)(kp+j*2048+512); }
;   #define DMA_K(t,slot) glds16(ksrc+(long)(t)*KVBLK*PK,(unsigned)__builtin_amdgcn_readfirstlane(kdst+(slot)))
;   #define DMA_V(t,slot) glds16(vsrc+(long)(t)*KVBLK*PV,(unsigned)__builtin_amdgcn_readfirstlane(vdst+(slot)))
;   #define ROT() do{sl_prev=sl_cur;sl_cur=sl_next;sl_next=(sl_next==(NSLOT-1)*SLOTB)?0:sl_next+SLOTB;}while(0)
; template<int THRL,bool FIXREF,bool HALFK> __device__ __forceinline__ void attn_unit(float mref,long rowbase,int q0,const bf16*Qh,int PQ,const bf16*__restrict__ Kh_,int PK,const bf16*__restrict__ Vh_,int PV,bf16*Oh,int PO,const bf16*Gh,int PG,u32x4(&okeep)[4],int omode,float lam,float oml,const float ...
;     ...
;   START(pA0,pA1);
;   _Pragma("unroll") for(int r=0;r<16;++r)pA1[r]=__builtin_amdgcn_exp2f(pA1[r]);
;   WAIT_BAR(0);
;   DMA_K(3,0);DMA_V(1,SLOTB);
;   ROT();
;   if constexpr(HALFK){ kload2(kf,kp0+sl_cur,0); kload2(kf,kp0+sl_cur,1); } else kload8(kf,kp0+sl_cur);
;   WAIT_BAR(2);
	s_nop 2
	v_exp_f32_e32 v82, v34
	v_exp_f32_e32 v83, v35
	s_nop 6
	v_exp_f32_e32 v66, v18
	v_exp_f32_e32 v67, v19
	v_lshl_add_u64 v[18:19], v[210:211], 0, s[12:13]
	s_mov_b32 m0, s62
	s_nop 0
	global_load_lds_dwordx4 v[18:19], off
	v_lshl_add_u64 v[18:19], v[208:209], 0, s[22:23]
	s_add_i32 s70, s62, 0x8000
	s_mov_b32 m0, s70
	s_nop 0
	global_load_lds_dwordx4 v[18:19], off
	ds_read_b128 v[98:101], v228 offset:8192
	ds_read_b128 v[182:185], v228 offset:8704
	ds_read_b128 v[186:189], v228 offset:10240
	ds_read_b128 v[178:181], v228 offset:10752
	ds_read_b128 v[142:145], v228 offset:12288
	ds_read_b128 v[138:141], v228 offset:12800
	ds_read_b128 v[134:137], v228 offset:14336
	ds_read_b128 v[130:133], v228 offset:14848
	s_add_u32 s46, s46, s69
	s_addc_u32 s47, s47, s68
	s_add_u32 s42, s50, s42
	s_addc_u32 s43, s51, s43
	s_add_u32 s42, s42, s67
	v_exp_f32_e32 v84, v36
	v_exp_f32_e32 v85, v37
	v_exp_f32_e32 v86, v38
	v_exp_f32_e32 v87, v39
	v_exp_f32_e32 v88, v40
	v_exp_f32_e32 v89, v41
	v_exp_f32_e32 v90, v42
	v_exp_f32_e32 v91, v43
	v_exp_f32_e32 v92, v44
	v_exp_f32_e32 v93, v45
	v_exp_f32_e32 v94, v46
	v_exp_f32_e32 v95, v47
	v_exp_f32_e32 v96, v48
	v_exp_f32_e32 v97, v49
	v_exp_f32_e32 v68, v20
	v_exp_f32_e32 v69, v21
	v_exp_f32_e32 v70, v22
	v_exp_f32_e32 v71, v23
	v_exp_f32_e32 v72, v24
	v_exp_f32_e32 v73, v25
	v_exp_f32_e32 v74, v26
	v_exp_f32_e32 v75, v27
	v_exp_f32_e32 v76, v28
	v_exp_f32_e32 v77, v29
	v_exp_f32_e32 v78, v30
	v_exp_f32_e32 v79, v31
	v_exp_f32_e32 v80, v32
	v_exp_f32_e32 v81, v33
	v_and_b32_e32 v18, 3, v104
	s_addc_u32 s43, s43, 0
	s_waitcnt vmcnt(2) lgkmcnt(0)
	s_barrier
	v_lshl_or_b32 v18, v18, 4, s46
	v_mov_b32_e32 v19, s47
	s_add_u32 s40, s42, s40
	v_lshl_add_u64 v[18:19], v[18:19], 0, v[102:103]
	s_addc_u32 s41, s43, s41
	v_lshl_add_u64 v[212:213], s[0:1], 0, v[18:19]
	v_lshl_add_u64 v[214:215], s[40:41], 0, v[0:1]
	v_mov_b32_e32 v18, 0
	v_mov_b32_e32 v19, v232
	v_mov_b32_e32 v20, v232
	v_mov_b32_e32 v21, v232
	v_mov_b32_e32 v22, v232
	v_mov_b32_e32 v23, v232
	v_mov_b32_e32 v24, v232
	v_mov_b32_e32 v25, v232
	v_mov_b32_e32 v26, v232
	v_mov_b32_e32 v27, v232
	v_mov_b32_e32 v28, v232
	v_mov_b32_e32 v29, v232
	v_mov_b32_e32 v30, v232
	v_mov_b32_e32 v31, v232
	v_mov_b32_e32 v32, v232
	v_mov_b32_e32 v33, v232
	v_mov_b32_e32 v34, 0
	v_mov_b32_e32 v35, v232
	v_mov_b32_e32 v36, v232
	v_mov_b32_e32 v37, v232
	v_mov_b32_e32 v38, v232
	v_mov_b32_e32 v39, v232
	v_mov_b32_e32 v40, v232
	v_mov_b32_e32 v41, v232
	v_mov_b32_e32 v42, v232
	v_mov_b32_e32 v43, v232
	v_mov_b32_e32 v44, v232
	v_mov_b32_e32 v45, v232
	v_mov_b32_e32 v46, v232
	v_mov_b32_e32 v47, v232
	v_mov_b32_e32 v48, v232
	v_mov_b32_e32 v49, v232
.LBB0_451:
	v_add_u32_e32 v0, s66, v227
	ds_read_b64_tr_b16 v[234:235], v0 offset:24576
	ds_read_b64_tr_b16 v[236:237], v0 offset:25088
	v_add_f32_e32 v102, v82, v83
	v_add_f32_e32 v102, v84, v102
	v_add_f32_e32 v102, v85, v102
	v_add_f32_e32 v102, v86, v102
	v_add_f32_e32 v102, v87, v102
	v_cvt_pk_bf16_f32 v166, v82, v83
	v_cvt_pk_bf16_f32 v167, v84, v85
	s_waitcnt lgkmcnt(9)
	v_mfma_f32_32x32x16_bf16 v[114:129], v[98:101], v[174:177], v[50:65]
	ds_read_b64_tr_b16 v[82:83], v0 offset:28672
	ds_read_b64_tr_b16 v[84:85], v0 offset:29184
	v_add_f32_e32 v98, v88, v102
	v_add_f32_e32 v98, v89, v98
	v_add_f32_e32 v98, v90, v98
	v_add_f32_e32 v146, v91, v98
	s_waitcnt lgkmcnt(10)
	v_mfma_f32_32x32x16_bf16 v[98:113], v[182:185], v[174:177], v[50:65]
	v_cvt_pk_bf16_f32 v168, v86, v87
	v_cvt_pk_bf16_f32 v169, v88, v89
	ds_read_b64_tr_b16 v[86:87], v0 offset:25600
	ds_read_b64_tr_b16 v[88:89], v0 offset:26112
	v_add_f32_e32 v146, v92, v146
	v_add_f32_e32 v146, v93, v146
	v_add_f32_e32 v146, v94, v146
	v_add_f32_e32 v146, v95, v146
	v_cvt_pk_bf16_f32 v158, v90, v91
	v_cvt_pk_bf16_f32 v159, v92, v93
	s_waitcnt lgkmcnt(11)
	v_mfma_f32_32x32x16_bf16 v[114:129], v[186:189], v[170:173], v[114:129]
	ds_read_b64_tr_b16 v[90:91], v0 offset:29696
	ds_read_b64_tr_b16 v[92:93], v0 offset:30208
	s_waitcnt lgkmcnt(12)
	v_mfma_f32_32x32x16_bf16 v[98:113], v[178:181], v[170:173], v[98:113]
	v_add_f32_e32 v146, v96, v146
	v_add_f32_e32 v146, v97, v146
	v_add_f32_e32 v146, v66, v146
	v_add_f32_e32 v146, v67, v146
	v_cvt_pk_bf16_f32 v160, v94, v95
	v_cvt_pk_bf16_f32 v161, v96, v97
	ds_read_b64_tr_b16 v[94:95], v0 offset:26624
	ds_read_b64_tr_b16 v[96:97], v0 offset:27136
	s_waitcnt lgkmcnt(13)
	v_mfma_f32_32x32x16_bf16 v[114:129], v[142:145], v[162:165], v[114:129]
	v_add_f32_e32 v142, v68, v146
	v_add_f32_e32 v142, v69, v142
	v_add_f32_e32 v142, v70, v142
	v_add_f32_e32 v142, v71, v142
	v_cvt_pk_bf16_f32 v150, v66, v67
	v_cvt_pk_bf16_f32 v151, v68, v69
	ds_read_b64_tr_b16 v[66:67], v0 offset:30720
	ds_read_b64_tr_b16 v[68:69], v0 offset:31232
	s_waitcnt lgkmcnt(14)
	v_mfma_f32_32x32x16_bf16 v[98:113], v[138:141], v[162:165], v[98:113]
	v_add_f32_e32 v138, v72, v142
	v_add_f32_e32 v138, v73, v138
	v_add_f32_e32 v138, v74, v138
	v_add_f32_e32 v138, v75, v138
	v_cvt_pk_bf16_f32 v152, v70, v71
	v_cvt_pk_bf16_f32 v153, v72, v73
	ds_read_b64_tr_b16 v[70:71], v0 offset:27648
	ds_read_b64_tr_b16 v[72:73], v0 offset:28160
	s_waitcnt lgkmcnt(14)
	v_mfma_f32_32x32x16_bf16 v[114:129], v[134:137], v[154:157], v[114:129]
	v_add_f32_e32 v134, v76, v138
	v_add_f32_e32 v134, v77, v134
	v_add_f32_e32 v134, v78, v134
	v_add_f32_e32 v134, v79, v134
	v_cvt_pk_bf16_f32 v146, v74, v75
	v_cvt_pk_bf16_f32 v147, v76, v77
	ds_read_b64_tr_b16 v[74:75], v0 offset:31744
	ds_read_b64_tr_b16 v[76:77], v0 offset:32256
	v_mfma_f32_32x32x16_bf16 v[98:113], v[130:133], v[154:157], v[98:113]
	v_add_f32_e32 v0, v80, v134
	v_add_f32_e32 v0, v81, v0
	v_cvt_pk_bf16_f32 v148, v78, v79
	v_cvt_pk_bf16_f32 v149, v80, v81
	v_lshl_add_u64 v[78:79], v[214:215], 0, s[12:13]
	s_add_i32 s40, s65, s62
	s_mov_b32 m0, s40
	s_nop 0
	global_load_lds_dwordx4 v[78:79], off
	v_lshl_add_u64 v[78:79], v[212:213], 0, s[22:23]
	s_add_i32 s40, s49, s61
	s_mov_b32 m0, s40
	s_nop 0
	global_load_lds_dwordx4 v[78:79], off
	v_add_f32_e32 v0, v232, v0
	s_waitcnt lgkmcnt(14)
; #define WAIT_BAR(N) asm volatile("s_waitcnt vmcnt(" #N ") lgkmcnt(0)\n\ts_barrier":::"memory")
;   #define RESC() do{ if(!FIXREF&&resc){ asm volatile("s_waitcnt lgkmcnt(0)":::"memory"); \
;       _Pragma("unroll") for(int d_=0;d_<2;++d_) _Pragma("unroll") for(int r=0;r<16;++r)o[d_][r]*=wsf[crow(r,hi)]; } }while(0)
;   #define ROT() do{sl_prev=sl_cur;sl_cur=sl_next;sl_next=(sl_next==(NSLOT-1)*SLOTB)?0:sl_next+SLOTB;}while(0)
; template<int THRL,bool FIXREF,bool HALFK> __device__ __forceinline__ void attn_unit(float mref,long rowbase,int q0,const bf16*Qh,int PQ,const bf16*__restrict__ Kh_,int PK,const bf16*__restrict__ Vh_,int PV,bf16*Oh,int PO,const bf16*Gh,int PG,u32x4(&okeep)[4],int omode,float lam,float oml,const float ...
;     ...
;   int t=1;
;     ...
;   for(;t+5<NT;t+=2){
;     STEP(pB0,pB1,pA0,pA1,t,true,true,true);     WAIT_BAR(2); RESC(); ROT();
;     STEP(pA0,pA1,pB0,pB1,t+1,true,true,true);   WAIT_BAR(2); RESC(); ROT();
	v_mfma_f32_32x32x16_bf16 v[18:33], v[166:169], v[234:237], v[18:33]
	v_exp_f32_e32 v114, v114
	v_exp_f32_e32 v115, v115
	v_exp_f32_e32 v116, v116
	v_exp_f32_e32 v117, v117
	s_waitcnt lgkmcnt(12)
	v_mfma_f32_32x32x16_bf16 v[34:49], v[166:169], v[82:85], v[34:49]
	v_exp_f32_e32 v118, v118
	v_exp_f32_e32 v119, v119
	v_exp_f32_e32 v120, v120
	v_exp_f32_e32 v121, v121
	v_add_u32_e32 v82, s49, v228
	ds_read_b128 v[78:81], v82
	ds_read_b128 v[134:137], v82 offset:512
	s_waitcnt lgkmcnt(12)
	v_mfma_f32_32x32x16_bf16 v[18:33], v[158:161], v[86:89], v[18:33]
	v_exp_f32_e32 v122, v122
	v_exp_f32_e32 v123, v123
	v_exp_f32_e32 v124, v124
	v_exp_f32_e32 v125, v125
	ds_read_b128 v[138:141], v82 offset:2048
	ds_read_b128 v[142:145], v82 offset:2560
	s_waitcnt lgkmcnt(12)
	v_mfma_f32_32x32x16_bf16 v[34:49], v[158:161], v[90:93], v[34:49]
	v_exp_f32_e32 v126, v126
	v_exp_f32_e32 v127, v127
	v_exp_f32_e32 v128, v128
	v_exp_f32_e32 v129, v129
	ds_read_b128 v[178:181], v82 offset:4096
	ds_read_b128 v[182:185], v82 offset:4608
	s_waitcnt lgkmcnt(12)
	v_mfma_f32_32x32x16_bf16 v[18:33], v[150:153], v[94:97], v[18:33]
	v_exp_f32_e32 v98, v98
	v_exp_f32_e32 v99, v99
	v_exp_f32_e32 v100, v100
	v_exp_f32_e32 v101, v101
	ds_read_b128 v[186:189], v82 offset:6144
	ds_read_b128 v[130:133], v82 offset:6656
	s_waitcnt lgkmcnt(12)
	v_mfma_f32_32x32x16_bf16 v[34:49], v[150:153], v[66:69], v[34:49]
	v_exp_f32_e32 v102, v102
	v_exp_f32_e32 v103, v103
	v_exp_f32_e32 v104, v104
	v_exp_f32_e32 v105, v105
	s_waitcnt lgkmcnt(10)
	v_mfma_f32_32x32x16_bf16 v[18:33], v[146:149], v[70:73], v[18:33]
	v_exp_f32_e32 v106, v106
	v_exp_f32_e32 v107, v107
	v_exp_f32_e32 v108, v108
	v_exp_f32_e32 v109, v109
	s_waitcnt lgkmcnt(8)
	v_mfma_f32_32x32x16_bf16 v[34:49], v[146:149], v[74:77], v[34:49]
	v_exp_f32_e32 v110, v110
	v_exp_f32_e32 v111, v111
	v_exp_f32_e32 v112, v112
	v_exp_f32_e32 v113, v113
	s_waitcnt vmcnt(2) lgkmcnt(0)
	s_barrier
	s_add_i32 s40, s49, 0x2000
	s_cmpk_lg_i32 s49, 0x4000
	s_cselect_b32 s40, s40, 0
	v_add_u32_e32 v232, s65, v227
	ds_read_b64_tr_b16 v[234:235], v232 offset:24576
	ds_read_b64_tr_b16 v[236:237], v232 offset:25088
	s_waitcnt lgkmcnt(9)
	v_mfma_f32_32x32x16_bf16 v[82:97], v[78:81], v[174:177], v[50:65]
	v_add_f32_e32 v66, v114, v115
	v_add_f32_e32 v66, v116, v66
	v_add_f32_e32 v66, v117, v66
	v_add_f32_e32 v66, v118, v66
	v_add_f32_e32 v66, v119, v66
	v_cvt_pk_bf16_f32 v166, v114, v115
	v_cvt_pk_bf16_f32 v167, v116, v117
	ds_read_b64_tr_b16 v[114:115], v232 offset:28672
	ds_read_b64_tr_b16 v[116:117], v232 offset:29184
	v_add_f32_e32 v66, v120, v66
	v_add_f32_e32 v66, v121, v66
	v_add_f32_e32 v66, v122, v66
	v_add_f32_e32 v146, v123, v66
	s_waitcnt lgkmcnt(10)
	v_mfma_f32_32x32x16_bf16 v[66:81], v[134:137], v[174:177], v[50:65]
	v_cvt_pk_bf16_f32 v168, v118, v119
	v_cvt_pk_bf16_f32 v169, v120, v121
	ds_read_b64_tr_b16 v[118:119], v232 offset:25600
	ds_read_b64_tr_b16 v[120:121], v232 offset:26112
	s_waitcnt lgkmcnt(11)
	v_mfma_f32_32x32x16_bf16 v[82:97], v[138:141], v[170:173], v[82:97]
	v_add_f32_e32 v134, v124, v146
	v_add_f32_e32 v134, v125, v134
	v_add_f32_e32 v134, v126, v134
	v_add_f32_e32 v134, v127, v134
	v_cvt_pk_bf16_f32 v158, v122, v123
	v_cvt_pk_bf16_f32 v159, v124, v125
	ds_read_b64_tr_b16 v[122:123], v232 offset:29696
	ds_read_b64_tr_b16 v[124:125], v232 offset:30208
	s_waitcnt lgkmcnt(12)
	v_mfma_f32_32x32x16_bf16 v[66:81], v[142:145], v[170:173], v[66:81]
	v_add_f32_e32 v134, v128, v134
	v_add_f32_e32 v134, v129, v134
	v_add_f32_e32 v134, v98, v134
	v_add_f32_e32 v134, v99, v134
	v_cvt_pk_bf16_f32 v160, v126, v127
	v_cvt_pk_bf16_f32 v161, v128, v129
	ds_read_b64_tr_b16 v[126:127], v232 offset:26624
	ds_read_b64_tr_b16 v[128:129], v232 offset:27136
	s_waitcnt lgkmcnt(13)
	v_mfma_f32_32x32x16_bf16 v[82:97], v[178:181], v[162:165], v[82:97]
	v_add_f32_e32 v134, v100, v134
	v_add_f32_e32 v134, v101, v134
	v_add_f32_e32 v134, v102, v134
	v_add_f32_e32 v134, v103, v134
	v_cvt_pk_bf16_f32 v150, v98, v99
	v_cvt_pk_bf16_f32 v151, v100, v101
	ds_read_b64_tr_b16 v[238:239], v232 offset:30720
	ds_read_b64_tr_b16 v[240:241], v232 offset:31232
	s_waitcnt lgkmcnt(14)
	v_mfma_f32_32x32x16_bf16 v[66:81], v[182:185], v[162:165], v[66:81]
	v_add_f32_e32 v98, v104, v134
	v_add_f32_e32 v98, v105, v98
	v_add_f32_e32 v98, v106, v98
	v_add_f32_e32 v98, v107, v98
	v_cvt_pk_bf16_f32 v152, v102, v103
	v_cvt_pk_bf16_f32 v153, v104, v105
	ds_read_b64_tr_b16 v[102:103], v232 offset:27648
	ds_read_b64_tr_b16 v[104:105], v232 offset:28160
	s_waitcnt lgkmcnt(14)
	v_mfma_f32_32x32x16_bf16 v[82:97], v[186:189], v[154:157], v[82:97]
	v_add_f32_e32 v98, v108, v98
	v_add_f32_e32 v98, v109, v98
	v_add_f32_e32 v98, v110, v98
	v_add_f32_e32 v98, v111, v98
	v_cvt_pk_bf16_f32 v146, v106, v107
	v_cvt_pk_bf16_f32 v147, v108, v109
	ds_read_b64_tr_b16 v[106:107], v232 offset:31744
	ds_read_b64_tr_b16 v[108:109], v232 offset:32256
	v_mfma_f32_32x32x16_bf16 v[66:81], v[130:133], v[154:157], v[66:81]
	v_add_f32_e32 v98, v112, v98
	v_add_f32_e32 v98, v113, v98
	v_cvt_pk_bf16_f32 v148, v110, v111
	v_cvt_pk_bf16_f32 v149, v112, v113
	s_nop 0
	v_add_f32_e32 v232, v0, v98
	v_lshl_add_u64 v[98:99], v[214:215], 0, s[92:93]
	s_add_i32 s41, s49, s62
	s_mov_b32 m0, s41
	s_nop 0
	global_load_lds_dwordx4 v[98:99], off
	v_lshl_add_u64 v[212:213], v[212:213], 0, s[4:5]
	s_add_i32 s41, s40, s61
	s_mov_b32 m0, s41
	s_nop 0
	global_load_lds_dwordx4 v[212:213], off
	s_waitcnt lgkmcnt(14)
	v_mfma_f32_32x32x16_bf16 v[18:33], v[166:169], v[234:237], v[18:33]
	v_exp_f32_e32 v82, v82
	v_exp_f32_e32 v83, v83
	v_exp_f32_e32 v84, v84
	v_exp_f32_e32 v85, v85
	s_waitcnt lgkmcnt(12)
; #define WAIT_BAR(N) asm volatile("s_waitcnt vmcnt(" #N ") lgkmcnt(0)\n\ts_barrier":::"memory")
;   #define RESC() do{ if(!FIXREF&&resc){ asm volatile("s_waitcnt lgkmcnt(0)":::"memory"); \
;       _Pragma("unroll") for(int d_=0;d_<2;++d_) _Pragma("unroll") for(int r=0;r<16;++r)o[d_][r]*=wsf[crow(r,hi)]; } }while(0)
;   #define ROT() do{sl_prev=sl_cur;sl_cur=sl_next;sl_next=(sl_next==(NSLOT-1)*SLOTB)?0:sl_next+SLOTB;}while(0)
;   #define ENDW(tt) do{ if((tt)+3<NT){WAIT_BAR(2);} else if((tt)+2<NT){WAIT_BAR(1);} else {WAIT_BAR(0);} }while(0)
; template<int THRL,bool FIXREF,bool HALFK> __device__ __forceinline__ void attn_unit(float mref,long rowbase,int q0,const bf16*Qh,int PQ,const bf16*__restrict__ Kh_,int PK,const bf16*__restrict__ Vh_,int PV,bf16*Oh,int PO,const bf16*Gh,int PG,u32x4(&okeep)[4],int omode,float lam,float oml,const float ...
;     ...
;   int t=1;
;     ...
;   for(;t+5<NT;t+=2){
;     STEP(pB0,pB1,pA0,pA1,t,true,true,true);     WAIT_BAR(2); RESC(); ROT();
;     STEP(pA0,pA1,pB0,pB1,t+1,true,true,true);   WAIT_BAR(2); RESC(); ROT();
;   }
;     ...
;   for(;t+1<NT;t+=2){
;     STEP(pB0,pB1,pA0,pA1,t,(t+3<NT),(t+1<NT),(t+1<NT));       ENDW(t);   RESC(); ROT();
;     STEP(pA0,pA1,pB0,pB1,t+1,(t+4<NT),(t+2<NT),(t+2<NT));     ENDW(t+1); RESC(); ROT();
	v_mfma_f32_32x32x16_bf16 v[34:49], v[166:169], v[114:117], v[34:49]
	v_exp_f32_e32 v86, v86
	v_exp_f32_e32 v87, v87
	v_exp_f32_e32 v88, v88
	v_exp_f32_e32 v89, v89
	v_add_u32_e32 v0, s40, v228
	ds_read_b128 v[98:101], v0
	ds_read_b128 v[182:185], v0 offset:512
	s_waitcnt lgkmcnt(12)
	v_mfma_f32_32x32x16_bf16 v[18:33], v[158:161], v[118:121], v[18:33]
	v_exp_f32_e32 v90, v90
	v_exp_f32_e32 v91, v91
	v_exp_f32_e32 v92, v92
	v_exp_f32_e32 v93, v93
	ds_read_b128 v[186:189], v0 offset:2048
	ds_read_b128 v[178:181], v0 offset:2560
	s_waitcnt lgkmcnt(12)
	v_mfma_f32_32x32x16_bf16 v[34:49], v[158:161], v[122:125], v[34:49]
	v_exp_f32_e32 v94, v94
	v_exp_f32_e32 v95, v95
	v_exp_f32_e32 v96, v96
	v_exp_f32_e32 v97, v97
	ds_read_b128 v[142:145], v0 offset:4096
	ds_read_b128 v[138:141], v0 offset:4608
	s_waitcnt lgkmcnt(12)
	v_mfma_f32_32x32x16_bf16 v[18:33], v[150:153], v[126:129], v[18:33]
	v_exp_f32_e32 v66, v66
	v_exp_f32_e32 v67, v67
	v_exp_f32_e32 v68, v68
	v_exp_f32_e32 v69, v69
	ds_read_b128 v[134:137], v0 offset:6144
	ds_read_b128 v[130:133], v0 offset:6656
	s_waitcnt lgkmcnt(12)
	v_mfma_f32_32x32x16_bf16 v[34:49], v[150:153], v[238:241], v[34:49]
	v_exp_f32_e32 v70, v70
	v_exp_f32_e32 v71, v71
	v_exp_f32_e32 v72, v72
	v_exp_f32_e32 v73, v73
	s_waitcnt lgkmcnt(10)
	v_mfma_f32_32x32x16_bf16 v[18:33], v[146:149], v[102:105], v[18:33]
	v_exp_f32_e32 v74, v74
	v_exp_f32_e32 v75, v75
	v_exp_f32_e32 v76, v76
	v_exp_f32_e32 v77, v77
	s_waitcnt lgkmcnt(8)
	v_mfma_f32_32x32x16_bf16 v[34:49], v[146:149], v[106:109], v[34:49]
	v_exp_f32_e32 v78, v78
	v_exp_f32_e32 v79, v79
	v_exp_f32_e32 v80, v80
	v_exp_f32_e32 v81, v81
	s_add_i32 s41, s40, 0x2000
	s_waitcnt vmcnt(2) lgkmcnt(0)
	s_barrier
	s_cmpk_lg_i32 s40, 0x4000
	s_mov_b32 s66, s49
	s_cselect_b32 s49, s41, 0
	s_add_i32 s48, s48, 2
	v_lshl_add_u64 v[214:215], v[214:215], 0, s[10:11]
	s_mov_b32 s65, s40
	s_cmp_gt_u32 s48, 56
	s_cbranch_scc0 .LBB0_451
	s_and_b32 s41, s64, 0x3fffffc0
	s_cmp_lg_u32 0, -1
	s_cselect_b32 s40, 0, 0
	s_add_i32 s42, s40, 0x6000
	v_add_u32_e32 v0, s42, v231
	s_lshl_b32 s41, s41, 2
	s_add_i32 s42, s41, 0
	v_add3_u32 v0, v0, v229, v230
	ds_read_b64_tr_b16 v[212:213], v227 offset:32768
	ds_read_b64_tr_b16 v[214:215], v227 offset:33280
	v_add_f32_e32 v102, v82, v83
	v_add_f32_e32 v102, v84, v102
	v_add_f32_e32 v102, v85, v102
	v_add_f32_e32 v102, v86, v102
	v_add_f32_e32 v102, v87, v102
	v_cvt_pk_bf16_f32 v166, v82, v83
	v_cvt_pk_bf16_f32 v167, v84, v85
	s_waitcnt lgkmcnt(9)
	v_mfma_f32_32x32x16_bf16 v[114:129], v[98:101], v[174:177], v[50:65]
	ds_read_b64_tr_b16 v[82:83], v227 offset:36864
	ds_read_b64_tr_b16 v[84:85], v227 offset:37376
	v_add_f32_e32 v98, v88, v102
	v_add_f32_e32 v98, v89, v98
	v_add_f32_e32 v98, v90, v98
	v_add_f32_e32 v146, v91, v98
	v_cvt_pk_bf16_f32 v168, v86, v87
	v_cvt_pk_bf16_f32 v169, v88, v89
	s_waitcnt lgkmcnt(10)
	v_mfma_f32_32x32x16_bf16 v[98:113], v[182:185], v[174:177], v[50:65]
	ds_read_b64_tr_b16 v[86:87], v227 offset:33792
	ds_read_b64_tr_b16 v[88:89], v227 offset:34304
	v_add_f32_e32 v146, v92, v146
	v_add_f32_e32 v146, v93, v146
	v_add_f32_e32 v146, v94, v146
	v_add_f32_e32 v146, v95, v146
	v_cvt_pk_bf16_f32 v158, v90, v91
	v_cvt_pk_bf16_f32 v159, v92, v93
	s_waitcnt lgkmcnt(11)
	v_mfma_f32_32x32x16_bf16 v[114:129], v[186:189], v[170:173], v[114:129]
	ds_read_b64_tr_b16 v[90:91], v227 offset:37888
	ds_read_b64_tr_b16 v[92:93], v227 offset:38400
	v_add_f32_e32 v146, v96, v146
	v_add_f32_e32 v146, v97, v146
	v_add_f32_e32 v146, v66, v146
	v_add_f32_e32 v146, v67, v146
	v_cvt_pk_bf16_f32 v160, v94, v95
	v_cvt_pk_bf16_f32 v161, v96, v97
	s_waitcnt lgkmcnt(12)
	v_mfma_f32_32x32x16_bf16 v[98:113], v[178:181], v[170:173], v[98:113]
	ds_read_b64_tr_b16 v[94:95], v227 offset:34816
	ds_read_b64_tr_b16 v[96:97], v227 offset:35328
	s_waitcnt lgkmcnt(13)
	v_mfma_f32_32x32x16_bf16 v[114:129], v[142:145], v[162:165], v[114:129]
	v_add_f32_e32 v142, v68, v146
	v_add_f32_e32 v142, v69, v142
	v_add_f32_e32 v142, v70, v142
	v_add_f32_e32 v142, v71, v142
	v_cvt_pk_bf16_f32 v150, v66, v67
	v_cvt_pk_bf16_f32 v151, v68, v69
	ds_read_b64_tr_b16 v[66:67], v227 offset:38912
	ds_read_b64_tr_b16 v[68:69], v227 offset:39424
	s_waitcnt lgkmcnt(14)
	v_mfma_f32_32x32x16_bf16 v[98:113], v[138:141], v[162:165], v[98:113]
	v_add_f32_e32 v138, v72, v142
	v_add_f32_e32 v138, v73, v138
	v_add_f32_e32 v138, v74, v138
	v_add_f32_e32 v138, v75, v138
	v_cvt_pk_bf16_f32 v152, v70, v71
	v_cvt_pk_bf16_f32 v153, v72, v73
	ds_read_b64_tr_b16 v[70:71], v227 offset:35840
	ds_read_b64_tr_b16 v[72:73], v227 offset:36352
	s_waitcnt lgkmcnt(14)
	v_mfma_f32_32x32x16_bf16 v[114:129], v[134:137], v[154:157], v[114:129]
	v_add_f32_e32 v134, v76, v138
	v_add_f32_e32 v134, v77, v134
	v_add_f32_e32 v134, v78, v134
	v_add_f32_e32 v134, v79, v134
	v_cvt_pk_bf16_f32 v146, v74, v75
	v_cvt_pk_bf16_f32 v147, v76, v77
	ds_read_b64_tr_b16 v[74:75], v227 offset:39936
	ds_read_b64_tr_b16 v[76:77], v227 offset:40448
	v_mfma_f32_32x32x16_bf16 v[98:113], v[130:133], v[154:157], v[98:113]
	v_add_f32_e32 v130, v80, v134
	v_add_f32_e32 v130, v81, v130
	v_cvt_pk_bf16_f32 v148, v78, v79
	v_cvt_pk_bf16_f32 v149, v80, v81
	s_mov_b64 s[46:47], 0xf8000
	s_add_i32 s40, s40, s63
	v_lshl_add_u64 v[78:79], v[210:211], 0, s[46:47]
	s_add_i32 s41, s40, 0x4000
	s_mov_b32 m0, s41
	s_nop 0
	global_load_lds_dwordx4 v[78:79], off
	v_lshl_add_u64 v[78:79], v[208:209], 0, s[18:19]
	s_mov_b32 m0, s61
	s_nop 0
	global_load_lds_dwordx4 v[78:79], off
	v_add_f32_e32 v229, v232, v130
	s_waitcnt lgkmcnt(14)
	v_mfma_f32_32x32x16_bf16 v[18:33], v[166:169], v[212:215], v[18:33]
	v_exp_f32_e32 v114, v114
	v_exp_f32_e32 v115, v115
	v_exp_f32_e32 v116, v116
	v_exp_f32_e32 v117, v117
	s_waitcnt lgkmcnt(12)
;   #define RESC() do{ if(!FIXREF&&resc){ asm volatile("s_waitcnt lgkmcnt(0)":::"memory"); \
;       _Pragma("unroll") for(int d_=0;d_<2;++d_) _Pragma("unroll") for(int r=0;r<16;++r)o[d_][r]*=wsf[crow(r,hi)]; } }while(0)
;   #define ROT() do{sl_prev=sl_cur;sl_cur=sl_next;sl_next=(sl_next==(NSLOT-1)*SLOTB)?0:sl_next+SLOTB;}while(0)
;   #define ENDW(tt) do{ if((tt)+3<NT){WAIT_BAR(2);} else if((tt)+2<NT){WAIT_BAR(1);} else {WAIT_BAR(0);} }while(0)
; template<int THRL,bool FIXREF,bool HALFK> __device__ __forceinline__ void attn_unit(float mref,long rowbase,int q0,const bf16*Qh,int PQ,const bf16*__restrict__ Kh_,int PK,const bf16*__restrict__ Vh_,int PV,bf16*Oh,int PO,const bf16*Gh,int PG,u32x4(&okeep)[4],int omode,float lam,float oml,const float ...
;     ...
;   for(;t+1<NT;t+=2){
;     STEP(pB0,pB1,pA0,pA1,t,(t+3<NT),(t+1<NT),(t+1<NT));       ENDW(t);   RESC(); ROT();
;     STEP(pA0,pA1,pB0,pB1,t+1,(t+4<NT),(t+2<NT),(t+2<NT));     ENDW(t+1); RESC(); ROT();
	v_mfma_f32_32x32x16_bf16 v[34:49], v[166:169], v[82:85], v[34:49]
	v_exp_f32_e32 v118, v118
	v_exp_f32_e32 v119, v119
	v_exp_f32_e32 v120, v120
	v_exp_f32_e32 v121, v121
	ds_read_b128 v[78:81], v228
	ds_read_b128 v[178:181], v228 offset:512
	s_waitcnt lgkmcnt(12)
	v_mfma_f32_32x32x16_bf16 v[18:33], v[158:161], v[86:89], v[18:33]
	v_exp_f32_e32 v122, v122
	v_exp_f32_e32 v123, v123
	v_exp_f32_e32 v124, v124
	v_exp_f32_e32 v125, v125
	ds_read_b128 v[86:89], v228 offset:2048
	ds_read_b128 v[182:185], v228 offset:2560
	s_waitcnt lgkmcnt(12)
	v_mfma_f32_32x32x16_bf16 v[34:49], v[158:161], v[90:93], v[34:49]
	v_exp_f32_e32 v126, v126
	v_exp_f32_e32 v127, v127
	v_exp_f32_e32 v128, v128
	v_exp_f32_e32 v129, v129
	ds_read_b128 v[90:93], v228 offset:4096
	ds_read_b128 v[186:189], v228 offset:4608
	s_waitcnt lgkmcnt(12)
	v_mfma_f32_32x32x16_bf16 v[18:33], v[150:153], v[94:97], v[18:33]
	v_exp_f32_e32 v98, v98
	v_exp_f32_e32 v99, v99
	v_exp_f32_e32 v100, v100
	v_exp_f32_e32 v101, v101
	ds_read_b128 v[94:97], v228 offset:6144
	ds_read_b128 v[82:85], v228 offset:6656
	s_waitcnt lgkmcnt(12)
	v_mfma_f32_32x32x16_bf16 v[34:49], v[150:153], v[66:69], v[34:49]
	v_exp_f32_e32 v102, v102
	v_exp_f32_e32 v103, v103
	v_exp_f32_e32 v104, v104
	v_exp_f32_e32 v105, v105
	s_waitcnt lgkmcnt(10)
	v_mfma_f32_32x32x16_bf16 v[18:33], v[146:149], v[70:73], v[18:33]
	v_exp_f32_e32 v106, v106
	v_exp_f32_e32 v107, v107
	v_exp_f32_e32 v108, v108
	v_exp_f32_e32 v109, v109
	s_waitcnt lgkmcnt(8)
	v_mfma_f32_32x32x16_bf16 v[34:49], v[146:149], v[74:77], v[34:49]
	v_exp_f32_e32 v110, v110
	v_exp_f32_e32 v111, v111
	v_exp_f32_e32 v112, v112
	v_exp_f32_e32 v113, v113
	s_waitcnt vmcnt(2) lgkmcnt(0)
	s_barrier
	ds_read_b64_tr_b16 v[212:213], v227 offset:40960
	ds_read_b64_tr_b16 v[214:215], v227 offset:41472
	v_add_f32_e32 v66, v114, v115
	v_add_f32_e32 v66, v116, v66
	v_add_f32_e32 v66, v117, v66
	v_add_f32_e32 v66, v118, v66
	v_add_f32_e32 v66, v119, v66
	v_cvt_pk_bf16_f32 v166, v114, v115
	v_cvt_pk_bf16_f32 v167, v116, v117
	s_waitcnt lgkmcnt(9)
	v_mfma_f32_32x32x16_bf16 v[130:145], v[78:81], v[174:177], v[50:65]
	ds_read_b64_tr_b16 v[114:115], v227 offset:45056
	ds_read_b64_tr_b16 v[116:117], v227 offset:45568
	v_add_f32_e32 v66, v120, v66
	v_add_f32_e32 v66, v121, v66
	v_add_f32_e32 v66, v122, v66
	v_add_f32_e32 v146, v123, v66
	s_waitcnt lgkmcnt(10)
	v_mfma_f32_32x32x16_bf16 v[66:81], v[178:181], v[174:177], v[50:65]
	v_cvt_pk_bf16_f32 v168, v118, v119
	v_cvt_pk_bf16_f32 v169, v120, v121
	ds_read_b64_tr_b16 v[118:119], v227 offset:41984
	ds_read_b64_tr_b16 v[120:121], v227 offset:42496
	s_waitcnt lgkmcnt(11)
	v_mfma_f32_32x32x16_bf16 v[130:145], v[86:89], v[170:173], v[130:145]
	v_add_f32_e32 v86, v124, v146
	v_add_f32_e32 v86, v125, v86
	v_add_f32_e32 v86, v126, v86
	v_add_f32_e32 v146, v127, v86
	v_cvt_pk_bf16_f32 v158, v122, v123
	v_cvt_pk_bf16_f32 v159, v124, v125
	ds_read_b64_tr_b16 v[86:87], v227 offset:46080
	ds_read_b64_tr_b16 v[88:89], v227 offset:46592
	s_waitcnt lgkmcnt(12)
	v_mfma_f32_32x32x16_bf16 v[66:81], v[182:185], v[170:173], v[66:81]
	v_add_f32_e32 v122, v128, v146
	v_add_f32_e32 v122, v129, v122
	v_add_f32_e32 v122, v98, v122
	v_add_f32_e32 v146, v99, v122
	v_cvt_pk_bf16_f32 v160, v126, v127
	v_cvt_pk_bf16_f32 v161, v128, v129
	ds_read_b64_tr_b16 v[122:123], v227 offset:43008
	ds_read_b64_tr_b16 v[124:125], v227 offset:43520
	s_waitcnt lgkmcnt(13)
	v_mfma_f32_32x32x16_bf16 v[130:145], v[90:93], v[162:165], v[130:145]
	v_add_f32_e32 v90, v100, v146
	v_add_f32_e32 v90, v101, v90
	v_add_f32_e32 v90, v102, v90
	v_add_f32_e32 v126, v103, v90
	v_cvt_pk_bf16_f32 v150, v98, v99
	v_cvt_pk_bf16_f32 v151, v100, v101
	ds_read_b64_tr_b16 v[90:91], v227 offset:47104
	ds_read_b64_tr_b16 v[92:93], v227 offset:47616
	s_waitcnt lgkmcnt(14)
	v_mfma_f32_32x32x16_bf16 v[66:81], v[186:189], v[162:165], v[66:81]
	v_add_f32_e32 v98, v104, v126
	v_add_f32_e32 v98, v105, v98
	v_add_f32_e32 v98, v106, v98
	v_add_f32_e32 v98, v107, v98
	v_cvt_pk_bf16_f32 v152, v102, v103
	v_cvt_pk_bf16_f32 v153, v104, v105
	ds_read_b64_tr_b16 v[102:103], v227 offset:44032
	ds_read_b64_tr_b16 v[104:105], v227 offset:44544
	s_waitcnt lgkmcnt(14)
	v_mfma_f32_32x32x16_bf16 v[130:145], v[94:97], v[154:157], v[130:145]
	v_add_f32_e32 v94, v108, v98
	v_add_f32_e32 v94, v109, v94
	v_add_f32_e32 v94, v110, v94
	v_add_f32_e32 v98, v111, v94
	v_cvt_pk_bf16_f32 v146, v106, v107
	v_cvt_pk_bf16_f32 v147, v108, v109
	ds_read_b64_tr_b16 v[94:95], v227 offset:48128
	ds_read_b64_tr_b16 v[96:97], v227 offset:48640
	v_mfma_f32_32x32x16_bf16 v[66:81], v[82:85], v[154:157], v[66:81]
	v_add_f32_e32 v82, v112, v98
	v_add_f32_e32 v82, v113, v82
	v_cvt_pk_bf16_f32 v148, v110, v111
	v_cvt_pk_bf16_f32 v149, v112, v113
	s_mov_b64 s[46:47], 0xfc000
	v_add_f32_e32 v229, v229, v82
	v_lshl_add_u64 v[82:83], v[210:211], 0, s[46:47]
	s_mov_b32 m0, s62
	s_nop 0
	global_load_lds_dwordx4 v[82:83], off
	v_lshl_add_u64 v[82:83], v[208:209], 0, s[6:7]
	s_add_i32 s41, s40, 0x8000
	s_mov_b32 m0, s41
	s_nop 0
	global_load_lds_dwordx4 v[82:83], off
	s_waitcnt lgkmcnt(14)
	v_mfma_f32_32x32x16_bf16 v[18:33], v[166:169], v[212:215], v[18:33]
	v_exp_f32_e32 v130, v130
	v_exp_f32_e32 v131, v131
	v_exp_f32_e32 v132, v132
	v_exp_f32_e32 v133, v133
	s_waitcnt lgkmcnt(12)
	v_mfma_f32_32x32x16_bf16 v[34:49], v[166:169], v[114:117], v[34:49]
	v_exp_f32_e32 v134, v134
	v_exp_f32_e32 v135, v135
	v_exp_f32_e32 v136, v136
	v_exp_f32_e32 v137, v137
	ds_read_b128 v[82:85], v228 offset:8192
	ds_read_b128 v[106:109], v228 offset:8704
	s_waitcnt lgkmcnt(12)
	v_mfma_f32_32x32x16_bf16 v[18:33], v[158:161], v[118:121], v[18:33]
	v_exp_f32_e32 v138, v138
	v_exp_f32_e32 v139, v139
	v_exp_f32_e32 v140, v140
	v_exp_f32_e32 v141, v141
	ds_read_b128 v[110:113], v228 offset:10240
	ds_read_b128 v[178:181], v228 offset:10752
	s_waitcnt lgkmcnt(12)
	v_mfma_f32_32x32x16_bf16 v[34:49], v[158:161], v[86:89], v[34:49]
	v_exp_f32_e32 v142, v142
	v_exp_f32_e32 v143, v143
	v_exp_f32_e32 v144, v144
	v_exp_f32_e32 v145, v145
	ds_read_b128 v[182:185], v228 offset:12288
	ds_read_b128 v[186:189], v228 offset:12800
	s_waitcnt lgkmcnt(12)
	v_mfma_f32_32x32x16_bf16 v[18:33], v[150:153], v[122:125], v[18:33]
	v_exp_f32_e32 v66, v66
	v_exp_f32_e32 v67, v67
	v_exp_f32_e32 v68, v68
	v_exp_f32_e32 v69, v69
	ds_read_b128 v[210:213], v228 offset:14336
	ds_read_b128 v[98:101], v228 offset:14848
	s_waitcnt lgkmcnt(12)
	v_mfma_f32_32x32x16_bf16 v[34:49], v[150:153], v[90:93], v[34:49]
	v_exp_f32_e32 v70, v70
	v_exp_f32_e32 v71, v71
	v_exp_f32_e32 v72, v72
	v_exp_f32_e32 v73, v73
	s_waitcnt lgkmcnt(10)
	v_mfma_f32_32x32x16_bf16 v[18:33], v[146:149], v[102:105], v[18:33]
	v_exp_f32_e32 v74, v74
	v_exp_f32_e32 v75, v75
	v_exp_f32_e32 v76, v76
	v_exp_f32_e32 v77, v77
	s_waitcnt lgkmcnt(8)
	v_mfma_f32_32x32x16_bf16 v[34:49], v[146:149], v[94:97], v[34:49]
	v_exp_f32_e32 v78, v78
	v_exp_f32_e32 v79, v79
	v_exp_f32_e32 v80, v80
	v_exp_f32_e32 v81, v81
	s_waitcnt vmcnt(2) lgkmcnt(0)
	s_barrier
;   #define RESC() do{ if(!FIXREF&&resc){ asm volatile("s_waitcnt lgkmcnt(0)":::"memory"); \
;       _Pragma("unroll") for(int d_=0;d_<2;++d_) _Pragma("unroll") for(int r=0;r<16;++r)o[d_][r]*=wsf[crow(r,hi)]; } }while(0)
;   #define ROT() do{sl_prev=sl_cur;sl_cur=sl_next;sl_next=(sl_next==(NSLOT-1)*SLOTB)?0:sl_next+SLOTB;}while(0)
;   #define ENDW(tt) do{ if((tt)+3<NT){WAIT_BAR(2);} else if((tt)+2<NT){WAIT_BAR(1);} else {WAIT_BAR(0);} }while(0)
; template<int THRL,bool FIXREF,bool HALFK> __device__ __forceinline__ void attn_unit(float mref,long rowbase,int q0,const bf16*Qh,int PQ,const bf16*__restrict__ Kh_,int PK,const bf16*__restrict__ Vh_,int PV,bf16*Oh,int PO,const bf16*Gh,int PG,u32x4(&okeep)[4],int omode,float lam,float oml,const float ...
;     ...
;   for(;t+1<NT;t+=2){
;     STEP(pB0,pB1,pA0,pA1,t,(t+3<NT),(t+1<NT),(t+1<NT));       ENDW(t);   RESC(); ROT();
;     STEP(pA0,pA1,pB0,pB1,t+1,(t+4<NT),(t+2<NT),(t+2<NT));     ENDW(t+1); RESC(); ROT();
	ds_read_b64_tr_b16 v[102:103], v227 offset:24576
	ds_read_b64_tr_b16 v[104:105], v227 offset:25088
	v_add_f32_e32 v86, v130, v131
	v_add_f32_e32 v86, v132, v86
	v_add_f32_e32 v86, v133, v86
	v_add_f32_e32 v86, v134, v86
	v_add_f32_e32 v86, v135, v86
	v_cvt_pk_bf16_f32 v166, v130, v131
	v_cvt_pk_bf16_f32 v167, v132, v133
	s_waitcnt lgkmcnt(9)
	v_mfma_f32_32x32x16_bf16 v[114:129], v[82:85], v[174:177], v[50:65]
	ds_read_b64_tr_b16 v[130:131], v227 offset:28672
	ds_read_b64_tr_b16 v[132:133], v227 offset:29184
	v_add_f32_e32 v82, v136, v86
	v_add_f32_e32 v82, v137, v82
	v_add_f32_e32 v82, v138, v82
	v_add_f32_e32 v146, v139, v82
	v_cvt_pk_bf16_f32 v168, v134, v135
	v_cvt_pk_bf16_f32 v169, v136, v137
	s_waitcnt lgkmcnt(10)
	v_mfma_f32_32x32x16_bf16 v[82:97], v[106:109], v[174:177], v[50:65]
	ds_read_b64_tr_b16 v[106:107], v227 offset:25600
	ds_read_b64_tr_b16 v[108:109], v227 offset:26112
	s_waitcnt lgkmcnt(11)
	v_mfma_f32_32x32x16_bf16 v[114:129], v[110:113], v[170:173], v[114:129]
	v_add_f32_e32 v110, v140, v146
	v_add_f32_e32 v110, v141, v110
	v_add_f32_e32 v110, v142, v110
	v_add_f32_e32 v134, v143, v110
	v_cvt_pk_bf16_f32 v158, v138, v139
	v_cvt_pk_bf16_f32 v159, v140, v141
	ds_read_b64_tr_b16 v[110:111], v227 offset:29696
	ds_read_b64_tr_b16 v[112:113], v227 offset:30208
	v_add_f32_e32 v134, v144, v134
	v_add_f32_e32 v134, v145, v134
	v_add_f32_e32 v134, v66, v134
	v_add_f32_e32 v138, v67, v134
	v_cvt_pk_bf16_f32 v160, v142, v143
	v_cvt_pk_bf16_f32 v161, v144, v145
	s_waitcnt lgkmcnt(12)
	v_mfma_f32_32x32x16_bf16 v[82:97], v[178:181], v[170:173], v[82:97]
	ds_read_b64_tr_b16 v[134:135], v227 offset:26624
	ds_read_b64_tr_b16 v[136:137], v227 offset:27136
	v_add_f32_e32 v138, v68, v138
	v_add_f32_e32 v138, v69, v138
	v_add_f32_e32 v138, v70, v138
	v_add_f32_e32 v138, v71, v138
	v_cvt_pk_bf16_f32 v150, v66, v67
	v_cvt_pk_bf16_f32 v151, v68, v69
	s_waitcnt lgkmcnt(13)
	v_mfma_f32_32x32x16_bf16 v[114:129], v[182:185], v[162:165], v[114:129]
	ds_read_b64_tr_b16 v[66:67], v227 offset:30720
	ds_read_b64_tr_b16 v[68:69], v227 offset:31232
	v_add_f32_e32 v138, v72, v138
	v_add_f32_e32 v138, v73, v138
	v_add_f32_e32 v138, v74, v138
	v_add_f32_e32 v138, v75, v138
	v_cvt_pk_bf16_f32 v152, v70, v71
	v_cvt_pk_bf16_f32 v153, v72, v73
	s_waitcnt lgkmcnt(14)
	v_mfma_f32_32x32x16_bf16 v[82:97], v[186:189], v[162:165], v[82:97]
	ds_read_b64_tr_b16 v[70:71], v227 offset:27648
	ds_read_b64_tr_b16 v[72:73], v227 offset:28160
	v_add_f32_e32 v138, v76, v138
	v_add_f32_e32 v138, v77, v138
	v_add_f32_e32 v138, v78, v138
	v_add_f32_e32 v138, v79, v138
	v_cvt_pk_bf16_f32 v146, v74, v75
	v_cvt_pk_bf16_f32 v147, v76, v77
	s_waitcnt lgkmcnt(14)
	v_mfma_f32_32x32x16_bf16 v[114:129], v[210:213], v[154:157], v[114:129]
	ds_read_b64_tr_b16 v[74:75], v227 offset:31744
	ds_read_b64_tr_b16 v[76:77], v227 offset:32256
	v_mfma_f32_32x32x16_bf16 v[82:97], v[98:101], v[154:157], v[82:97]
	v_add_f32_e32 v98, v80, v138
	v_add_f32_e32 v98, v81, v98
	v_cvt_pk_bf16_f32 v148, v78, v79
	v_cvt_pk_bf16_f32 v149, v80, v81
	v_lshl_add_u64 v[78:79], v[208:209], 0, s[94:95]
	s_add_i32 s40, s40, 0xa000
	s_mov_b32 m0, s40
	s_nop 0
	global_load_lds_dwordx4 v[78:79], off
	v_add_f32_e32 v214, v229, v98
	s_waitcnt lgkmcnt(14)
	v_mfma_f32_32x32x16_bf16 v[18:33], v[166:169], v[102:105], v[18:33]
	v_exp_f32_e32 v114, v114
	v_exp_f32_e32 v115, v115
	v_exp_f32_e32 v116, v116
	v_exp_f32_e32 v117, v117
	s_waitcnt lgkmcnt(12)
	v_mfma_f32_32x32x16_bf16 v[34:49], v[166:169], v[130:133], v[34:49]
	v_exp_f32_e32 v118, v118
	v_exp_f32_e32 v119, v119
	v_exp_f32_e32 v120, v120
	v_exp_f32_e32 v121, v121
	ds_read_b128 v[78:81], v228 offset:16384
	ds_read_b128 v[138:141], v228 offset:16896
	s_waitcnt lgkmcnt(12)
	v_mfma_f32_32x32x16_bf16 v[18:33], v[158:161], v[106:109], v[18:33]
	v_exp_f32_e32 v122, v122
	v_exp_f32_e32 v123, v123
	v_exp_f32_e32 v124, v124
	v_exp_f32_e32 v125, v125
	ds_read_b128 v[142:145], v228 offset:18432
	ds_read_b128 v[178:181], v228 offset:18944
	s_waitcnt lgkmcnt(12)
	v_mfma_f32_32x32x16_bf16 v[34:49], v[158:161], v[110:113], v[34:49]
	v_exp_f32_e32 v126, v126
	v_exp_f32_e32 v127, v127
	v_exp_f32_e32 v128, v128
	v_exp_f32_e32 v129, v129
	ds_read_b128 v[182:185], v228 offset:20480
	ds_read_b128 v[186:189], v228 offset:20992
	s_waitcnt lgkmcnt(12)
	v_mfma_f32_32x32x16_bf16 v[18:33], v[150:153], v[134:137], v[18:33]
	v_exp_f32_e32 v82, v82
	v_exp_f32_e32 v83, v83
	v_exp_f32_e32 v84, v84
	v_exp_f32_e32 v85, v85
	ds_read_b128 v[134:137], v228 offset:22528
	ds_read_b128 v[130:133], v228 offset:23040
	s_waitcnt lgkmcnt(12)
	v_mfma_f32_32x32x16_bf16 v[34:49], v[150:153], v[66:69], v[34:49]
	v_exp_f32_e32 v86, v86
	v_exp_f32_e32 v87, v87
	v_exp_f32_e32 v88, v88
	v_exp_f32_e32 v89, v89
	s_waitcnt lgkmcnt(10)
	v_mfma_f32_32x32x16_bf16 v[18:33], v[146:149], v[70:73], v[18:33]
	v_exp_f32_e32 v90, v90
	v_exp_f32_e32 v91, v91
	v_exp_f32_e32 v92, v92
	v_exp_f32_e32 v93, v93
	s_waitcnt lgkmcnt(8)
	v_mfma_f32_32x32x16_bf16 v[34:49], v[146:149], v[74:77], v[34:49]
	v_exp_f32_e32 v94, v94
	v_exp_f32_e32 v95, v95
	v_exp_f32_e32 v96, v96
	v_exp_f32_e32 v97, v97
	s_waitcnt vmcnt(1) lgkmcnt(0)
	s_barrier
;   #define RESC() do{ if(!FIXREF&&resc){ asm volatile("s_waitcnt lgkmcnt(0)":::"memory"); \
;       _Pragma("unroll") for(int d_=0;d_<2;++d_) _Pragma("unroll") for(int r=0;r<16;++r)o[d_][r]*=wsf[crow(r,hi)]; } }while(0)
;   #define ROT() do{sl_prev=sl_cur;sl_cur=sl_next;sl_next=(sl_next==(NSLOT-1)*SLOTB)?0:sl_next+SLOTB;}while(0)
;   #define ENDW(tt) do{ if((tt)+3<NT){WAIT_BAR(2);} else if((tt)+2<NT){WAIT_BAR(1);} else {WAIT_BAR(0);} }while(0)
; template<int THRL,bool FIXREF,bool HALFK> __device__ __forceinline__ void attn_unit(float mref,long rowbase,int q0,const bf16*Qh,int PQ,const bf16*__restrict__ Kh_,int PK,const bf16*__restrict__ Vh_,int PV,bf16*Oh,int PO,const bf16*Gh,int PG,u32x4(&okeep)[4],int omode,float lam,float oml,const float ...
;     ...
;   for(;t+1<NT;t+=2){
;     STEP(pB0,pB1,pA0,pA1,t,(t+3<NT),(t+1<NT),(t+1<NT));       ENDW(t);   RESC(); ROT();
;     STEP(pA0,pA1,pB0,pB1,t+1,(t+4<NT),(t+2<NT),(t+2<NT));     ENDW(t+1); RESC(); ROT();
	ds_read_b64_tr_b16 v[210:211], v227 offset:32768
	ds_read_b64_tr_b16 v[212:213], v227 offset:33280
	v_add_f32_e32 v66, v114, v115
	v_add_f32_e32 v66, v116, v66
	v_add_f32_e32 v66, v117, v66
	v_add_f32_e32 v66, v118, v66
	v_add_f32_e32 v66, v119, v66
	v_cvt_pk_bf16_f32 v166, v114, v115
	v_cvt_pk_bf16_f32 v167, v116, v117
	s_waitcnt lgkmcnt(9)
	v_mfma_f32_32x32x16_bf16 v[98:113], v[78:81], v[174:177], v[50:65]
	ds_read_b64_tr_b16 v[114:115], v227 offset:36864
	ds_read_b64_tr_b16 v[116:117], v227 offset:37376
	v_add_f32_e32 v66, v120, v66
	v_add_f32_e32 v66, v121, v66
	v_add_f32_e32 v66, v122, v66
	v_add_f32_e32 v146, v123, v66
	s_waitcnt lgkmcnt(10)
	v_mfma_f32_32x32x16_bf16 v[66:81], v[138:141], v[174:177], v[50:65]
	v_cvt_pk_bf16_f32 v168, v118, v119
	v_cvt_pk_bf16_f32 v169, v120, v121
	ds_read_b64_tr_b16 v[138:139], v227 offset:33792
	ds_read_b64_tr_b16 v[140:141], v227 offset:34304
	v_add_f32_e32 v118, v124, v146
	v_add_f32_e32 v118, v125, v118
	v_add_f32_e32 v118, v126, v118
	v_add_f32_e32 v118, v127, v118
	v_cvt_pk_bf16_f32 v158, v122, v123
	v_cvt_pk_bf16_f32 v159, v124, v125
	s_waitcnt lgkmcnt(11)
	v_mfma_f32_32x32x16_bf16 v[98:113], v[142:145], v[170:173], v[98:113]
	ds_read_b64_tr_b16 v[120:121], v227 offset:37888
	ds_read_b64_tr_b16 v[122:123], v227 offset:38400
	s_waitcnt lgkmcnt(12)
	v_mfma_f32_32x32x16_bf16 v[66:81], v[178:181], v[170:173], v[66:81]
	v_add_f32_e32 v118, v128, v118
	v_add_f32_e32 v118, v129, v118
	v_add_f32_e32 v118, v82, v118
	v_add_f32_e32 v118, v83, v118
	v_cvt_pk_bf16_f32 v160, v126, v127
	v_cvt_pk_bf16_f32 v161, v128, v129
	ds_read_b64_tr_b16 v[124:125], v227 offset:34816
	ds_read_b64_tr_b16 v[126:127], v227 offset:35328
	v_add_f32_e32 v118, v84, v118
	v_add_f32_e32 v118, v85, v118
	v_add_f32_e32 v118, v86, v118
	v_add_f32_e32 v118, v87, v118
	v_cvt_pk_bf16_f32 v150, v82, v83
	v_cvt_pk_bf16_f32 v151, v84, v85
	s_waitcnt lgkmcnt(13)
	v_mfma_f32_32x32x16_bf16 v[98:113], v[182:185], v[162:165], v[98:113]
	ds_read_b64_tr_b16 v[82:83], v227 offset:38912
	ds_read_b64_tr_b16 v[84:85], v227 offset:39424
	s_waitcnt lgkmcnt(14)
	v_mfma_f32_32x32x16_bf16 v[66:81], v[186:189], v[162:165], v[66:81]
	v_add_f32_e32 v118, v88, v118
	v_add_f32_e32 v118, v89, v118
	v_add_f32_e32 v118, v90, v118
	v_add_f32_e32 v118, v91, v118
	v_cvt_pk_bf16_f32 v152, v86, v87
	v_cvt_pk_bf16_f32 v153, v88, v89
	ds_read_b64_tr_b16 v[86:87], v227 offset:35840
	ds_read_b64_tr_b16 v[88:89], v227 offset:36352
	v_add_f32_e32 v118, v92, v118
	v_add_f32_e32 v118, v93, v118
	v_add_f32_e32 v118, v94, v118
	v_add_f32_e32 v118, v95, v118
	v_cvt_pk_bf16_f32 v146, v90, v91
	v_cvt_pk_bf16_f32 v147, v92, v93
	s_waitcnt lgkmcnt(14)
	v_mfma_f32_32x32x16_bf16 v[98:113], v[134:137], v[154:157], v[98:113]
	ds_read_b64_tr_b16 v[90:91], v227 offset:39936
	ds_read_b64_tr_b16 v[92:93], v227 offset:40448
	v_mfma_f32_32x32x16_bf16 v[66:81], v[130:133], v[154:157], v[66:81]
	v_add_f32_e32 v118, v96, v118
	v_add_f32_e32 v118, v97, v118
	v_cvt_pk_bf16_f32 v148, v94, v95
	v_cvt_pk_bf16_f32 v149, v96, v97
	v_lshl_add_u64 v[94:95], v[208:209], 0, s[26:27]
	s_mov_b32 m0, s61
	s_nop 0
	global_load_lds_dwordx4 v[94:95], off
	v_add_f32_e32 v118, v214, v118
	s_waitcnt lgkmcnt(14)
	v_mfma_f32_32x32x16_bf16 v[18:33], v[166:169], v[210:213], v[18:33]
	v_exp_f32_e32 v98, v98
	v_exp_f32_e32 v99, v99
	v_exp_f32_e32 v100, v100
	v_exp_f32_e32 v101, v101
	s_waitcnt lgkmcnt(12)
	v_mfma_f32_32x32x16_bf16 v[34:49], v[166:169], v[114:117], v[34:49]
	v_exp_f32_e32 v102, v102
	v_exp_f32_e32 v103, v103
	v_exp_f32_e32 v104, v104
	v_exp_f32_e32 v105, v105
	ds_read_b128 v[128:131], v228
	ds_read_b128 v[132:135], v228 offset:512
	s_waitcnt lgkmcnt(12)
	v_mfma_f32_32x32x16_bf16 v[18:33], v[158:161], v[138:141], v[18:33]
	v_exp_f32_e32 v106, v106
	v_exp_f32_e32 v107, v107
	v_exp_f32_e32 v108, v108
	v_exp_f32_e32 v109, v109
	ds_read_b128 v[136:139], v228 offset:2048
	ds_read_b128 v[140:143], v228 offset:2560
	s_waitcnt lgkmcnt(12)
	v_mfma_f32_32x32x16_bf16 v[34:49], v[158:161], v[120:123], v[34:49]
	v_exp_f32_e32 v110, v110
	v_exp_f32_e32 v111, v111
	v_exp_f32_e32 v112, v112
	v_exp_f32_e32 v113, v113
	ds_read_b128 v[120:123], v228 offset:4096
	ds_read_b128 v[178:181], v228 offset:4608
	s_waitcnt lgkmcnt(12)
	v_mfma_f32_32x32x16_bf16 v[18:33], v[150:153], v[124:127], v[18:33]
	v_exp_f32_e32 v66, v66
	v_exp_f32_e32 v67, v67
	v_exp_f32_e32 v68, v68
	v_exp_f32_e32 v69, v69
	ds_read_b128 v[124:127], v228 offset:6144
	ds_read_b128 v[114:117], v228 offset:6656
	s_waitcnt lgkmcnt(12)
	v_mfma_f32_32x32x16_bf16 v[34:49], v[150:153], v[82:85], v[34:49]
	v_exp_f32_e32 v70, v70
	v_exp_f32_e32 v71, v71
	v_exp_f32_e32 v72, v72
	v_exp_f32_e32 v73, v73
	s_waitcnt lgkmcnt(10)
	v_mfma_f32_32x32x16_bf16 v[18:33], v[146:149], v[86:89], v[18:33]
	v_exp_f32_e32 v74, v74
	v_exp_f32_e32 v75, v75
	v_exp_f32_e32 v76, v76
	v_exp_f32_e32 v77, v77
	s_waitcnt lgkmcnt(8)
	v_mfma_f32_32x32x16_bf16 v[34:49], v[146:149], v[90:93], v[34:49]
	v_exp_f32_e32 v78, v78
	v_exp_f32_e32 v79, v79
	v_exp_f32_e32 v80, v80
	v_exp_f32_e32 v81, v81
	s_waitcnt vmcnt(0) lgkmcnt(0)
	s_barrier
;   #define RESC() do{ if(!FIXREF&&resc){ asm volatile("s_waitcnt lgkmcnt(0)":::"memory"); \
;       _Pragma("unroll") for(int d_=0;d_<2;++d_) _Pragma("unroll") for(int r=0;r<16;++r)o[d_][r]*=wsf[crow(r,hi)]; } }while(0)
; template<int THRL,bool FIXREF,bool HALFK> __device__ __forceinline__ void attn_unit(float mref,long rowbase,int q0,const bf16*Qh,int PQ,const bf16*__restrict__ Kh_,int PK,const bf16*__restrict__ Vh_,int PV,bf16*Oh,int PO,const bf16*Gh,int PG,u32x4(&okeep)[4],int omode,float lam,float oml,const float ...
;     ...
;   STEP(pB0,pB1,pA0,pA1,NT-1,false,false,false); RESC();
	ds_read_b64_tr_b16 v[182:183], v227 offset:40960
	ds_read_b64_tr_b16 v[184:185], v227 offset:41472
	v_add_f32_e32 v82, v98, v99
	v_add_f32_e32 v82, v100, v82
	v_add_f32_e32 v82, v101, v82
	v_add_f32_e32 v82, v102, v82
	v_add_f32_e32 v119, v103, v82
	v_cvt_pk_bf16_f32 v166, v98, v99
	v_cvt_pk_bf16_f32 v167, v100, v101
	s_waitcnt lgkmcnt(9)
	v_mfma_f32_32x32x16_bf16 v[82:97], v[128:131], v[174:177], v[50:65]
	ds_read_b64_tr_b16 v[98:99], v227 offset:45056
	ds_read_b64_tr_b16 v[100:101], v227 offset:45568
	v_add_f32_e32 v119, v104, v119
	v_add_f32_e32 v119, v105, v119
	v_add_f32_e32 v119, v106, v119
	v_add_f32_e32 v119, v107, v119
	v_cvt_pk_bf16_f32 v168, v102, v103
	v_cvt_pk_bf16_f32 v169, v104, v105
	s_waitcnt lgkmcnt(10)
	v_mfma_f32_32x32x16_bf16 v[50:65], v[132:135], v[174:177], v[50:65]
	ds_read_b64_tr_b16 v[102:103], v227 offset:41984
	ds_read_b64_tr_b16 v[104:105], v227 offset:42496
	v_add_f32_e32 v119, v108, v119
	v_add_f32_e32 v119, v109, v119
	v_add_f32_e32 v119, v110, v119
	v_add_f32_e32 v119, v111, v119
	v_cvt_pk_bf16_f32 v158, v106, v107
	v_cvt_pk_bf16_f32 v159, v108, v109
	s_waitcnt lgkmcnt(11)
	v_mfma_f32_32x32x16_bf16 v[82:97], v[136:139], v[170:173], v[82:97]
	ds_read_b64_tr_b16 v[106:107], v227 offset:46080
	ds_read_b64_tr_b16 v[108:109], v227 offset:46592
	v_add_f32_e32 v119, v112, v119
	v_add_f32_e32 v119, v113, v119
	v_add_f32_e32 v119, v66, v119
	v_add_f32_e32 v119, v67, v119
	v_cvt_pk_bf16_f32 v160, v110, v111
	v_cvt_pk_bf16_f32 v161, v112, v113
	s_waitcnt lgkmcnt(12)
	v_mfma_f32_32x32x16_bf16 v[50:65], v[140:143], v[170:173], v[50:65]
	ds_read_b64_tr_b16 v[110:111], v227 offset:43008
	ds_read_b64_tr_b16 v[112:113], v227 offset:43520
	v_add_f32_e32 v119, v68, v119
	v_add_f32_e32 v119, v69, v119
	v_add_f32_e32 v119, v70, v119
	v_add_f32_e32 v119, v71, v119
	v_cvt_pk_bf16_f32 v150, v66, v67
	v_cvt_pk_bf16_f32 v151, v68, v69
	s_waitcnt lgkmcnt(13)
	v_mfma_f32_32x32x16_bf16 v[82:97], v[120:123], v[162:165], v[82:97]
	ds_read_b64_tr_b16 v[66:67], v227 offset:47104
	ds_read_b64_tr_b16 v[68:69], v227 offset:47616
	v_add_f32_e32 v119, v72, v119
	v_add_f32_e32 v119, v73, v119
	v_add_f32_e32 v119, v74, v119
	v_add_f32_e32 v119, v75, v119
	v_cvt_pk_bf16_f32 v152, v70, v71
	v_cvt_pk_bf16_f32 v153, v72, v73
	s_waitcnt lgkmcnt(14)
	v_mfma_f32_32x32x16_bf16 v[50:65], v[178:181], v[162:165], v[50:65]
	ds_read_b64_tr_b16 v[70:71], v227 offset:44032
	ds_read_b64_tr_b16 v[72:73], v227 offset:44544
	v_add_f32_e32 v119, v76, v119
	v_add_f32_e32 v119, v77, v119
	v_add_f32_e32 v119, v78, v119
	v_add_f32_e32 v119, v79, v119
	v_cvt_pk_bf16_f32 v146, v74, v75
	v_cvt_pk_bf16_f32 v147, v76, v77
	s_waitcnt lgkmcnt(14)
	v_mfma_f32_32x32x16_bf16 v[82:97], v[124:127], v[154:157], v[82:97]
	ds_read_b64_tr_b16 v[74:75], v227 offset:48128
	ds_read_b64_tr_b16 v[76:77], v227 offset:48640
	v_mfma_f32_32x32x16_bf16 v[50:65], v[114:117], v[154:157], v[50:65]
	v_add_f32_e32 v114, v80, v119
	v_add_f32_e32 v114, v81, v114
	v_cvt_pk_bf16_f32 v148, v78, v79
	v_cvt_pk_bf16_f32 v149, v80, v81
	s_waitcnt lgkmcnt(14)
	v_mfma_f32_32x32x16_bf16 v[18:33], v[166:169], v[182:185], v[18:33]
	s_nop 1
	v_exp_f32_e32 v82, v82
	v_exp_f32_e32 v83, v83
	v_exp_f32_e32 v84, v84
	v_exp_f32_e32 v85, v85
	s_waitcnt lgkmcnt(12)
	v_mfma_f32_32x32x16_bf16 v[34:49], v[166:169], v[98:101], v[34:49]
	v_exp_f32_e32 v86, v86
	v_exp_f32_e32 v87, v87
	v_exp_f32_e32 v88, v88
	v_exp_f32_e32 v89, v89
	s_waitcnt lgkmcnt(10)
	v_mfma_f32_32x32x16_bf16 v[18:33], v[158:161], v[102:105], v[18:33]
	v_exp_f32_e32 v90, v90
	v_exp_f32_e32 v91, v91
	v_exp_f32_e32 v92, v92
	v_exp_f32_e32 v93, v93
	s_waitcnt lgkmcnt(8)
	v_mfma_f32_32x32x16_bf16 v[34:49], v[158:161], v[106:109], v[34:49]
	v_exp_f32_e32 v94, v94
	v_exp_f32_e32 v95, v95
	v_exp_f32_e32 v96, v96
	v_exp_f32_e32 v97, v97
	s_waitcnt lgkmcnt(6)
; #define SBAR() __builtin_amdgcn_sched_barrier(0)
;   #define RESC() do{ if(!FIXREF&&resc){ asm volatile("s_waitcnt lgkmcnt(0)":::"memory"); \
;       _Pragma("unroll") for(int d_=0;d_<2;++d_) _Pragma("unroll") for(int r=0;r<16;++r)o[d_][r]*=wsf[crow(r,hi)]; } }while(0)
;   #define PKW(P,B) cvtpk_s(P[B],P[B+1])
; template<int THRL,bool FIXREF,bool HALFK> __device__ __forceinline__ void attn_unit(float mref,long rowbase,int q0,const bf16*Qh,int PQ,const bf16*__restrict__ Kh_,int PK,const bf16*__restrict__ Vh_,int PV,bf16*Oh,int PO,const bf16*Gh,int PG,u32x4(&okeep)[4],int omode,float lam,float oml,const float ...
;     ...
;   STEP(pB0,pB1,pA0,pA1,NT-1,false,false,false); RESC();
;   { float sacc=pB0[0]+pB0[1]; _Pragma("unroll") for(int r=2;r<16;++r)sacc+=pB0[r]; _Pragma("unroll") for(int r=0;r<16;++r)sacc+=pB1[r]; l_reg+=sacc;
;     pw0=(u32x4){PKW(pB0,0),PKW(pB0,2),PKW(pB0,4),PKW(pB0,6)};pw1=(u32x4){PKW(pB0,8),PKW(pB0,10),PKW(pB0,12),PKW(pB0,14)};pw2=(u32x4){PKW(pB1,0),PKW(pB1,2),PKW(pB1,4),PKW(pB1,6)};pw3=(u32x4){PKW(pB1,8),PKW(pB1,10),PKW(pB1,12),PKW(pB1,14)};
;     SBAR(); pv(o,vb0+sl_cur,PAF(0),PAF(1),PAF(2),PAF(3)); }
;     ...
;   {auto rr=__builtin_amdgcn_permlane32_swap(__float_as_uint(l_reg),__float_as_uint(l_reg),false,false);l_reg=__uint_as_float(rr[0])+__uint_as_float(rr[1]);}
;   if(hi==0)wsf[32+r32]=l_reg;asm volatile("s_waitcnt lgkmcnt(0)":::"memory");
	v_mfma_f32_32x32x16_bf16 v[18:33], v[150:153], v[110:113], v[18:33]
	v_exp_f32_e32 v50, v50
	v_exp_f32_e32 v51, v51
	v_exp_f32_e32 v52, v52
	v_exp_f32_e32 v53, v53
	s_waitcnt lgkmcnt(4)
	v_mfma_f32_32x32x16_bf16 v[34:49], v[150:153], v[66:69], v[34:49]
	v_exp_f32_e32 v54, v54
	v_exp_f32_e32 v55, v55
	v_exp_f32_e32 v56, v56
	v_exp_f32_e32 v57, v57
	s_waitcnt lgkmcnt(2)
	v_mfma_f32_32x32x16_bf16 v[18:33], v[146:149], v[70:73], v[18:33]
	v_exp_f32_e32 v58, v58
	v_exp_f32_e32 v59, v59
	v_exp_f32_e32 v60, v60
	v_exp_f32_e32 v61, v61
	s_waitcnt lgkmcnt(0)
	v_mfma_f32_32x32x16_bf16 v[34:49], v[146:149], v[74:77], v[34:49]
	v_exp_f32_e32 v62, v62
	v_exp_f32_e32 v63, v63
	v_exp_f32_e32 v64, v64
	v_exp_f32_e32 v65, v65
	v_add_f32_e32 v66, v82, v83
	v_add_f32_e32 v66, v84, v66
	v_add_f32_e32 v66, v85, v66
	v_add_f32_e32 v66, v86, v66
	v_add_f32_e32 v66, v87, v66
	v_add_f32_e32 v66, v88, v66
	v_add_f32_e32 v66, v89, v66
	v_add_f32_e32 v66, v90, v66
	v_add_f32_e32 v66, v91, v66
	v_add_f32_e32 v66, v92, v66
	v_add_f32_e32 v66, v93, v66
	v_add_f32_e32 v66, v94, v66
	v_add_f32_e32 v66, v95, v66
	v_add_f32_e32 v66, v96, v66
	v_add_f32_e32 v66, v97, v66
	v_add_f32_e32 v66, v50, v66
	v_add_f32_e32 v66, v51, v66
	v_add_f32_e32 v66, v52, v66
	v_add_f32_e32 v66, v53, v66
	v_add_f32_e32 v66, v54, v66
	v_add_f32_e32 v66, v55, v66
	v_add_f32_e32 v66, v56, v66
	v_add_f32_e32 v66, v57, v66
	v_add_f32_e32 v66, v58, v66
	v_add_f32_e32 v66, v59, v66
	v_add_f32_e32 v66, v60, v66
	v_add_f32_e32 v66, v61, v66
	v_add_f32_e32 v66, v62, v66
	v_add_f32_e32 v66, v63, v66
	v_add_f32_e32 v66, v64, v66
	v_add_f32_e32 v66, v65, v66
	v_add_f32_e32 v67, v118, v114
	v_add_f32_e32 v66, v67, v66
	v_cvt_pk_bf16_f32 v68, v82, v83
	v_cvt_pk_bf16_f32 v69, v84, v85
	v_cvt_pk_bf16_f32 v70, v86, v87
	v_cvt_pk_bf16_f32 v71, v88, v89
	v_cvt_pk_bf16_f32 v72, v90, v91
	v_cvt_pk_bf16_f32 v73, v92, v93
	v_cvt_pk_bf16_f32 v74, v94, v95
	v_cvt_pk_bf16_f32 v75, v96, v97
	v_cvt_pk_bf16_f32 v50, v50, v51
	v_cvt_pk_bf16_f32 v51, v52, v53
	v_cvt_pk_bf16_f32 v52, v54, v55
	v_cvt_pk_bf16_f32 v53, v56, v57
	v_cvt_pk_bf16_f32 v54, v58, v59
	v_cvt_pk_bf16_f32 v55, v60, v61
	v_cvt_pk_bf16_f32 v56, v62, v63
	v_cvt_pk_bf16_f32 v57, v64, v65
	ds_read_b64_tr_b16 v[58:59],v0 offset:0
	ds_read_b64_tr_b16 v[60:61],v0 offset:512
	ds_read_b64_tr_b16 v[62:63],v0 offset:1024
	ds_read_b64_tr_b16 v[64:65],v0 offset:1536
	ds_read_b64_tr_b16 v[76:77],v0 offset:2048
	ds_read_b64_tr_b16 v[78:79],v0 offset:2560
	ds_read_b64_tr_b16 v[80:81],v0 offset:3072
	ds_read_b64_tr_b16 v[82:83],v0 offset:3584
	s_waitcnt lgkmcnt(0)
	s_nop 0
	v_mfma_f32_32x32x16_bf16 v[18:33], v[68:71], v[58:61], v[18:33]
	ds_read_b64_tr_b16 v[58:59],v0 offset:4096
	ds_read_b64_tr_b16 v[60:61],v0 offset:4608
	v_mfma_f32_32x32x16_bf16 v[18:33], v[72:75], v[62:65], v[18:33]
	ds_read_b64_tr_b16 v[62:63],v0 offset:5120
	ds_read_b64_tr_b16 v[64:65],v0 offset:5632
	v_mfma_f32_32x32x16_bf16 v[18:33], v[50:53], v[76:79], v[18:33]
	ds_read_b64_tr_b16 v[76:77],v0 offset:6144
	ds_read_b64_tr_b16 v[78:79],v0 offset:6656
	v_mfma_f32_32x32x16_bf16 v[18:33], v[54:57], v[80:83], v[18:33]
	ds_read_b64_tr_b16 v[80:81],v0 offset:7168
	ds_read_b64_tr_b16 v[82:83],v0 offset:7680
	s_waitcnt lgkmcnt(0)
	v_mfma_f32_32x32x16_bf16 v[34:49], v[68:71], v[58:61], v[34:49]
	v_mov_b32_e32 v0, v66
	s_nop 1
	v_permlane32_swap_b32_e32 v66, v0
	v_cmp_gt_u32_e32 vcc, 32, v205
	v_mfma_f32_32x32x16_bf16 v[34:49], v[72:75], v[62:65], v[34:49]
	v_mfma_f32_32x32x16_bf16 v[34:49], v[50:53], v[76:79], v[34:49]
	v_mfma_f32_32x32x16_bf16 v[34:49], v[54:57], v[80:83], v[34:49]
	s_and_saveexec_b64 s[40:41], vcc
	s_cbranch_execz .LBB0_449
	v_lshl_add_u32 v50, v216, 2, s42
	v_add_f32_e32 v0, v66, v0
	ds_write_b32 v50, v0 offset:49280
	s_branch .LBB0_449

;   #define CMASK(P0,P1,t) do{}while(0)
; template<int THRL,bool FIXREF,bool HALFK> __device__ __forceinline__ void attn_unit(float mref,long rowbase,int q0,const bf16*Qh,int PQ,const bf16*__restrict__ Kh_,int PK,const bf16*__restrict__ Vh_,int PV,bf16*Oh,int PO,const bf16*Gh,int PG,u32x4(&okeep)[4],int omode,float lam,float oml,const float ...
;   const int tid=fresh_tid(),lane=tid&63,r32=lane&31,hi=lane>>5; const int wid=__builtin_amdgcn_readfirstlane(tid>>6);
;   const bf16*Qw=Qh+(rowbase+q0+wid*QBLK)*PQ;
;   const bf16*Kh=Kh_+rowbase*PK,*Vh=Vh_+rowbase*PV;
;   const unsigned lds0=(unsigned)(uintptr_t)shm;
;   float*wsf=(float*)(shm+LDS_WS)+wid*64;
;   const bf16*ksrc=Kh+(long)lane*PK+wid*8;
;   const bf16*vsrc=Vh+(long)(16*(wid&3)+(lane>>2))*PV+(wid>>2)*32+(lane&3)*8;
;   const unsigned kdst=lds0+LDS_K+wid*1024, vdst=lds0+LDS_V+wid*1024;
;     ...
;   const int vb0=(int)(lds0+LDS_V)+((lane>>4)&1)*32+(lane&3)*8+(4*hi+((lane&15)>>2))*64;
;   const char*Kbase=shm+LDS_K; bf16x8 kf[8];
;   const lds_cptr shm3=(lds_cptr)shm; const lds_cptr kp0=shm3+LDS_K+hi*1024+r32*16; const lds_cptr vp0=shm3+LDS_V+((lane>>4)&1)*32+(lane&3)*8+(4*hi+((lane&15)>>2))*64;
;   constexpr int NT=SEQ/KVBLK;
;   if(Gh){ const bf16*Gw=Gh+(rowbase+q0+wid*QBLK)*PG;
;     #pragma unroll
;     for(int i=0;i<4;++i) glds16(Gw+(long)(i*8+(lane>>3))*PG+(lane&7)*8,(unsigned)__builtin_amdgcn_readfirstlane(lds0+LDS_GST+wid*4096+i*1024)); }
;   DMA_K(0,0);DMA_V(0,0);DMA_K(1,SLOTB);
;   bf16x8 qr[4];
;   #pragma unroll
;   for(int d0=0;d0<4;++d0)qr[d0]=*reinterpret_cast<const bf16x8*>(&Qw[(long)r32*PQ+d0*16+hi*8]);
;   float mhat=0.f,l_reg=0.f;f32x16 o[2];o[0]=f32x16{};o[1]=f32x16{};f32x16 negm=f32x16{};
;   if constexpr(FIXREF){ mhat=mref; _Pragma("unroll") for(int r=0;r<16;++r)negm[r]=-mref; }
;   asm volatile("":"+v"(negm));
;     ...
;   bool resc=false;
;     ...
;   f32x16 pA0,pA1,pB0,pB1;
;   int sl_prev=0,sl_cur=0,sl_next=SLOTB;
;     ...
;   DMA_K(2,2*SLOTB);
;   WAIT_BAR(3);
;   qkt<HALFK?2:4>(pA0,pA1,Kbase,qr,negm,r32,hi);asm volatile("s_nop 15\n\ts_nop 7":"+v"(pA0),"+v"(pA1));CMASK(pA0,pA1,0);
;   START(pA0,pA1);
;   _Pragma("unroll") for(int r=0;r<16;++r)pA1[r]=__builtin_amdgcn_exp2f(pA1[r]);
;   WAIT_BAR(0);
; __device__ __forceinline__ void phase_attn(int l, char* lds_generic, int vcu, int G) {
;     ...
;         for (int du = vcu; du < 32 * 16; du += G)
;             for (int mp = 0; mp < 2; ++mp) { ATTN_C_ARGS
.LBB0_458:
	s_waitcnt lgkmcnt(3)
	v_mov_b32_e32 v176, v26
	v_mov_b32_e32 v177, v27
	v_mov_b32_e32 v178, v28
	v_mov_b32_e32 v179, v29
	s_waitcnt lgkmcnt(2)
	v_mov_b32_e32 v180, v30
	v_mov_b32_e32 v181, v31
	v_mov_b32_e32 v182, v32
	v_mov_b32_e32 v183, v33
	s_waitcnt lgkmcnt(1)
	v_mov_b32_e32 v184, v22
	v_mov_b32_e32 v185, v23
	v_mov_b32_e32 v186, v24
	v_mov_b32_e32 v187, v25
	s_waitcnt lgkmcnt(0)
	v_mov_b32_e32 v188, v18
	v_mov_b32_e32 v189, v19
	v_mov_b32_e32 v206, v20
	v_mov_b32_e32 v207, v21
	v_mov_b32_e32 v102, v218
	s_nop 0
	v_readfirstlane_b32 s83, v102
	s_ashr_i32 s79, s83, 6
	s_lshl_b32 s20, s79, 5
	s_ashr_i32 s40, s20, 31
	v_lshlrev_b32_e32 v211, 3, v102
	v_and_b32_e32 v209, 63, v102
	s_add_u32 s46, s0, s20
	v_and_b32_e32 v210, 56, v211
	s_addc_u32 s47, s1, s40
	s_and_b64 vcc, exec, s[48:49]
	v_lshrrev_b32_e32 v208, 3, v209
	v_lshlrev_b32_e32 v170, 1, v210
	s_cbranch_vccnz .LBB0_460
	s_mul_i32 s20, s47, 0x1e00
	s_mul_hi_u32 s40, s46, 0x1e00
	s_add_i32 s20, s40, s20
	s_mul_i32 s40, s46, 0x1e00
	s_add_u32 s40, s75, s40
	s_addc_u32 s41, s76, s20
	s_lshl_b32 s20, s79, 12
	v_mov_b32_e32 v171, v1
	s_cmp_lg_u32 0, -1
	v_lshl_add_u64 v[18:19], s[40:41], 0, v[170:171]
	v_mul_u32_u24_e32 v0, 0xf00, v208
	s_cselect_b32 s40, 0, 0
	v_lshlrev_b32_e32 v0, 1, v0
	s_add_i32 s20, s40, s20
	v_lshl_add_u64 v[18:19], v[18:19], 0, v[0:1]
	s_add_i32 s40, s20, 0x14800
	s_mov_b32 m0, s40
	s_nop 0
	global_load_lds_dwordx4 v[18:19], off
	v_lshl_add_u64 v[20:21], v[18:19], 0, s[30:31]
	s_add_i32 s40, s20, 0x14c00
	s_mov_b32 m0, s40
	s_nop 0
	global_load_lds_dwordx4 v[20:21], off
	v_lshl_add_u64 v[20:21], v[18:19], 0, s[56:57]
	s_add_i32 s40, s20, 0x15000
	s_mov_b32 m0, s40
	s_nop 0
	global_load_lds_dwordx4 v[20:21], off
	v_lshl_add_u64 v[18:19], v[18:19], 0, s[8:9]
	s_add_i32 s20, s20, 0x15400
	s_mov_b32 m0, s20
	s_nop 0
	global_load_lds_dwordx4 v[18:19], off
.LBB0_460:
	s_or_b32 s20, s88, s68
	s_xor_b64 s[42:43], s[42:43], -1
	s_xor_b64 s[40:41], s[48:49], -1
	s_lshl_b64 s[48:49], s[20:21], 1
	s_add_u32 s20, s2, s48
	s_addc_u32 s80, s3, s49
	s_lshl_b64 s[50:51], s[46:47], 9
	s_add_u32 s84, s20, s50
	s_addc_u32 s85, s80, s51
	s_add_u32 s48, s71, s48
	s_addc_u32 s49, s73, s49
	v_lshlrev_b32_e32 v0, 9, v209
	v_lshl_add_u64 v[18:19], s[48:49], 0, v[0:1]
	s_lshl_b32 s48, s79, 3
	s_ashr_i32 s49, s48, 31
	s_lshl_b64 s[48:49], s[48:49], 1
	v_lshl_add_u64 v[174:175], v[18:19], 0, s[48:49]
	s_lshl_b32 s20, s79, 4
	v_lshrrev_b32_e32 v18, 2, v209
	v_and_or_b32 v18, s20, 48, v18
	s_ashr_i32 s20, s83, 3
	s_and_b32 s50, s20, 0xffffffe0
	s_ashr_i32 s51, s50, 31
	v_mul_u32_u24_e32 v18, 0xf00, v18
	s_lshl_b64 s[50:51], s[50:51], 1
	s_lshl_b32 s82, s79, 10
	v_lshlrev_b32_e32 v104, 1, v18
	v_mov_b32_e32 v105, v1
	s_cmp_lg_u32 0, -1
	v_lshl_add_u64 v[18:19], s[16:17], 0, v[104:105]
	v_and_b32_e32 v215, 24, v211
	s_cselect_b32 s20, 0, 0
	v_lshl_add_u64 v[18:19], v[18:19], 0, s[50:51]
	v_lshlrev_b32_e32 v20, 1, v215
	v_mov_b32_e32 v21, v1
	s_add_i32 s81, s82, s20
	s_mov_b32 m0, s81
	s_nop 0
	global_load_lds_dwordx4 v[174:175], off
	v_and_b32_e32 v171, 31, v102
	v_lshl_add_u64 v[172:173], v[18:19], 0, v[20:21]
	s_add_i32 s80, s81, 0x6000
	s_mov_b32 m0, s80
	s_nop 0
	global_load_lds_dwordx4 v[172:173], off
	v_lshl_add_u64 v[18:19], v[174:175], 0, s[10:11]
	v_lshrrev_b32_e32 v212, 5, v209
	s_add_i32 s20, s81, 0x2000
	s_mov_b32 m0, s20
	s_nop 0
	global_load_lds_dwordx4 v[18:19], off
	v_lshlrev_b32_e32 v18, 9, v171
	v_lshl_or_b32 v18, v212, 4, v18
	global_load_dwordx4 v[166:169], v18, s[84:85]
	global_load_dwordx4 v[162:165], v18, s[84:85] offset:32
	v_mov_b64_e32 v[64:65], v[16:17]
	v_mov_b64_e32 v[62:63], v[14:15]
	v_mov_b64_e32 v[60:61], v[12:13]
	v_mov_b64_e32 v[58:59], v[10:11]
	v_mov_b64_e32 v[56:57], v[8:9]
	v_mov_b64_e32 v[54:55], v[6:7]
	v_mov_b64_e32 v[52:53], v[4:5]
	v_mov_b64_e32 v[50:51], v[2:3]
	v_lshlrev_b32_e32 v18, 10, v212
	v_lshlrev_b32_e32 v19, 4, v171
	v_add3_u32 v214, 0, v18, v19
	v_lshl_add_u64 v[18:19], v[174:175], 0, s[92:93]
	s_add_i32 s20, s81, 0x4000
	s_mov_b32 m0, s20
	s_nop 0
	global_load_lds_dwordx4 v[18:19], off
	s_waitcnt vmcnt(3) lgkmcnt(0)
	s_barrier
	ds_read_b128 v[18:21], v214
	ds_read_b128 v[66:69], v214 offset:512
	ds_read_b128 v[70:73], v214 offset:2560
	ds_read_b128 v[74:77], v214 offset:2048
	v_lshl_add_u64 v[98:99], v[174:175], 0, s[36:37]
	v_lshl_add_u64 v[100:101], v[172:173], 0, s[22:23]
	s_add_i32 s20, s81, 0x8000
	v_mov_b32_e32 v227, 0
	s_mov_b32 s84, -1
	s_mov_b32 s87, 0
	s_movk_i32 s86, 0x2000
	s_movk_i32 s85, 0x4000
	s_waitcnt vmcnt(1) lgkmcnt(3)
	v_mfma_f32_32x32x16_bf16 v[34:49], v[18:21], v[166:169], v[50:65]
	s_waitcnt lgkmcnt(2)
	v_mfma_f32_32x32x16_bf16 v[18:33], v[66:69], v[166:169], v[50:65]
	v_lshlrev_b32_e32 v66, 1, v102
	v_lshlrev_b32_e32 v67, 4, v102
	v_and_b32_e32 v216, 32, v66
	v_and_b32_e32 v66, 0xc0, v67
	v_lshl_or_b32 v217, v212, 8, v66
	v_add_u32_e32 v66, 0, v216
	v_add3_u32 v213, v66, v215, v217
	s_waitcnt vmcnt(0) lgkmcnt(0)
	v_mfma_f32_32x32x16_bf16 v[34:49], v[74:77], v[162:165], v[34:49]
	v_mfma_f32_32x32x16_bf16 v[18:33], v[70:73], v[162:165], v[18:33]
	s_nop 15
	s_nop 7
	s_waitcnt vmcnt(0) lgkmcnt(0)
	s_barrier
; #define WAIT_BAR(N) asm volatile("s_waitcnt vmcnt(" #N ") lgkmcnt(0)\n\ts_barrier":::"memory")
; __device__ __forceinline__ void kload2(bf16x8*kf,lds_cptr kp,int j){ kf[2*j]=*(const __attribute__((address_space(3))) bf16x8*)(kp+j*2048); kf[2*j+1]=*(const __attribute__((address_space(3))) bf16x8*)(kp+j*2048+512); }
;   #define DMA_K(t,slot) glds16(ksrc+(long)(t)*KVBLK*PK,(unsigned)__builtin_amdgcn_readfirstlane(kdst+(slot)))
;   #define DMA_V(t,slot) glds16(vsrc+(long)(t)*KVBLK*PV,(unsigned)__builtin_amdgcn_readfirstlane(vdst+(slot)))
;   #define ROT() do{sl_prev=sl_cur;sl_cur=sl_next;sl_next=(sl_next==(NSLOT-1)*SLOTB)?0:sl_next+SLOTB;}while(0)
; template<int THRL,bool FIXREF,bool HALFK> __device__ __forceinline__ void attn_unit(float mref,long rowbase,int q0,const bf16*Qh,int PQ,const bf16*__restrict__ Kh_,int PK,const bf16*__restrict__ Vh_,int PV,bf16*Oh,int PO,const bf16*Gh,int PG,u32x4(&okeep)[4],int omode,float lam,float oml,const float ...
;     ...
;   START(pA0,pA1);
;   _Pragma("unroll") for(int r=0;r<16;++r)pA1[r]=__builtin_amdgcn_exp2f(pA1[r]);
;   WAIT_BAR(0);
;   DMA_K(3,0);DMA_V(1,SLOTB);
;   ROT();
;   if constexpr(HALFK){ kload2(kf,kp0+sl_cur,0); kload2(kf,kp0+sl_cur,1); } else kload8(kf,kp0+sl_cur);
;   WAIT_BAR(2);
	s_mov_b32 m0, s81
	s_nop 0
	global_load_lds_dwordx4 v[98:99], off
	s_nop 0
	s_mov_b32 m0, s20
	s_nop 0
	global_load_lds_dwordx4 v[100:101], off
	s_nop 10
	v_exp_f32_e32 v66, v18
	ds_read_b128 v[98:101], v214 offset:8192
	ds_read_b128 v[134:137], v214 offset:8704
	ds_read_b128 v[138:141], v214 offset:10240
	ds_read_b128 v[130:133], v214 offset:10752
	v_and_b32_e32 v18, 3, v102
	s_add_i32 s20, s67, s88
	v_exp_f32_e32 v67, v19
	v_lshl_or_b32 v18, v18, 4, s50
	v_mov_b32_e32 v19, s51
	s_lshl_b64 s[50:51], s[20:21], 1
	s_add_u32 s20, s77, s50
	v_exp_f32_e32 v82, v34
	v_exp_f32_e32 v83, v35
	v_exp_f32_e32 v84, v36
	v_exp_f32_e32 v85, v37
	v_exp_f32_e32 v86, v38
	v_exp_f32_e32 v87, v39
	v_exp_f32_e32 v88, v40
	v_exp_f32_e32 v89, v41
	v_exp_f32_e32 v90, v42
	v_exp_f32_e32 v91, v43
	v_exp_f32_e32 v92, v44
	v_exp_f32_e32 v93, v45
	v_exp_f32_e32 v94, v46
	v_exp_f32_e32 v95, v47
	v_exp_f32_e32 v96, v48
	v_exp_f32_e32 v97, v49
	v_exp_f32_e32 v68, v20
	v_exp_f32_e32 v69, v21
	v_exp_f32_e32 v70, v22
	v_exp_f32_e32 v71, v23
	v_exp_f32_e32 v72, v24
	v_exp_f32_e32 v73, v25
	v_exp_f32_e32 v74, v26
	v_exp_f32_e32 v75, v27
	v_exp_f32_e32 v76, v28
	v_exp_f32_e32 v77, v29
	v_exp_f32_e32 v78, v30
	v_exp_f32_e32 v79, v31
	v_exp_f32_e32 v80, v32
	v_exp_f32_e32 v81, v33
	s_addc_u32 s50, s78, s51
	s_waitcnt vmcnt(2) lgkmcnt(0)
	s_barrier
	s_add_u32 s48, s20, s48
	v_lshl_add_u64 v[18:19], v[18:19], 0, v[104:105]
	s_addc_u32 s49, s50, s49
	v_lshl_add_u64 v[142:143], s[34:35], 0, v[18:19]
	v_lshl_add_u64 v[144:145], s[48:49], 0, v[0:1]
	v_mov_b32_e32 v18, 0
	v_mov_b32_e32 v19, v227
	v_mov_b32_e32 v20, v227
	v_mov_b32_e32 v21, v227
	v_mov_b32_e32 v22, v227
	v_mov_b32_e32 v23, v227
	v_mov_b32_e32 v24, v227
	v_mov_b32_e32 v25, v227
	v_mov_b32_e32 v26, v227
	v_mov_b32_e32 v27, v227
	v_mov_b32_e32 v28, v227
	v_mov_b32_e32 v29, v227
	v_mov_b32_e32 v30, v227
	v_mov_b32_e32 v31, v227
	v_mov_b32_e32 v32, v227
	v_mov_b32_e32 v33, v227
	v_mov_b32_e32 v34, 0
	v_mov_b32_e32 v35, v227
	v_mov_b32_e32 v36, v227
	v_mov_b32_e32 v37, v227
	v_mov_b32_e32 v38, v227
	v_mov_b32_e32 v39, v227
	v_mov_b32_e32 v40, v227
	v_mov_b32_e32 v41, v227
	v_mov_b32_e32 v42, v227
	v_mov_b32_e32 v43, v227
	v_mov_b32_e32 v44, v227
	v_mov_b32_e32 v45, v227
	v_mov_b32_e32 v46, v227
	v_mov_b32_e32 v47, v227
	v_mov_b32_e32 v48, v227
	v_mov_b32_e32 v49, v227
.LBB0_461:
	v_add_u32_e32 v0, s87, v213
	ds_read_b64_tr_b16 v[228:229], v0 offset:24576
	ds_read_b64_tr_b16 v[230:231], v0 offset:25088
	v_add_f32_e32 v102, v82, v83
	v_add_f32_e32 v102, v84, v102
	v_add_f32_e32 v102, v85, v102
	v_add_f32_e32 v102, v86, v102
	v_add_f32_e32 v102, v87, v102
	v_cvt_pk_bf16_f32 v158, v82, v83
	v_cvt_pk_bf16_f32 v159, v84, v85
	s_waitcnt lgkmcnt(5)
	v_mfma_f32_32x32x16_bf16 v[114:129], v[98:101], v[166:169], v[50:65]
	ds_read_b64_tr_b16 v[82:83], v0 offset:28672
	ds_read_b64_tr_b16 v[84:85], v0 offset:29184
	v_add_f32_e32 v98, v88, v102
	v_add_f32_e32 v98, v89, v98
	v_add_f32_e32 v98, v90, v98
	v_add_f32_e32 v146, v91, v98
	s_waitcnt lgkmcnt(6)
	v_mfma_f32_32x32x16_bf16 v[98:113], v[134:137], v[166:169], v[50:65]
	v_cvt_pk_bf16_f32 v160, v86, v87
	v_cvt_pk_bf16_f32 v161, v88, v89
	ds_read_b64_tr_b16 v[86:87], v0 offset:25600
	ds_read_b64_tr_b16 v[88:89], v0 offset:26112
	v_add_f32_e32 v134, v92, v146
	v_add_f32_e32 v134, v93, v134
	v_add_f32_e32 v134, v94, v134
	v_add_f32_e32 v134, v95, v134
	v_cvt_pk_bf16_f32 v154, v90, v91
	v_cvt_pk_bf16_f32 v155, v92, v93
	s_waitcnt lgkmcnt(7)
	v_mfma_f32_32x32x16_bf16 v[114:129], v[138:141], v[162:165], v[114:129]
	ds_read_b64_tr_b16 v[90:91], v0 offset:29696
	ds_read_b64_tr_b16 v[92:93], v0 offset:30208
	s_waitcnt lgkmcnt(8)
	v_mfma_f32_32x32x16_bf16 v[98:113], v[130:133], v[162:165], v[98:113]
	v_add_f32_e32 v130, v96, v134
	v_add_f32_e32 v130, v97, v130
	v_add_f32_e32 v130, v66, v130
	v_add_f32_e32 v130, v67, v130
	v_cvt_pk_bf16_f32 v156, v94, v95
	v_cvt_pk_bf16_f32 v157, v96, v97
	ds_read_b64_tr_b16 v[94:95], v0 offset:26624
	ds_read_b64_tr_b16 v[96:97], v0 offset:27136
	v_add_f32_e32 v130, v68, v130
	v_add_f32_e32 v130, v69, v130
	v_add_f32_e32 v130, v70, v130
	v_add_f32_e32 v130, v71, v130
	v_cvt_pk_bf16_f32 v150, v66, v67
	v_cvt_pk_bf16_f32 v151, v68, v69
	ds_read_b64_tr_b16 v[66:67], v0 offset:30720
	ds_read_b64_tr_b16 v[68:69], v0 offset:31232
	v_add_f32_e32 v130, v72, v130
	v_add_f32_e32 v130, v73, v130
	v_add_f32_e32 v130, v74, v130
	v_add_f32_e32 v130, v75, v130
	v_cvt_pk_bf16_f32 v152, v70, v71
	v_cvt_pk_bf16_f32 v153, v72, v73
	ds_read_b64_tr_b16 v[70:71], v0 offset:27648
	ds_read_b64_tr_b16 v[72:73], v0 offset:28160
	v_add_f32_e32 v130, v76, v130
	v_add_f32_e32 v130, v77, v130
	v_add_f32_e32 v130, v78, v130
	v_add_f32_e32 v130, v79, v130
	v_cvt_pk_bf16_f32 v146, v74, v75
	v_cvt_pk_bf16_f32 v147, v76, v77
	ds_read_b64_tr_b16 v[74:75], v0 offset:31744
	ds_read_b64_tr_b16 v[76:77], v0 offset:32256
	v_add_f32_e32 v0, v80, v130
	v_add_f32_e32 v0, v81, v0
	v_cvt_pk_bf16_f32 v148, v78, v79
	v_cvt_pk_bf16_f32 v149, v80, v81
	v_lshl_add_u64 v[78:79], v[144:145], 0, s[36:37]
	s_add_i32 s20, s86, s81
	s_mov_b32 m0, s20
	s_nop 0
	global_load_lds_dwordx4 v[78:79], off
	v_lshl_add_u64 v[78:79], v[142:143], 0, s[22:23]
	s_add_i32 s20, s85, s80
	s_mov_b32 m0, s20
	s_nop 0
	global_load_lds_dwordx4 v[78:79], off
	v_add_f32_e32 v0, v227, v0
	s_waitcnt lgkmcnt(14)
	v_mfma_f32_32x32x16_bf16 v[18:33], v[158:161], v[228:231], v[18:33]
	v_exp_f32_e32 v114, v114
	v_exp_f32_e32 v115, v115
	v_exp_f32_e32 v116, v116
	v_exp_f32_e32 v117, v117
	s_waitcnt lgkmcnt(12)
; #define WAIT_BAR(N) asm volatile("s_waitcnt vmcnt(" #N ") lgkmcnt(0)\n\ts_barrier":::"memory")
;   #define RESC() do{ if(!FIXREF&&resc){ asm volatile("s_waitcnt lgkmcnt(0)":::"memory"); \
;       _Pragma("unroll") for(int d_=0;d_<2;++d_) _Pragma("unroll") for(int r=0;r<16;++r)o[d_][r]*=wsf[crow(r,hi)]; } }while(0)
;   #define ROT() do{sl_prev=sl_cur;sl_cur=sl_next;sl_next=(sl_next==(NSLOT-1)*SLOTB)?0:sl_next+SLOTB;}while(0)
; template<int THRL,bool FIXREF,bool HALFK> __device__ __forceinline__ void attn_unit(float mref,long rowbase,int q0,const bf16*Qh,int PQ,const bf16*__restrict__ Kh_,int PK,const bf16*__restrict__ Vh_,int PV,bf16*Oh,int PO,const bf16*Gh,int PG,u32x4(&okeep)[4],int omode,float lam,float oml,const float ...
;     ...
;   int t=1;
;     ...
;   for(;t+5<NT;t+=2){
;     STEP(pB0,pB1,pA0,pA1,t,true,true,true);     WAIT_BAR(2); RESC(); ROT();
;     STEP(pA0,pA1,pB0,pB1,t+1,true,true,true);   WAIT_BAR(2); RESC(); ROT();
	v_mfma_f32_32x32x16_bf16 v[34:49], v[158:161], v[82:85], v[34:49]
	v_exp_f32_e32 v118, v118
	v_exp_f32_e32 v119, v119
	v_exp_f32_e32 v120, v120
	v_exp_f32_e32 v121, v121
	v_add_u32_e32 v82, s85, v214
	ds_read_b128 v[78:81], v82
	ds_read_b128 v[130:133], v82 offset:512
	s_waitcnt lgkmcnt(12)
	v_mfma_f32_32x32x16_bf16 v[18:33], v[154:157], v[86:89], v[18:33]
	v_exp_f32_e32 v122, v122
	v_exp_f32_e32 v123, v123
	v_exp_f32_e32 v124, v124
	v_exp_f32_e32 v125, v125
	ds_read_b128 v[134:137], v82 offset:2048
	ds_read_b128 v[138:141], v82 offset:2560
	s_waitcnt lgkmcnt(12)
	v_mfma_f32_32x32x16_bf16 v[34:49], v[154:157], v[90:93], v[34:49]
	v_exp_f32_e32 v126, v126
	v_exp_f32_e32 v127, v127
	v_exp_f32_e32 v128, v128
	v_exp_f32_e32 v129, v129
	s_waitcnt lgkmcnt(10)
	v_mfma_f32_32x32x16_bf16 v[18:33], v[150:153], v[94:97], v[18:33]
	v_exp_f32_e32 v98, v98
	v_exp_f32_e32 v99, v99
	v_exp_f32_e32 v100, v100
	v_exp_f32_e32 v101, v101
	s_waitcnt lgkmcnt(8)
	v_mfma_f32_32x32x16_bf16 v[34:49], v[150:153], v[66:69], v[34:49]
	v_exp_f32_e32 v102, v102
	v_exp_f32_e32 v103, v103
	v_exp_f32_e32 v104, v104
	v_exp_f32_e32 v105, v105
	s_waitcnt lgkmcnt(6)
	v_mfma_f32_32x32x16_bf16 v[18:33], v[146:149], v[70:73], v[18:33]
	v_exp_f32_e32 v106, v106
	v_exp_f32_e32 v107, v107
	v_exp_f32_e32 v108, v108
	v_exp_f32_e32 v109, v109
	s_waitcnt lgkmcnt(4)
	v_mfma_f32_32x32x16_bf16 v[34:49], v[146:149], v[74:77], v[34:49]
	v_exp_f32_e32 v110, v110
	v_exp_f32_e32 v111, v111
	v_exp_f32_e32 v112, v112
	v_exp_f32_e32 v113, v113
	s_waitcnt vmcnt(2) lgkmcnt(0)
	s_barrier
	s_add_i32 s20, s85, 0x2000
	s_cmpk_lg_i32 s85, 0x4000
	s_cselect_b32 s20, s20, 0
	v_add_u32_e32 v227, s86, v213
	ds_read_b64_tr_b16 v[228:229], v227 offset:24576
	ds_read_b64_tr_b16 v[230:231], v227 offset:25088
	s_waitcnt lgkmcnt(5)
	v_mfma_f32_32x32x16_bf16 v[82:97], v[78:81], v[166:169], v[50:65]
	v_add_f32_e32 v66, v114, v115
	v_add_f32_e32 v66, v116, v66
	v_add_f32_e32 v66, v117, v66
	v_add_f32_e32 v66, v118, v66
	v_add_f32_e32 v66, v119, v66
	v_cvt_pk_bf16_f32 v158, v114, v115
	v_cvt_pk_bf16_f32 v159, v116, v117
	ds_read_b64_tr_b16 v[114:115], v227 offset:28672
	ds_read_b64_tr_b16 v[116:117], v227 offset:29184
	v_add_f32_e32 v66, v120, v66
	v_add_f32_e32 v66, v121, v66
	v_add_f32_e32 v66, v122, v66
	v_add_f32_e32 v146, v123, v66
	s_waitcnt lgkmcnt(6)
	v_mfma_f32_32x32x16_bf16 v[66:81], v[130:133], v[166:169], v[50:65]
	v_cvt_pk_bf16_f32 v160, v118, v119
	v_cvt_pk_bf16_f32 v161, v120, v121
	ds_read_b64_tr_b16 v[118:119], v227 offset:25600
	ds_read_b64_tr_b16 v[120:121], v227 offset:26112
	s_waitcnt lgkmcnt(7)
	v_mfma_f32_32x32x16_bf16 v[82:97], v[134:137], v[162:165], v[82:97]
	v_add_f32_e32 v130, v124, v146
	v_add_f32_e32 v130, v125, v130
	v_add_f32_e32 v130, v126, v130
	v_add_f32_e32 v130, v127, v130
	v_cvt_pk_bf16_f32 v154, v122, v123
	v_cvt_pk_bf16_f32 v155, v124, v125
	ds_read_b64_tr_b16 v[122:123], v227 offset:29696
	ds_read_b64_tr_b16 v[124:125], v227 offset:30208
	s_waitcnt lgkmcnt(8)
	v_mfma_f32_32x32x16_bf16 v[66:81], v[138:141], v[162:165], v[66:81]
	v_add_f32_e32 v130, v128, v130
	v_add_f32_e32 v130, v129, v130
	v_add_f32_e32 v130, v98, v130
	v_add_f32_e32 v130, v99, v130
	v_cvt_pk_bf16_f32 v156, v126, v127
	v_cvt_pk_bf16_f32 v157, v128, v129
	ds_read_b64_tr_b16 v[126:127], v227 offset:26624
	ds_read_b64_tr_b16 v[128:129], v227 offset:27136
	v_add_f32_e32 v130, v100, v130
	v_add_f32_e32 v130, v101, v130
	v_add_f32_e32 v130, v102, v130
	v_add_f32_e32 v130, v103, v130
	v_cvt_pk_bf16_f32 v150, v98, v99
	v_cvt_pk_bf16_f32 v151, v100, v101
	ds_read_b64_tr_b16 v[232:233], v227 offset:30720
	ds_read_b64_tr_b16 v[234:235], v227 offset:31232
	v_add_f32_e32 v98, v104, v130
	v_add_f32_e32 v98, v105, v98
	v_add_f32_e32 v98, v106, v98
	v_add_f32_e32 v98, v107, v98
	v_cvt_pk_bf16_f32 v152, v102, v103
	v_cvt_pk_bf16_f32 v153, v104, v105
	ds_read_b64_tr_b16 v[102:103], v227 offset:27648
	ds_read_b64_tr_b16 v[104:105], v227 offset:28160
	v_add_f32_e32 v98, v108, v98
	v_add_f32_e32 v98, v109, v98
	v_add_f32_e32 v98, v110, v98
	v_add_f32_e32 v98, v111, v98
	v_cvt_pk_bf16_f32 v146, v106, v107
	v_cvt_pk_bf16_f32 v147, v108, v109
	ds_read_b64_tr_b16 v[106:107], v227 offset:31744
	ds_read_b64_tr_b16 v[108:109], v227 offset:32256
	v_add_f32_e32 v98, v112, v98
	v_add_f32_e32 v98, v113, v98
	v_cvt_pk_bf16_f32 v148, v110, v111
	v_cvt_pk_bf16_f32 v149, v112, v113
	s_nop 0
	v_add_f32_e32 v227, v0, v98
	v_lshl_add_u64 v[98:99], v[144:145], 0, s[96:97]
	s_add_i32 s48, s85, s81
	s_mov_b32 m0, s48
	s_nop 0
	global_load_lds_dwordx4 v[98:99], off
	v_lshl_add_u64 v[142:143], v[142:143], 0, s[4:5]
	s_add_i32 s48, s20, s80
	s_mov_b32 m0, s48
	s_nop 0
	global_load_lds_dwordx4 v[142:143], off
	s_waitcnt lgkmcnt(14)
	v_mfma_f32_32x32x16_bf16 v[18:33], v[158:161], v[228:231], v[18:33]
	v_exp_f32_e32 v82, v82
	v_exp_f32_e32 v83, v83
	v_exp_f32_e32 v84, v84
	v_exp_f32_e32 v85, v85
	s_waitcnt lgkmcnt(12)
	v_mfma_f32_32x32x16_bf16 v[34:49], v[158:161], v[114:117], v[34:49]
	v_exp_f32_e32 v86, v86
	v_exp_f32_e32 v87, v87
	v_exp_f32_e32 v88, v88
	v_exp_f32_e32 v89, v89
	v_add_u32_e32 v0, s20, v214
	ds_read_b128 v[98:101], v0
	ds_read_b128 v[134:137], v0 offset:512
	s_waitcnt lgkmcnt(12)
	v_mfma_f32_32x32x16_bf16 v[18:33], v[154:157], v[118:121], v[18:33]
	v_exp_f32_e32 v90, v90
	v_exp_f32_e32 v91, v91
	v_exp_f32_e32 v92, v92
	v_exp_f32_e32 v93, v93
	ds_read_b128 v[138:141], v0 offset:2048
	ds_read_b128 v[130:133], v0 offset:2560
	s_waitcnt lgkmcnt(12)
	v_mfma_f32_32x32x16_bf16 v[34:49], v[154:157], v[122:125], v[34:49]
	v_exp_f32_e32 v94, v94
	v_exp_f32_e32 v95, v95
	v_exp_f32_e32 v96, v96
	v_exp_f32_e32 v97, v97
	s_waitcnt lgkmcnt(10)
	v_mfma_f32_32x32x16_bf16 v[18:33], v[150:153], v[126:129], v[18:33]
	v_exp_f32_e32 v66, v66
	v_exp_f32_e32 v67, v67
	v_exp_f32_e32 v68, v68
	v_exp_f32_e32 v69, v69
	s_waitcnt lgkmcnt(8)
	v_mfma_f32_32x32x16_bf16 v[34:49], v[150:153], v[232:235], v[34:49]
	v_exp_f32_e32 v70, v70
	v_exp_f32_e32 v71, v71
	v_exp_f32_e32 v72, v72
	v_exp_f32_e32 v73, v73
	s_waitcnt lgkmcnt(6)
	v_mfma_f32_32x32x16_bf16 v[18:33], v[146:149], v[102:105], v[18:33]
	v_exp_f32_e32 v74, v74
	v_exp_f32_e32 v75, v75
	v_exp_f32_e32 v76, v76
	v_exp_f32_e32 v77, v77
	s_waitcnt lgkmcnt(4)
	v_mfma_f32_32x32x16_bf16 v[34:49], v[146:149], v[106:109], v[34:49]
	v_exp_f32_e32 v78, v78
	v_exp_f32_e32 v79, v79
	v_exp_f32_e32 v80, v80
	v_exp_f32_e32 v81, v81
	s_add_i32 s48, s20, 0x2000
	s_waitcnt vmcnt(2) lgkmcnt(0)
	s_barrier
;   #define RESC() do{ if(!FIXREF&&resc){ asm volatile("s_waitcnt lgkmcnt(0)":::"memory"); \
;       _Pragma("unroll") for(int d_=0;d_<2;++d_) _Pragma("unroll") for(int r=0;r<16;++r)o[d_][r]*=wsf[crow(r,hi)]; } }while(0)
;   #define ROT() do{sl_prev=sl_cur;sl_cur=sl_next;sl_next=(sl_next==(NSLOT-1)*SLOTB)?0:sl_next+SLOTB;}while(0)
;   #define ENDW(tt) do{ if((tt)+3<NT){WAIT_BAR(2);} else if((tt)+2<NT){WAIT_BAR(1);} else {WAIT_BAR(0);} }while(0)
; template<int THRL,bool FIXREF,bool HALFK> __device__ __forceinline__ void attn_unit(float mref,long rowbase,int q0,const bf16*Qh,int PQ,const bf16*__restrict__ Kh_,int PK,const bf16*__restrict__ Vh_,int PV,bf16*Oh,int PO,const bf16*Gh,int PG,u32x4(&okeep)[4],int omode,float lam,float oml,const float ...
;     ...
;   for(;t+1<NT;t+=2){
;     STEP(pB0,pB1,pA0,pA1,t,(t+3<NT),(t+1<NT),(t+1<NT));       ENDW(t);   RESC(); ROT();
	s_cmpk_lg_i32 s20, 0x4000
	s_mov_b32 s87, s85
	s_cselect_b32 s85, s48, 0
	s_add_i32 s84, s84, 2
	v_lshl_add_u64 v[144:145], v[144:145], 0, s[92:93]
	s_mov_b32 s86, s20
	s_cmp_gt_u32 s84, 56
	s_cbranch_scc0 .LBB0_461
	s_and_b32 s20, s83, 0x3fffffc0
	s_lshl_b32 s20, s20, 2
	s_add_i32 s20, s20, 0
	s_cmp_lg_u32 0, -1
	s_cselect_b32 s50, 0, 0
	s_add_i32 s48, s50, 0x6000
	v_add_u32_e32 v0, s48, v216
	v_add3_u32 v0, v0, v215, v217
	ds_read_b64_tr_b16 v[142:143], v213 offset:32768
	ds_read_b64_tr_b16 v[144:145], v213 offset:33280
	v_add_f32_e32 v102, v82, v83
	v_add_f32_e32 v102, v84, v102
	v_add_f32_e32 v102, v85, v102
	v_add_f32_e32 v102, v86, v102
	v_add_f32_e32 v102, v87, v102
	v_cvt_pk_bf16_f32 v158, v82, v83
	v_cvt_pk_bf16_f32 v159, v84, v85
	s_waitcnt lgkmcnt(5)
	v_mfma_f32_32x32x16_bf16 v[114:129], v[98:101], v[166:169], v[50:65]
	ds_read_b64_tr_b16 v[82:83], v213 offset:36864
	ds_read_b64_tr_b16 v[84:85], v213 offset:37376
	v_add_f32_e32 v98, v88, v102
	v_add_f32_e32 v98, v89, v98
	v_add_f32_e32 v98, v90, v98
	v_add_f32_e32 v146, v91, v98
	v_cvt_pk_bf16_f32 v160, v86, v87
	v_cvt_pk_bf16_f32 v161, v88, v89
	s_waitcnt lgkmcnt(6)
	v_mfma_f32_32x32x16_bf16 v[98:113], v[134:137], v[166:169], v[50:65]
	ds_read_b64_tr_b16 v[86:87], v213 offset:33792
	ds_read_b64_tr_b16 v[88:89], v213 offset:34304
	v_add_f32_e32 v134, v92, v146
	v_add_f32_e32 v134, v93, v134
	v_add_f32_e32 v134, v94, v134
	v_add_f32_e32 v134, v95, v134
	v_cvt_pk_bf16_f32 v154, v90, v91
	v_cvt_pk_bf16_f32 v155, v92, v93
	s_waitcnt lgkmcnt(7)
	v_mfma_f32_32x32x16_bf16 v[114:129], v[138:141], v[162:165], v[114:129]
	ds_read_b64_tr_b16 v[90:91], v213 offset:37888
	ds_read_b64_tr_b16 v[92:93], v213 offset:38400
	s_waitcnt lgkmcnt(8)
	v_mfma_f32_32x32x16_bf16 v[98:113], v[130:133], v[162:165], v[98:113]
	v_add_f32_e32 v130, v96, v134
	v_add_f32_e32 v130, v97, v130
	v_add_f32_e32 v130, v66, v130
	v_add_f32_e32 v130, v67, v130
	v_cvt_pk_bf16_f32 v156, v94, v95
	v_cvt_pk_bf16_f32 v157, v96, v97
	ds_read_b64_tr_b16 v[94:95], v213 offset:34816
	ds_read_b64_tr_b16 v[96:97], v213 offset:35328
	v_add_f32_e32 v130, v68, v130
	v_add_f32_e32 v130, v69, v130
	v_add_f32_e32 v130, v70, v130
	v_add_f32_e32 v130, v71, v130
	v_cvt_pk_bf16_f32 v150, v66, v67
	v_cvt_pk_bf16_f32 v151, v68, v69
	ds_read_b64_tr_b16 v[66:67], v213 offset:38912
	ds_read_b64_tr_b16 v[68:69], v213 offset:39424
	v_add_f32_e32 v130, v72, v130
	v_add_f32_e32 v130, v73, v130
	v_add_f32_e32 v130, v74, v130
	v_add_f32_e32 v130, v75, v130
	v_cvt_pk_bf16_f32 v152, v70, v71
	v_cvt_pk_bf16_f32 v153, v72, v73
	ds_read_b64_tr_b16 v[70:71], v213 offset:35840
	ds_read_b64_tr_b16 v[72:73], v213 offset:36352
	v_add_f32_e32 v130, v76, v130
	v_add_f32_e32 v130, v77, v130
	v_add_f32_e32 v130, v78, v130
	v_add_f32_e32 v130, v79, v130
	v_cvt_pk_bf16_f32 v146, v74, v75
	v_cvt_pk_bf16_f32 v147, v76, v77
	ds_read_b64_tr_b16 v[74:75], v213 offset:39936
	ds_read_b64_tr_b16 v[76:77], v213 offset:40448
	v_add_f32_e32 v130, v80, v130
	v_add_f32_e32 v130, v81, v130
	v_cvt_pk_bf16_f32 v148, v78, v79
	v_cvt_pk_bf16_f32 v149, v80, v81
	s_mov_b64 s[48:49], 0x1f0000
	v_lshl_add_u64 v[78:79], v[174:175], 0, s[48:49]
	s_add_i32 s48, s50, s82
	s_add_i32 s49, s48, 0x4000
	s_mov_b32 m0, s49
	s_nop 0
	global_load_lds_dwordx4 v[78:79], off
	v_lshl_add_u64 v[78:79], v[172:173], 0, s[18:19]
	s_mov_b32 m0, s80
	s_nop 0
	global_load_lds_dwordx4 v[78:79], off
	v_add_f32_e32 v215, v227, v130
	s_waitcnt lgkmcnt(14)
	v_mfma_f32_32x32x16_bf16 v[18:33], v[158:161], v[142:145], v[18:33]
	v_exp_f32_e32 v114, v114
	v_exp_f32_e32 v115, v115
	v_exp_f32_e32 v116, v116
	v_exp_f32_e32 v117, v117
	s_waitcnt lgkmcnt(12)
	v_mfma_f32_32x32x16_bf16 v[34:49], v[158:161], v[82:85], v[34:49]
	v_exp_f32_e32 v118, v118
	v_exp_f32_e32 v119, v119
	v_exp_f32_e32 v120, v120
	v_exp_f32_e32 v121, v121
	ds_read_b128 v[78:81], v214
	ds_read_b128 v[82:85], v214 offset:512
	s_waitcnt lgkmcnt(12)
	v_mfma_f32_32x32x16_bf16 v[18:33], v[154:157], v[86:89], v[18:33]
	v_exp_f32_e32 v122, v122
	v_exp_f32_e32 v123, v123
	v_exp_f32_e32 v124, v124
	v_exp_f32_e32 v125, v125
	ds_read_b128 v[86:89], v214 offset:2048
	ds_read_b128 v[228:231], v214 offset:2560
	s_waitcnt lgkmcnt(12)
	v_mfma_f32_32x32x16_bf16 v[34:49], v[154:157], v[90:93], v[34:49]
	v_exp_f32_e32 v126, v126
	v_exp_f32_e32 v127, v127
	v_exp_f32_e32 v128, v128
	v_exp_f32_e32 v129, v129
	s_waitcnt lgkmcnt(10)
	v_mfma_f32_32x32x16_bf16 v[18:33], v[150:153], v[94:97], v[18:33]
	v_exp_f32_e32 v98, v98
	v_exp_f32_e32 v99, v99
	v_exp_f32_e32 v100, v100
	v_exp_f32_e32 v101, v101
	s_waitcnt lgkmcnt(8)
	v_mfma_f32_32x32x16_bf16 v[34:49], v[150:153], v[66:69], v[34:49]
	v_exp_f32_e32 v102, v102
	v_exp_f32_e32 v103, v103
	v_exp_f32_e32 v104, v104
	v_exp_f32_e32 v105, v105
	s_waitcnt lgkmcnt(6)
	v_mfma_f32_32x32x16_bf16 v[18:33], v[146:149], v[70:73], v[18:33]
	v_exp_f32_e32 v106, v106
	v_exp_f32_e32 v107, v107
	v_exp_f32_e32 v108, v108
	v_exp_f32_e32 v109, v109
	s_waitcnt lgkmcnt(4)
	v_mfma_f32_32x32x16_bf16 v[34:49], v[146:149], v[74:77], v[34:49]
	v_exp_f32_e32 v110, v110
	v_exp_f32_e32 v111, v111
	v_exp_f32_e32 v112, v112
	v_exp_f32_e32 v113, v113
	s_waitcnt vmcnt(2) lgkmcnt(0)
	s_barrier
;   #define RESC() do{ if(!FIXREF&&resc){ asm volatile("s_waitcnt lgkmcnt(0)":::"memory"); \
;       _Pragma("unroll") for(int d_=0;d_<2;++d_) _Pragma("unroll") for(int r=0;r<16;++r)o[d_][r]*=wsf[crow(r,hi)]; } }while(0)
;   #define ROT() do{sl_prev=sl_cur;sl_cur=sl_next;sl_next=(sl_next==(NSLOT-1)*SLOTB)?0:sl_next+SLOTB;}while(0)
;   #define ENDW(tt) do{ if((tt)+3<NT){WAIT_BAR(2);} else if((tt)+2<NT){WAIT_BAR(1);} else {WAIT_BAR(0);} }while(0)
; template<int THRL,bool FIXREF,bool HALFK> __device__ __forceinline__ void attn_unit(float mref,long rowbase,int q0,const bf16*Qh,int PQ,const bf16*__restrict__ Kh_,int PK,const bf16*__restrict__ Vh_,int PV,bf16*Oh,int PO,const bf16*Gh,int PG,u32x4(&okeep)[4],int omode,float lam,float oml,const float ...
;     ...
;     STEP(pA0,pA1,pB0,pB1,t+1,(t+4<NT),(t+2<NT),(t+2<NT));     ENDW(t+1); RESC(); ROT();
	ds_read_b64_tr_b16 v[90:91], v213 offset:40960
	ds_read_b64_tr_b16 v[92:93], v213 offset:41472
	v_add_f32_e32 v66, v114, v115
	v_add_f32_e32 v66, v116, v66
	v_add_f32_e32 v66, v117, v66
	v_add_f32_e32 v66, v118, v66
	v_add_f32_e32 v66, v119, v66
	v_cvt_pk_bf16_f32 v158, v114, v115
	v_cvt_pk_bf16_f32 v159, v116, v117
	s_waitcnt lgkmcnt(5)
	v_mfma_f32_32x32x16_bf16 v[130:145], v[78:81], v[166:169], v[50:65]
	ds_read_b64_tr_b16 v[94:95], v213 offset:45056
	ds_read_b64_tr_b16 v[96:97], v213 offset:45568
	v_add_f32_e32 v66, v120, v66
	v_add_f32_e32 v66, v121, v66
	v_add_f32_e32 v66, v122, v66
	v_add_f32_e32 v114, v123, v66
	s_waitcnt lgkmcnt(6)
	v_mfma_f32_32x32x16_bf16 v[66:81], v[82:85], v[166:169], v[50:65]
	v_cvt_pk_bf16_f32 v160, v118, v119
	v_cvt_pk_bf16_f32 v161, v120, v121
	ds_read_b64_tr_b16 v[82:83], v213 offset:41984
	ds_read_b64_tr_b16 v[84:85], v213 offset:42496
	s_waitcnt lgkmcnt(7)
	v_mfma_f32_32x32x16_bf16 v[130:145], v[86:89], v[162:165], v[130:145]
	v_add_f32_e32 v86, v124, v114
	v_add_f32_e32 v86, v125, v86
	v_add_f32_e32 v86, v126, v86
	v_add_f32_e32 v114, v127, v86
	v_cvt_pk_bf16_f32 v154, v122, v123
	v_cvt_pk_bf16_f32 v155, v124, v125
	ds_read_b64_tr_b16 v[86:87], v213 offset:46080
	ds_read_b64_tr_b16 v[88:89], v213 offset:46592
	s_waitcnt lgkmcnt(8)
	v_mfma_f32_32x32x16_bf16 v[66:81], v[228:231], v[162:165], v[66:81]
	v_add_f32_e32 v114, v128, v114
	v_add_f32_e32 v114, v129, v114
	v_add_f32_e32 v114, v98, v114
	v_add_f32_e32 v118, v99, v114
	v_cvt_pk_bf16_f32 v156, v126, v127
	v_cvt_pk_bf16_f32 v157, v128, v129
	ds_read_b64_tr_b16 v[114:115], v213 offset:43008
	ds_read_b64_tr_b16 v[116:117], v213 offset:43520
	v_add_f32_e32 v118, v100, v118
	v_add_f32_e32 v118, v101, v118
	v_add_f32_e32 v118, v102, v118
	v_add_f32_e32 v118, v103, v118
	v_cvt_pk_bf16_f32 v150, v98, v99
	v_cvt_pk_bf16_f32 v151, v100, v101
	ds_read_b64_tr_b16 v[98:99], v213 offset:47104
	ds_read_b64_tr_b16 v[100:101], v213 offset:47616
	v_add_f32_e32 v118, v104, v118
	v_add_f32_e32 v118, v105, v118
	v_add_f32_e32 v118, v106, v118
	v_add_f32_e32 v118, v107, v118
	v_cvt_pk_bf16_f32 v152, v102, v103
	v_cvt_pk_bf16_f32 v153, v104, v105
	ds_read_b64_tr_b16 v[102:103], v213 offset:44032
	ds_read_b64_tr_b16 v[104:105], v213 offset:44544
	v_add_f32_e32 v118, v108, v118
	v_add_f32_e32 v118, v109, v118
	v_add_f32_e32 v118, v110, v118
	v_add_f32_e32 v118, v111, v118
	v_cvt_pk_bf16_f32 v146, v106, v107
	v_cvt_pk_bf16_f32 v147, v108, v109
	ds_read_b64_tr_b16 v[106:107], v213 offset:48128
	ds_read_b64_tr_b16 v[108:109], v213 offset:48640
	v_add_f32_e32 v118, v112, v118
	v_add_f32_e32 v118, v113, v118
	v_cvt_pk_bf16_f32 v148, v110, v111
	v_cvt_pk_bf16_f32 v149, v112, v113
	s_mov_b64 s[50:51], 0x1f8000
	v_lshl_add_u64 v[110:111], v[174:175], 0, s[50:51]
	s_mov_b32 m0, s81
	s_nop 0
	global_load_lds_dwordx4 v[110:111], off
	v_lshl_add_u64 v[110:111], v[172:173], 0, s[6:7]
	s_add_i32 s49, s48, 0x8000
	s_mov_b32 m0, s49
	s_nop 0
	global_load_lds_dwordx4 v[110:111], off
	v_add_f32_e32 v215, v215, v118
	s_waitcnt lgkmcnt(14)
	v_mfma_f32_32x32x16_bf16 v[18:33], v[158:161], v[90:93], v[18:33]
	v_exp_f32_e32 v130, v130
	v_exp_f32_e32 v131, v131
	v_exp_f32_e32 v132, v132
	v_exp_f32_e32 v133, v133
	s_waitcnt lgkmcnt(12)
	v_mfma_f32_32x32x16_bf16 v[34:49], v[158:161], v[94:97], v[34:49]
	v_exp_f32_e32 v134, v134
	v_exp_f32_e32 v135, v135
	v_exp_f32_e32 v136, v136
	v_exp_f32_e32 v137, v137
	ds_read_b128 v[90:93], v214 offset:8192
	ds_read_b128 v[110:113], v214 offset:8704
	s_waitcnt lgkmcnt(12)
	v_mfma_f32_32x32x16_bf16 v[18:33], v[154:157], v[82:85], v[18:33]
	v_exp_f32_e32 v138, v138
	v_exp_f32_e32 v139, v139
	v_exp_f32_e32 v140, v140
	v_exp_f32_e32 v141, v141
	ds_read_b128 v[228:231], v214 offset:10240
	ds_read_b128 v[232:235], v214 offset:10752
	s_waitcnt lgkmcnt(12)
	v_mfma_f32_32x32x16_bf16 v[34:49], v[154:157], v[86:89], v[34:49]
	v_exp_f32_e32 v142, v142
	v_exp_f32_e32 v143, v143
	v_exp_f32_e32 v144, v144
	v_exp_f32_e32 v145, v145
	s_waitcnt lgkmcnt(10)
	v_mfma_f32_32x32x16_bf16 v[18:33], v[150:153], v[114:117], v[18:33]
	v_exp_f32_e32 v66, v66
	v_exp_f32_e32 v67, v67
	v_exp_f32_e32 v68, v68
	v_exp_f32_e32 v69, v69
	s_waitcnt lgkmcnt(8)
	v_mfma_f32_32x32x16_bf16 v[34:49], v[150:153], v[98:101], v[34:49]
	v_exp_f32_e32 v70, v70
	v_exp_f32_e32 v71, v71
	v_exp_f32_e32 v72, v72
	v_exp_f32_e32 v73, v73
	s_waitcnt lgkmcnt(6)
	v_mfma_f32_32x32x16_bf16 v[18:33], v[146:149], v[102:105], v[18:33]
	v_exp_f32_e32 v74, v74
	v_exp_f32_e32 v75, v75
	v_exp_f32_e32 v76, v76
	v_exp_f32_e32 v77, v77
	s_waitcnt lgkmcnt(4)
	v_mfma_f32_32x32x16_bf16 v[34:49], v[146:149], v[106:109], v[34:49]
	v_exp_f32_e32 v78, v78
	v_exp_f32_e32 v79, v79
	v_exp_f32_e32 v80, v80
	v_exp_f32_e32 v81, v81
	s_waitcnt vmcnt(2) lgkmcnt(0)
	s_barrier
;   #define RESC() do{ if(!FIXREF&&resc){ asm volatile("s_waitcnt lgkmcnt(0)":::"memory"); \
;       _Pragma("unroll") for(int d_=0;d_<2;++d_) _Pragma("unroll") for(int r=0;r<16;++r)o[d_][r]*=wsf[crow(r,hi)]; } }while(0)
;   #define ROT() do{sl_prev=sl_cur;sl_cur=sl_next;sl_next=(sl_next==(NSLOT-1)*SLOTB)?0:sl_next+SLOTB;}while(0)
;   #define ENDW(tt) do{ if((tt)+3<NT){WAIT_BAR(2);} else if((tt)+2<NT){WAIT_BAR(1);} else {WAIT_BAR(0);} }while(0)
; template<int THRL,bool FIXREF,bool HALFK> __device__ __forceinline__ void attn_unit(float mref,long rowbase,int q0,const bf16*Qh,int PQ,const bf16*__restrict__ Kh_,int PK,const bf16*__restrict__ Vh_,int PV,bf16*Oh,int PO,const bf16*Gh,int PG,u32x4(&okeep)[4],int omode,float lam,float oml,const float ...
;     ...
;     STEP(pA0,pA1,pB0,pB1,t+1,(t+4<NT),(t+2<NT),(t+2<NT));     ENDW(t+1); RESC(); ROT();
	ds_read_b64_tr_b16 v[98:99], v213 offset:24576
	ds_read_b64_tr_b16 v[100:101], v213 offset:25088
	v_add_f32_e32 v82, v130, v131
	v_add_f32_e32 v82, v132, v82
	v_add_f32_e32 v82, v133, v82
	v_add_f32_e32 v82, v134, v82
	v_add_f32_e32 v82, v135, v82
	v_cvt_pk_bf16_f32 v158, v130, v131
	v_cvt_pk_bf16_f32 v159, v132, v133
	s_waitcnt lgkmcnt(5)
	v_mfma_f32_32x32x16_bf16 v[114:129], v[90:93], v[166:169], v[50:65]
	ds_read_b64_tr_b16 v[102:103], v213 offset:28672
	ds_read_b64_tr_b16 v[104:105], v213 offset:29184
	v_add_f32_e32 v82, v136, v82
	v_add_f32_e32 v82, v137, v82
	v_add_f32_e32 v82, v138, v82
	v_add_f32_e32 v130, v139, v82
	v_cvt_pk_bf16_f32 v160, v134, v135
	v_cvt_pk_bf16_f32 v161, v136, v137
	s_waitcnt lgkmcnt(6)
	v_mfma_f32_32x32x16_bf16 v[82:97], v[110:113], v[166:169], v[50:65]
	ds_read_b64_tr_b16 v[106:107], v213 offset:25600
	ds_read_b64_tr_b16 v[108:109], v213 offset:26112
	v_add_f32_e32 v110, v140, v130
	v_add_f32_e32 v110, v141, v110
	v_add_f32_e32 v110, v142, v110
	v_add_f32_e32 v130, v143, v110
	v_cvt_pk_bf16_f32 v154, v138, v139
	v_cvt_pk_bf16_f32 v155, v140, v141
	s_waitcnt lgkmcnt(7)
	v_mfma_f32_32x32x16_bf16 v[114:129], v[228:231], v[162:165], v[114:129]
	ds_read_b64_tr_b16 v[110:111], v213 offset:29696
	ds_read_b64_tr_b16 v[112:113], v213 offset:30208
	v_add_f32_e32 v130, v144, v130
	v_add_f32_e32 v130, v145, v130
	v_add_f32_e32 v130, v66, v130
	v_add_f32_e32 v134, v67, v130
	v_cvt_pk_bf16_f32 v156, v142, v143
	v_cvt_pk_bf16_f32 v157, v144, v145
	s_waitcnt lgkmcnt(8)
	v_mfma_f32_32x32x16_bf16 v[82:97], v[232:235], v[162:165], v[82:97]
	ds_read_b64_tr_b16 v[130:131], v213 offset:26624
	ds_read_b64_tr_b16 v[132:133], v213 offset:27136
	v_add_f32_e32 v134, v68, v134
	v_add_f32_e32 v134, v69, v134
	v_add_f32_e32 v134, v70, v134
	v_add_f32_e32 v134, v71, v134
	v_cvt_pk_bf16_f32 v150, v66, v67
	v_cvt_pk_bf16_f32 v151, v68, v69
	ds_read_b64_tr_b16 v[66:67], v213 offset:30720
	ds_read_b64_tr_b16 v[68:69], v213 offset:31232
	v_add_f32_e32 v134, v72, v134
	v_add_f32_e32 v134, v73, v134
	v_add_f32_e32 v134, v74, v134
	v_add_f32_e32 v134, v75, v134
	v_cvt_pk_bf16_f32 v152, v70, v71
	v_cvt_pk_bf16_f32 v153, v72, v73
	ds_read_b64_tr_b16 v[70:71], v213 offset:27648
	ds_read_b64_tr_b16 v[72:73], v213 offset:28160
	v_add_f32_e32 v134, v76, v134
	v_add_f32_e32 v134, v77, v134
	v_add_f32_e32 v134, v78, v134
	v_add_f32_e32 v134, v79, v134
	v_cvt_pk_bf16_f32 v146, v74, v75
	v_cvt_pk_bf16_f32 v147, v76, v77
	ds_read_b64_tr_b16 v[74:75], v213 offset:31744
	ds_read_b64_tr_b16 v[76:77], v213 offset:32256
	v_add_f32_e32 v134, v80, v134
	v_add_f32_e32 v134, v81, v134
	v_cvt_pk_bf16_f32 v148, v78, v79
	v_cvt_pk_bf16_f32 v149, v80, v81
	v_lshl_add_u64 v[78:79], v[172:173], 0, s[94:95]
	s_add_i32 s48, s48, 0xa000
	s_mov_b32 m0, s48
	s_nop 0
	global_load_lds_dwordx4 v[78:79], off
	v_add_f32_e32 v174, v215, v134
	s_waitcnt lgkmcnt(14)
	v_mfma_f32_32x32x16_bf16 v[18:33], v[158:161], v[98:101], v[18:33]
	v_exp_f32_e32 v114, v114
	v_exp_f32_e32 v115, v115
	v_exp_f32_e32 v116, v116
	v_exp_f32_e32 v117, v117
	s_waitcnt lgkmcnt(12)
	v_mfma_f32_32x32x16_bf16 v[34:49], v[158:161], v[102:105], v[34:49]
	v_exp_f32_e32 v118, v118
	v_exp_f32_e32 v119, v119
	v_exp_f32_e32 v120, v120
	v_exp_f32_e32 v121, v121
	ds_read_b128 v[78:81], v214 offset:16384
	ds_read_b128 v[134:137], v214 offset:16896
	s_waitcnt lgkmcnt(12)
	v_mfma_f32_32x32x16_bf16 v[18:33], v[154:157], v[106:109], v[18:33]
	v_exp_f32_e32 v122, v122
	v_exp_f32_e32 v123, v123
	v_exp_f32_e32 v124, v124
	v_exp_f32_e32 v125, v125
	ds_read_b128 v[138:141], v214 offset:18432
	ds_read_b128 v[142:145], v214 offset:18944
	s_waitcnt lgkmcnt(12)
	v_mfma_f32_32x32x16_bf16 v[34:49], v[154:157], v[110:113], v[34:49]
	v_exp_f32_e32 v126, v126
	v_exp_f32_e32 v127, v127
	v_exp_f32_e32 v128, v128
	v_exp_f32_e32 v129, v129
	s_waitcnt lgkmcnt(10)
	v_mfma_f32_32x32x16_bf16 v[18:33], v[150:153], v[130:133], v[18:33]
	v_exp_f32_e32 v82, v82
	v_exp_f32_e32 v83, v83
	v_exp_f32_e32 v84, v84
	v_exp_f32_e32 v85, v85
	s_waitcnt lgkmcnt(8)
	v_mfma_f32_32x32x16_bf16 v[34:49], v[150:153], v[66:69], v[34:49]
	v_exp_f32_e32 v86, v86
	v_exp_f32_e32 v87, v87
	v_exp_f32_e32 v88, v88
	v_exp_f32_e32 v89, v89
	s_waitcnt lgkmcnt(6)
	v_mfma_f32_32x32x16_bf16 v[18:33], v[146:149], v[70:73], v[18:33]
	v_exp_f32_e32 v90, v90
	v_exp_f32_e32 v91, v91
	v_exp_f32_e32 v92, v92
	v_exp_f32_e32 v93, v93
	s_waitcnt lgkmcnt(4)
	v_mfma_f32_32x32x16_bf16 v[34:49], v[146:149], v[74:77], v[34:49]
	v_exp_f32_e32 v94, v94
	v_exp_f32_e32 v95, v95
	v_exp_f32_e32 v96, v96
	v_exp_f32_e32 v97, v97
	s_waitcnt vmcnt(1) lgkmcnt(0)
	s_barrier
;   #define RESC() do{ if(!FIXREF&&resc){ asm volatile("s_waitcnt lgkmcnt(0)":::"memory"); \
;       _Pragma("unroll") for(int d_=0;d_<2;++d_) _Pragma("unroll") for(int r=0;r<16;++r)o[d_][r]*=wsf[crow(r,hi)]; } }while(0)
;   #define ROT() do{sl_prev=sl_cur;sl_cur=sl_next;sl_next=(sl_next==(NSLOT-1)*SLOTB)?0:sl_next+SLOTB;}while(0)
;   #define ENDW(tt) do{ if((tt)+3<NT){WAIT_BAR(2);} else if((tt)+2<NT){WAIT_BAR(1);} else {WAIT_BAR(0);} }while(0)
; template<int THRL,bool FIXREF,bool HALFK> __device__ __forceinline__ void attn_unit(float mref,long rowbase,int q0,const bf16*Qh,int PQ,const bf16*__restrict__ Kh_,int PK,const bf16*__restrict__ Vh_,int PV,bf16*Oh,int PO,const bf16*Gh,int PG,u32x4(&okeep)[4],int omode,float lam,float oml,const float ...
;     ...
;     STEP(pA0,pA1,pB0,pB1,t+1,(t+4<NT),(t+2<NT),(t+2<NT));     ENDW(t+1); RESC(); ROT();
	ds_read_b64_tr_b16 v[130:131], v213 offset:32768
	ds_read_b64_tr_b16 v[132:133], v213 offset:33280
	v_add_f32_e32 v66, v114, v115
	v_add_f32_e32 v66, v116, v66
	v_add_f32_e32 v66, v117, v66
	v_add_f32_e32 v66, v118, v66
	v_add_f32_e32 v66, v119, v66
	v_cvt_pk_bf16_f32 v158, v114, v115
	v_cvt_pk_bf16_f32 v159, v116, v117
	s_waitcnt lgkmcnt(5)
	v_mfma_f32_32x32x16_bf16 v[98:113], v[78:81], v[166:169], v[50:65]
	ds_read_b64_tr_b16 v[114:115], v213 offset:36864
	ds_read_b64_tr_b16 v[116:117], v213 offset:37376
	v_add_f32_e32 v66, v120, v66
	v_add_f32_e32 v66, v121, v66
	v_add_f32_e32 v66, v122, v66
	v_add_f32_e32 v146, v123, v66
	s_waitcnt lgkmcnt(6)
	v_mfma_f32_32x32x16_bf16 v[66:81], v[134:137], v[166:169], v[50:65]
	v_cvt_pk_bf16_f32 v160, v118, v119
	v_cvt_pk_bf16_f32 v161, v120, v121
	ds_read_b64_tr_b16 v[118:119], v213 offset:33792
	ds_read_b64_tr_b16 v[120:121], v213 offset:34304
	v_add_f32_e32 v134, v124, v146
	v_add_f32_e32 v134, v125, v134
	v_add_f32_e32 v134, v126, v134
	s_waitcnt lgkmcnt(7)
	v_mfma_f32_32x32x16_bf16 v[98:113], v[138:141], v[162:165], v[98:113]
	v_add_f32_e32 v138, v127, v134
	v_cvt_pk_bf16_f32 v154, v122, v123
	v_cvt_pk_bf16_f32 v155, v124, v125
	ds_read_b64_tr_b16 v[134:135], v213 offset:37888
	ds_read_b64_tr_b16 v[136:137], v213 offset:38400
	s_waitcnt lgkmcnt(8)
	v_mfma_f32_32x32x16_bf16 v[66:81], v[142:145], v[162:165], v[66:81]
	v_add_f32_e32 v122, v128, v138
	v_add_f32_e32 v122, v129, v122
	v_add_f32_e32 v122, v82, v122
	v_add_f32_e32 v122, v83, v122
	v_cvt_pk_bf16_f32 v156, v126, v127
	v_cvt_pk_bf16_f32 v157, v128, v129
	ds_read_b64_tr_b16 v[124:125], v213 offset:34816
	ds_read_b64_tr_b16 v[126:127], v213 offset:35328
	v_add_f32_e32 v122, v84, v122
	v_add_f32_e32 v122, v85, v122
	v_add_f32_e32 v122, v86, v122
	v_add_f32_e32 v122, v87, v122
	v_cvt_pk_bf16_f32 v150, v82, v83
	v_cvt_pk_bf16_f32 v151, v84, v85
	ds_read_b64_tr_b16 v[82:83], v213 offset:38912
	ds_read_b64_tr_b16 v[84:85], v213 offset:39424
	v_add_f32_e32 v122, v88, v122
	v_add_f32_e32 v122, v89, v122
	v_add_f32_e32 v122, v90, v122
	v_add_f32_e32 v122, v91, v122
	v_cvt_pk_bf16_f32 v152, v86, v87
	v_cvt_pk_bf16_f32 v153, v88, v89
	ds_read_b64_tr_b16 v[86:87], v213 offset:35840
	ds_read_b64_tr_b16 v[88:89], v213 offset:36352
	v_add_f32_e32 v122, v92, v122
	v_add_f32_e32 v122, v93, v122
	v_add_f32_e32 v122, v94, v122
	v_add_f32_e32 v122, v95, v122
	v_cvt_pk_bf16_f32 v146, v90, v91
	v_cvt_pk_bf16_f32 v147, v92, v93
	ds_read_b64_tr_b16 v[90:91], v213 offset:39936
	ds_read_b64_tr_b16 v[92:93], v213 offset:40448
	v_add_f32_e32 v122, v96, v122
	v_add_f32_e32 v122, v97, v122
	v_cvt_pk_bf16_f32 v148, v94, v95
	v_cvt_pk_bf16_f32 v149, v96, v97
	v_lshl_add_u64 v[94:95], v[172:173], 0, s[26:27]
	s_mov_b32 m0, s80
	s_nop 0
	global_load_lds_dwordx4 v[94:95], off
	v_add_f32_e32 v122, v174, v122
	s_waitcnt lgkmcnt(14)
	v_mfma_f32_32x32x16_bf16 v[18:33], v[158:161], v[130:133], v[18:33]
	v_exp_f32_e32 v98, v98
	v_exp_f32_e32 v99, v99
	v_exp_f32_e32 v100, v100
	v_exp_f32_e32 v101, v101
	s_waitcnt lgkmcnt(12)
	v_mfma_f32_32x32x16_bf16 v[34:49], v[158:161], v[114:117], v[34:49]
	v_exp_f32_e32 v102, v102
	v_exp_f32_e32 v103, v103
	v_exp_f32_e32 v104, v104
	v_exp_f32_e32 v105, v105
	ds_read_b128 v[128:131], v214
	ds_read_b128 v[138:141], v214 offset:512
	s_waitcnt lgkmcnt(12)
	v_mfma_f32_32x32x16_bf16 v[18:33], v[154:157], v[118:121], v[18:33]
	v_exp_f32_e32 v106, v106
	v_exp_f32_e32 v107, v107
	v_exp_f32_e32 v108, v108
	v_exp_f32_e32 v109, v109
	ds_read_b128 v[142:145], v214 offset:2048
	ds_read_b128 v[172:175], v214 offset:2560
	s_waitcnt lgkmcnt(12)
	v_mfma_f32_32x32x16_bf16 v[34:49], v[154:157], v[134:137], v[34:49]
	v_exp_f32_e32 v110, v110
	v_exp_f32_e32 v111, v111
	v_exp_f32_e32 v112, v112
	v_exp_f32_e32 v113, v113
	s_waitcnt lgkmcnt(10)
	v_mfma_f32_32x32x16_bf16 v[18:33], v[150:153], v[124:127], v[18:33]
	v_exp_f32_e32 v66, v66
	v_exp_f32_e32 v67, v67
	v_exp_f32_e32 v68, v68
	v_exp_f32_e32 v69, v69
	s_waitcnt lgkmcnt(8)
	v_mfma_f32_32x32x16_bf16 v[34:49], v[150:153], v[82:85], v[34:49]
	v_exp_f32_e32 v70, v70
	v_exp_f32_e32 v71, v71
	v_exp_f32_e32 v72, v72
	v_exp_f32_e32 v73, v73
	s_waitcnt lgkmcnt(6)
	v_mfma_f32_32x32x16_bf16 v[18:33], v[146:149], v[86:89], v[18:33]
	v_exp_f32_e32 v74, v74
	v_exp_f32_e32 v75, v75
	v_exp_f32_e32 v76, v76
	v_exp_f32_e32 v77, v77
	s_waitcnt lgkmcnt(4)
	v_mfma_f32_32x32x16_bf16 v[34:49], v[146:149], v[90:93], v[34:49]
	v_exp_f32_e32 v78, v78
	v_exp_f32_e32 v79, v79
	v_exp_f32_e32 v80, v80
	v_exp_f32_e32 v81, v81
	s_waitcnt vmcnt(0) lgkmcnt(0)
	s_barrier
; #define SBAR() __builtin_amdgcn_sched_barrier(0)
;   #define RESC() do{ if(!FIXREF&&resc){ asm volatile("s_waitcnt lgkmcnt(0)":::"memory"); \
;       _Pragma("unroll") for(int d_=0;d_<2;++d_) _Pragma("unroll") for(int r=0;r<16;++r)o[d_][r]*=wsf[crow(r,hi)]; } }while(0)
;   #define PKW(P,B) cvtpk_s(P[B],P[B+1])
; template<int THRL,bool FIXREF,bool HALFK> __device__ __forceinline__ void attn_unit(float mref,long rowbase,int q0,const bf16*Qh,int PQ,const bf16*__restrict__ Kh_,int PK,const bf16*__restrict__ Vh_,int PV,bf16*Oh,int PO,const bf16*Gh,int PG,u32x4(&okeep)[4],int omode,float lam,float oml,const float ...
;     ...
;   STEP(pB0,pB1,pA0,pA1,NT-1,false,false,false); RESC();
;   { float sacc=pB0[0]+pB0[1]; _Pragma("unroll") for(int r=2;r<16;++r)sacc+=pB0[r]; _Pragma("unroll") for(int r=0;r<16;++r)sacc+=pB1[r]; l_reg+=sacc;
;     pw0=(u32x4){PKW(pB0,0),PKW(pB0,2),PKW(pB0,4),PKW(pB0,6)};pw1=(u32x4){PKW(pB0,8),PKW(pB0,10),PKW(pB0,12),PKW(pB0,14)};pw2=(u32x4){PKW(pB1,0),PKW(pB1,2),PKW(pB1,4),PKW(pB1,6)};pw3=(u32x4){PKW(pB1,8),PKW(pB1,10),PKW(pB1,12),PKW(pB1,14)};
;     SBAR(); pv(o,vb0+sl_cur,PAF(0),PAF(1),PAF(2),PAF(3)); }
	ds_read_b64_tr_b16 v[114:115], v213 offset:40960
	ds_read_b64_tr_b16 v[116:117], v213 offset:41472
	v_add_f32_e32 v82, v98, v99
	v_add_f32_e32 v82, v100, v82
	v_add_f32_e32 v82, v101, v82
	v_add_f32_e32 v82, v102, v82
	v_add_f32_e32 v118, v103, v82
	v_cvt_pk_bf16_f32 v158, v98, v99
	v_cvt_pk_bf16_f32 v159, v100, v101
	s_waitcnt lgkmcnt(5)
	v_mfma_f32_32x32x16_bf16 v[82:97], v[128:131], v[166:169], v[50:65]
	ds_read_b64_tr_b16 v[98:99], v213 offset:45056
	ds_read_b64_tr_b16 v[100:101], v213 offset:45568
	v_add_f32_e32 v118, v104, v118
	v_add_f32_e32 v118, v105, v118
	v_add_f32_e32 v118, v106, v118
	v_add_f32_e32 v123, v107, v118
	v_cvt_pk_bf16_f32 v160, v102, v103
	v_cvt_pk_bf16_f32 v161, v104, v105
	s_waitcnt lgkmcnt(6)
	v_mfma_f32_32x32x16_bf16 v[50:65], v[138:141], v[166:169], v[50:65]
	ds_read_b64_tr_b16 v[118:119], v213 offset:41984
	ds_read_b64_tr_b16 v[120:121], v213 offset:42496
	v_add_f32_e32 v102, v108, v123
	v_add_f32_e32 v102, v109, v102
	v_add_f32_e32 v102, v110, v102
	v_add_f32_e32 v123, v111, v102
	v_cvt_pk_bf16_f32 v154, v106, v107
	v_cvt_pk_bf16_f32 v155, v108, v109
	s_waitcnt lgkmcnt(7)
	v_mfma_f32_32x32x16_bf16 v[82:97], v[142:145], v[162:165], v[82:97]
	ds_read_b64_tr_b16 v[102:103], v213 offset:46080
	ds_read_b64_tr_b16 v[104:105], v213 offset:46592
	v_add_f32_e32 v106, v112, v123
	v_add_f32_e32 v106, v113, v106
	v_add_f32_e32 v106, v66, v106
	v_add_f32_e32 v123, v67, v106
	v_cvt_pk_bf16_f32 v156, v110, v111
	v_cvt_pk_bf16_f32 v157, v112, v113
	s_waitcnt lgkmcnt(8)
	v_mfma_f32_32x32x16_bf16 v[50:65], v[172:175], v[162:165], v[50:65]
	ds_read_b64_tr_b16 v[106:107], v213 offset:43008
	ds_read_b64_tr_b16 v[108:109], v213 offset:43520
	v_add_f32_e32 v110, v68, v123
	v_add_f32_e32 v110, v69, v110
	v_add_f32_e32 v110, v70, v110
	v_add_f32_e32 v110, v71, v110
	v_cvt_pk_bf16_f32 v150, v66, v67
	v_cvt_pk_bf16_f32 v151, v68, v69
	ds_read_b64_tr_b16 v[66:67], v213 offset:47104
	ds_read_b64_tr_b16 v[68:69], v213 offset:47616
	v_add_f32_e32 v110, v72, v110
	v_add_f32_e32 v110, v73, v110
	v_add_f32_e32 v110, v74, v110
	v_add_f32_e32 v123, v75, v110
	v_cvt_pk_bf16_f32 v152, v70, v71
	v_cvt_pk_bf16_f32 v153, v72, v73
	ds_read_b64_tr_b16 v[110:111], v213 offset:44032
	ds_read_b64_tr_b16 v[112:113], v213 offset:44544
	v_add_f32_e32 v70, v76, v123
	v_add_f32_e32 v70, v77, v70
	v_add_f32_e32 v70, v78, v70
	v_add_f32_e32 v123, v79, v70
	v_cvt_pk_bf16_f32 v146, v74, v75
	v_cvt_pk_bf16_f32 v147, v76, v77
	ds_read_b64_tr_b16 v[70:71], v213 offset:48128
	ds_read_b64_tr_b16 v[72:73], v213 offset:48640
	v_add_f32_e32 v74, v80, v123
	v_add_f32_e32 v74, v81, v74
	v_cvt_pk_bf16_f32 v148, v78, v79
	v_cvt_pk_bf16_f32 v149, v80, v81
	v_exp_f32_e32 v82, v82
	v_exp_f32_e32 v83, v83
	v_exp_f32_e32 v84, v84
	v_exp_f32_e32 v85, v85
	s_nop 0
	v_exp_f32_e32 v86, v86
	v_exp_f32_e32 v87, v87
	v_exp_f32_e32 v88, v88
	v_exp_f32_e32 v89, v89
	s_nop 0
	v_exp_f32_e32 v90, v90
	v_exp_f32_e32 v91, v91
	v_exp_f32_e32 v92, v92
	v_exp_f32_e32 v93, v93
	s_nop 0
	v_exp_f32_e32 v94, v94
	v_exp_f32_e32 v95, v95
	v_exp_f32_e32 v96, v96
	v_exp_f32_e32 v97, v97
	v_exp_f32_e32 v50, v50
	v_exp_f32_e32 v51, v51
	v_exp_f32_e32 v52, v52
	v_exp_f32_e32 v53, v53
	s_nop 0
	v_exp_f32_e32 v54, v54
	v_exp_f32_e32 v55, v55
	v_exp_f32_e32 v56, v56
	v_exp_f32_e32 v57, v57
	s_nop 0
	v_exp_f32_e32 v58, v58
	v_exp_f32_e32 v59, v59
	v_exp_f32_e32 v60, v60
	v_exp_f32_e32 v61, v61
	s_nop 0
	v_exp_f32_e32 v62, v62
	v_exp_f32_e32 v63, v63
	v_exp_f32_e32 v64, v64
	v_exp_f32_e32 v65, v65
	s_waitcnt lgkmcnt(14)
	v_mfma_f32_32x32x16_bf16 v[18:33], v[158:161], v[114:117], v[18:33]
	v_add_f32_e32 v75, v82, v83
	v_add_f32_e32 v75, v84, v75
	v_add_f32_e32 v75, v85, v75
	v_add_f32_e32 v75, v86, v75
	v_add_f32_e32 v75, v87, v75
	v_add_f32_e32 v75, v88, v75
	v_add_f32_e32 v75, v89, v75
	s_waitcnt lgkmcnt(12)
	v_mfma_f32_32x32x16_bf16 v[34:49], v[158:161], v[98:101], v[34:49]
	v_add_f32_e32 v75, v90, v75
	v_add_f32_e32 v75, v91, v75
	v_add_f32_e32 v75, v92, v75
	v_add_f32_e32 v75, v93, v75
	v_add_f32_e32 v75, v94, v75
	v_add_f32_e32 v75, v95, v75
	v_add_f32_e32 v75, v96, v75
	s_waitcnt lgkmcnt(10)
	v_mfma_f32_32x32x16_bf16 v[18:33], v[154:157], v[118:121], v[18:33]
	v_add_f32_e32 v75, v97, v75
	v_add_f32_e32 v75, v50, v75
	v_add_f32_e32 v75, v51, v75
	v_add_f32_e32 v75, v52, v75
	v_add_f32_e32 v75, v53, v75
	v_add_f32_e32 v75, v54, v75
	v_add_f32_e32 v75, v55, v75
	s_waitcnt lgkmcnt(8)
	v_mfma_f32_32x32x16_bf16 v[34:49], v[154:157], v[102:105], v[34:49]
	v_add_f32_e32 v75, v56, v75
	v_add_f32_e32 v75, v57, v75
	v_add_f32_e32 v75, v58, v75
	v_add_f32_e32 v75, v59, v75
	v_add_f32_e32 v75, v60, v75
	v_add_f32_e32 v75, v61, v75
	v_add_f32_e32 v75, v62, v75
	s_waitcnt lgkmcnt(6)
	v_mfma_f32_32x32x16_bf16 v[18:33], v[150:153], v[106:109], v[18:33]
	v_add_f32_e32 v75, v63, v75
	v_add_f32_e32 v75, v64, v75
	v_add_f32_e32 v75, v65, v75
	v_add_f32_e32 v74, v122, v74
	v_add_f32_e32 v74, v74, v75
	v_cvt_pk_bf16_f32 v76, v82, v83
	v_cvt_pk_bf16_f32 v77, v84, v85
	s_waitcnt lgkmcnt(4)
	v_mfma_f32_32x32x16_bf16 v[34:49], v[150:153], v[66:69], v[34:49]
	v_cvt_pk_bf16_f32 v78, v86, v87
	v_cvt_pk_bf16_f32 v79, v88, v89
	v_cvt_pk_bf16_f32 v80, v90, v91
	v_cvt_pk_bf16_f32 v81, v92, v93
	v_cvt_pk_bf16_f32 v82, v94, v95
	v_cvt_pk_bf16_f32 v83, v96, v97
	v_cvt_pk_bf16_f32 v50, v50, v51
	s_waitcnt lgkmcnt(2)
	v_mfma_f32_32x32x16_bf16 v[18:33], v[146:149], v[110:113], v[18:33]
	v_cvt_pk_bf16_f32 v51, v52, v53
	v_cvt_pk_bf16_f32 v52, v54, v55
	v_cvt_pk_bf16_f32 v53, v56, v57
	v_cvt_pk_bf16_f32 v54, v58, v59
	v_cvt_pk_bf16_f32 v55, v60, v61
	v_cvt_pk_bf16_f32 v56, v62, v63
	v_cvt_pk_bf16_f32 v57, v64, v65
	s_waitcnt lgkmcnt(0)
; #define SBAR() __builtin_amdgcn_sched_barrier(0)
; __device__ __forceinline__ void pv(f32x16*o,int vb,bf16x8 pa0,bf16x8 pa1,bf16x8 pa2,bf16x8 pa3){
;   #pragma unroll
;   for(int d0=0;d0<2;++d0){s16x4 lo[4],hi[4];
;     #pragma unroll
;     for(int ks=0;ks<4;++ks){
;       asm volatile("ds_read_b64_tr_b16 %0,%1 offset:%c2":"=&v"(lo[ks]):"v"(vb),"i"(d0*4096+ks*1024):"memory");
;       asm volatile("ds_read_b64_tr_b16 %0,%1 offset:%c2":"=&v"(hi[ks]):"v"(vb),"i"(d0*4096+ks*1024+512):"memory");}
;     asm volatile("s_waitcnt lgkmcnt(0)":::"memory");SBAR();
;     ...
;     o[d0]=__builtin_amdgcn_mfma_f32_32x32x16_bf16(pa0,PK(0),o[d0],0,0,0);
;     o[d0]=__builtin_amdgcn_mfma_f32_32x32x16_bf16(pa1,PK(1),o[d0],0,0,0);
;     o[d0]=__builtin_amdgcn_mfma_f32_32x32x16_bf16(pa2,PK(2),o[d0],0,0,0);
;     o[d0]=__builtin_amdgcn_mfma_f32_32x32x16_bf16(pa3,PK(3),o[d0],0,0,0);
;     ...
;   }
; }
; template<int THRL,bool FIXREF,bool HALFK> __device__ __forceinline__ void attn_unit(float mref,long rowbase,int q0,const bf16*Qh,int PQ,const bf16*__restrict__ Kh_,int PK,const bf16*__restrict__ Vh_,int PV,bf16*Oh,int PO,const bf16*Gh,int PG,u32x4(&okeep)[4],int omode,float lam,float oml,const float ...
;     ...
;   STEP(pB0,pB1,pA0,pA1,NT-1,false,false,false); RESC();
;   { float sacc=pB0[0]+pB0[1]; _Pragma("unroll") for(int r=2;r<16;++r)sacc+=pB0[r]; _Pragma("unroll") for(int r=0;r<16;++r)sacc+=pB1[r]; l_reg+=sacc;
;     pw0=(u32x4){PKW(pB0,0),PKW(pB0,2),PKW(pB0,4),PKW(pB0,6)};pw1=(u32x4){PKW(pB0,8),PKW(pB0,10),PKW(pB0,12),PKW(pB0,14)};pw2=(u32x4){PKW(pB1,0),PKW(pB1,2),PKW(pB1,4),PKW(pB1,6)};pw3=(u32x4){PKW(pB1,8),PKW(pB1,10),PKW(pB1,12),PKW(pB1,14)};
;     SBAR(); pv(o,vb0+sl_cur,PAF(0),PAF(1),PAF(2),PAF(3)); }
;     ...
;   {auto rr=__builtin_amdgcn_permlane32_swap(__float_as_uint(l_reg),__float_as_uint(l_reg),false,false);l_reg=__uint_as_float(rr[0])+__uint_as_float(rr[1]);}
;   if(hi==0)wsf[32+r32]=l_reg;asm volatile("s_waitcnt lgkmcnt(0)":::"memory");
;   float rli[16];
;   #pragma unroll
;   for(int r=0;r<16;++r)rli[r]=__builtin_amdgcn_rcpf(wsf[32+crow(r,hi)]);
;   bf16*Ow=Oh+(rowbase+q0+wid*QBLK)*PO;
;   { bf16*stg=(bf16*)(shm+LDS_OST)+wid*2048;
;     #pragma unroll
;     for(int r=0;r<16;++r){const int orow=crow(r,hi);
;       #pragma unroll
;       for(int d0=0;d0<2;++d0)stg[orow*64+d0*32+r32]=__float2bfloat16(o[d0][r]*rli[r]);}
;     asm volatile("s_waitcnt lgkmcnt(0)":::"memory");
	v_mfma_f32_32x32x16_bf16 v[34:49], v[146:149], v[70:73], v[34:49]
	ds_read_b64_tr_b16 v[58:59],v0 offset:0
	ds_read_b64_tr_b16 v[60:61],v0 offset:512
	ds_read_b64_tr_b16 v[62:63],v0 offset:1024
	ds_read_b64_tr_b16 v[64:65],v0 offset:1536
	ds_read_b64_tr_b16 v[66:67],v0 offset:2048
	ds_read_b64_tr_b16 v[68:69],v0 offset:2560
	ds_read_b64_tr_b16 v[70:71],v0 offset:3072
	ds_read_b64_tr_b16 v[72:73],v0 offset:3584
	s_waitcnt lgkmcnt(0)
	s_nop 0
	v_mfma_f32_32x32x16_bf16 v[18:33], v[76:79], v[58:61], v[18:33]
	ds_read_b64_tr_b16 v[58:59],v0 offset:4096
	ds_read_b64_tr_b16 v[60:61],v0 offset:4608
	v_mfma_f32_32x32x16_bf16 v[18:33], v[80:83], v[62:65], v[18:33]
	ds_read_b64_tr_b16 v[62:63],v0 offset:5120
	ds_read_b64_tr_b16 v[64:65],v0 offset:5632
	v_mfma_f32_32x32x16_bf16 v[18:33], v[50:53], v[66:69], v[18:33]
	ds_read_b64_tr_b16 v[66:67],v0 offset:6144
	ds_read_b64_tr_b16 v[68:69],v0 offset:6656
	v_mfma_f32_32x32x16_bf16 v[18:33], v[54:57], v[70:73], v[18:33]
	ds_read_b64_tr_b16 v[70:71],v0 offset:7168
	ds_read_b64_tr_b16 v[72:73],v0 offset:7680
	s_waitcnt lgkmcnt(0)
	v_mfma_f32_32x32x16_bf16 v[34:49], v[76:79], v[58:61], v[34:49]
	v_mov_b32_e32 v0, v74
	s_nop 1
	v_permlane32_swap_b32_e32 v74, v0
	v_cmp_gt_u32_e32 vcc, 32, v209
	v_mfma_f32_32x32x16_bf16 v[34:49], v[80:83], v[62:65], v[34:49]
	v_mfma_f32_32x32x16_bf16 v[34:49], v[50:53], v[66:69], v[34:49]
	v_mfma_f32_32x32x16_bf16 v[34:49], v[54:57], v[70:73], v[34:49]
	s_and_saveexec_b64 s[48:49], vcc
	v_lshl_add_u32 v50, v171, 2, s20
	v_add_f32_e32 v0, v74, v0
	ds_write_b32 v50, v0 offset:49280
	s_or_b64 exec, exec, s[48:49]
	s_waitcnt lgkmcnt(0)
	v_lshl_add_u32 v0, v212, 4, s20
	ds_read_b128 v[50:53], v0 offset:49280
	ds_read_b128 v[54:57], v0 offset:49312
	s_lshl_b32 s20, s79, 12
	s_add_i32 s20, s20, 0
	v_lshlrev_b32_e32 v66, 1, v171
	s_waitcnt lgkmcnt(1)
	v_rcp_f32_e32 v58, v50
	v_rcp_f32_e32 v59, v51
	v_rcp_f32_e32 v60, v52
	v_rcp_f32_e32 v61, v53
	s_waitcnt lgkmcnt(0)
	v_rcp_f32_e32 v62, v54
	ds_read_b128 v[50:53], v0 offset:49344
	v_rcp_f32_e32 v63, v55
	v_rcp_f32_e32 v64, v56
	v_rcp_f32_e32 v65, v57
	ds_read_b128 v[54:57], v0 offset:49376
	s_waitcnt lgkmcnt(1)
	v_rcp_f32_e32 v0, v50
	v_rcp_f32_e32 v50, v51
	v_rcp_f32_e32 v51, v52
	v_rcp_f32_e32 v52, v53
	s_waitcnt lgkmcnt(0)
	v_rcp_f32_e32 v53, v54
	v_rcp_f32_e32 v54, v55
	v_rcp_f32_e32 v55, v56
	v_rcp_f32_e32 v56, v57
	v_lshlrev_b32_e32 v57, 9, v212
	v_mul_f32_e32 v18, v18, v58
	v_add3_u32 v57, s20, v57, v66
	v_cvt_pk_bf16_f32 v18, v18, s0
	ds_write_b16 v57, v18 offset:51200
	v_mul_f32_e32 v18, v34, v58
	v_cvt_pk_bf16_f32 v18, v18, s0
	ds_write_b16 v57, v18 offset:51264
	v_mul_f32_e32 v18, v19, v59
	v_cvt_pk_bf16_f32 v18, v18, s0
	ds_write_b16 v57, v18 offset:51328
	v_mul_f32_e32 v18, v35, v59
	v_cvt_pk_bf16_f32 v18, v18, s0
	ds_write_b16 v57, v18 offset:51392
	v_mul_f32_e32 v18, v20, v60
	v_cvt_pk_bf16_f32 v18, v18, s0
	ds_write_b16 v57, v18 offset:51456
	v_mul_f32_e32 v18, v36, v60
	v_cvt_pk_bf16_f32 v18, v18, s0
	ds_write_b16 v57, v18 offset:51520
	v_mul_f32_e32 v18, v21, v61
	v_cvt_pk_bf16_f32 v18, v18, s0
	ds_write_b16 v57, v18 offset:51584
	v_mul_f32_e32 v18, v37, v61
	v_cvt_pk_bf16_f32 v18, v18, s0
	ds_write_b16 v57, v18 offset:51648
	v_mul_f32_e32 v18, v22, v62
	v_cvt_pk_bf16_f32 v18, v18, s0
	ds_write_b16 v57, v18 offset:52224
	v_mul_f32_e32 v18, v38, v62
	v_cvt_pk_bf16_f32 v18, v18, s0
	ds_write_b16 v57, v18 offset:52288
	v_mul_f32_e32 v18, v23, v63
	v_cvt_pk_bf16_f32 v18, v18, s0
	ds_write_b16 v57, v18 offset:52352
	v_mul_f32_e32 v18, v39, v63
	v_cvt_pk_bf16_f32 v18, v18, s0
	ds_write_b16 v57, v18 offset:52416
	v_mul_f32_e32 v18, v24, v64
	v_cvt_pk_bf16_f32 v18, v18, s0
	ds_write_b16 v57, v18 offset:52480
	v_mul_f32_e32 v18, v40, v64
	v_cvt_pk_bf16_f32 v18, v18, s0
	ds_write_b16 v57, v18 offset:52544
	v_mul_f32_e32 v18, v25, v65
	v_cvt_pk_bf16_f32 v18, v18, s0
	ds_write_b16 v57, v18 offset:52608
	v_mul_f32_e32 v18, v41, v65
	v_cvt_pk_bf16_f32 v18, v18, s0
	ds_write_b16 v57, v18 offset:52672
	v_mul_f32_e32 v18, v26, v0
	v_mul_f32_e32 v0, v42, v0
	v_cvt_pk_bf16_f32 v0, v0, s0
	ds_write_b16 v57, v0 offset:53312
	v_mul_f32_e32 v0, v27, v50
	v_cvt_pk_bf16_f32 v0, v0, s0
	ds_write_b16 v57, v0 offset:53376
	v_mul_f32_e32 v0, v43, v50
	v_cvt_pk_bf16_f32 v0, v0, s0
	ds_write_b16 v57, v0 offset:53440
	v_mul_f32_e32 v0, v28, v51
	v_cvt_pk_bf16_f32 v0, v0, s0
	ds_write_b16 v57, v0 offset:53504
	v_mul_f32_e32 v0, v44, v51
	v_cvt_pk_bf16_f32 v0, v0, s0
	ds_write_b16 v57, v0 offset:53568
	v_mul_f32_e32 v0, v29, v52
	v_cvt_pk_bf16_f32 v0, v0, s0
	ds_write_b16 v57, v0 offset:53632
	v_mul_f32_e32 v0, v45, v52
	v_cvt_pk_bf16_f32 v0, v0, s0
	ds_write_b16 v57, v0 offset:53696
	v_mul_f32_e32 v0, v30, v53
	v_cvt_pk_bf16_f32 v0, v0, s0
	ds_write_b16 v57, v0 offset:54272
	v_mul_f32_e32 v0, v46, v53
	v_cvt_pk_bf16_f32 v0, v0, s0
	ds_write_b16 v57, v0 offset:54336
	v_mul_f32_e32 v0, v31, v54
	v_cvt_pk_bf16_f32 v0, v0, s0
	ds_write_b16 v57, v0 offset:54400
	v_mul_f32_e32 v0, v47, v54
	v_cvt_pk_bf16_f32 v0, v0, s0
	ds_write_b16 v57, v0 offset:54464
	v_mul_f32_e32 v0, v32, v55
	v_cvt_pk_bf16_f32 v0, v0, s0
	ds_write_b16 v57, v0 offset:54528
	v_mul_f32_e32 v0, v48, v55
	v_cvt_pk_bf16_f32 v0, v0, s0
	ds_write_b16 v57, v0 offset:54592
	v_mul_f32_e32 v0, v33, v56
	v_cvt_pk_bf16_f32 v0, v0, s0
	ds_write_b16 v57, v0 offset:54656
	v_mul_f32_e32 v0, v49, v56
	v_cvt_pk_bf16_f32 v18, v18, s0
	v_cvt_pk_bf16_f32 v0, v0, s0
	ds_write_b16 v57, v18 offset:53248
	ds_write_b16 v57, v0 offset:54720
	s_lshl_b64 s[46:47], s[46:47], 11
	s_waitcnt lgkmcnt(0)
	s_add_u32 s46, s69, s46
	s_addc_u32 s47, s70, s47
	s_mov_b64 s[48:49], -1
	s_and_b64 vcc, exec, s[42:43]
	s_cbranch_vccz .LBB0_470
; __device__ __forceinline__ unsigned cvtpk_s(float lo,float hi){f32x2_t v={lo,hi};bf16x2_t b=__builtin_convertvector(v,bf16x2_t);return __builtin_bit_cast(unsigned,b);}
; template<int THRL,bool FIXREF,bool HALFK> __device__ __forceinline__ void attn_unit(float mref,long rowbase,int q0,const bf16*Qh,int PQ,const bf16*__restrict__ Kh_,int PK,const bf16*__restrict__ Vh_,int PV,bf16*Oh,int PO,const bf16*Gh,int PG,u32x4(&okeep)[4],int omode,float lam,float oml,const float ...
;     ...
;     else if(Gh){
;       u32x4 gv[4]; const char*gst=shm+LDS_GST+wid*4096+lane*16;
;       #pragma unroll
;       for(int i=0;i<4;++i) gv[i]=*(const u32x4*)(gst+i*1024);
;       #pragma unroll
;       for(int i=0;i<4;++i){const int row=i*8+(lane>>3),ch=lane&7; u32x4 v=*(const u32x4*)(stg+row*64+ch*8);
;         #pragma unroll
;         for(int k=0;k<4;++k){ const float g0=__uint_as_float(gv[i][k]<<16),g1=__uint_as_float(gv[i][k]&0xffff0000u),o0=__uint_as_float(v[k]<<16),o1=__uint_as_float(v[k]&0xffff0000u);
;           v[k]=cvtpk_s(o0*g0*__builtin_amdgcn_rcpf(1.f+__builtin_amdgcn_exp2f(-1.4426950408889634f*g0)),o1*g1*__builtin_amdgcn_rcpf(1.f+__builtin_amdgcn_exp2f(-1.4426950408889634f*g1))); }
;         ATTN_STORE16(Ow+(long)row*PO+ch*8,v);} }
	s_mov_b64 s[42:43], -1
	s_and_b64 vcc, exec, s[40:41]
	s_cbranch_vccz .LBB0_467
	v_lshl_add_u32 v0, v209, 4, s20
	v_add_u32_e32 v0, 0x14800, v0
	ds_read_b128 v[30:33], v0
	ds_read_b128 v[26:29], v0 offset:1024
	ds_read_b128 v[22:25], v0 offset:2048
	ds_read_b128 v[18:21], v0 offset:3072
	v_lshlrev_b32_e32 v0, 1, v211
	v_and_b32_e32 v0, 0x70, v0
	v_add_u32_e32 v36, s20, v0
	v_lshl_add_u64 v[34:35], s[46:47], 0, v[0:1]
	v_lshl_add_u32 v0, v208, 7, v36
	s_waitcnt lgkmcnt(3)
	v_lshlrev_b32_e32 v44, 16, v30
	ds_read_b128 v[38:41], v0 offset:51200
	v_mul_f32_e32 v0, 0xbfb8aa3b, v44
	v_exp_f32_e32 v0, v0
	v_and_b32_e32 v43, 0xffff0000, v30
	s_mov_b64 s[42:43], 0
	s_waitcnt lgkmcnt(0)
	v_lshlrev_b32_e32 v42, 16, v38
	v_add_f32_e32 v0, 1.0, v0
	v_rcp_f32_e32 v46, v0
	v_mul_f32_e32 v0, 0xbfb8aa3b, v43
	v_exp_f32_e32 v0, v0
	v_and_b32_e32 v45, 0xffff0000, v38
	v_lshlrev_b32_e32 v38, 16, v31
	v_pk_mul_f32 v[44:45], v[42:43], v[44:45]
	v_add_f32_e32 v0, 1.0, v0
	v_rcp_f32_e32 v47, v0
	v_mul_f32_e32 v0, 0xbfb8aa3b, v38
	v_exp_f32_e32 v0, v0
	v_pk_mul_f32 v[42:43], v[46:47], v[44:45]
	s_nop 0
	v_cvt_pk_bf16_f32 v30, v42, v43
	v_and_b32_e32 v43, 0xffff0000, v31
	v_add_f32_e32 v0, 1.0, v0
	v_rcp_f32_e32 v44, v0
	v_mul_f32_e32 v0, 0xbfb8aa3b, v43
	v_exp_f32_e32 v0, v0
	v_lshlrev_b32_e32 v42, 16, v39
	v_and_b32_e32 v39, 0xffff0000, v39
	v_pk_mul_f32 v[38:39], v[42:43], v[38:39]
	v_add_f32_e32 v0, 1.0, v0
	v_lshlrev_b32_e32 v42, 16, v32
	v_rcp_f32_e32 v45, v0
	v_mul_f32_e32 v0, 0xbfb8aa3b, v42
	v_exp_f32_e32 v0, v0
	v_and_b32_e32 v43, 0xffff0000, v40
	v_pk_mul_f32 v[38:39], v[44:45], v[38:39]
	v_add_f32_e32 v0, 1.0, v0
	v_cvt_pk_bf16_f32 v31, v38, v39
	v_and_b32_e32 v39, 0xffff0000, v32
	v_rcp_f32_e32 v44, v0
	v_mul_f32_e32 v0, 0xbfb8aa3b, v39
	v_exp_f32_e32 v0, v0
	v_lshlrev_b32_e32 v38, 16, v40
	v_lshlrev_b32_e32 v40, 16, v33
	v_pk_mul_f32 v[42:43], v[38:39], v[42:43]
	v_add_f32_e32 v0, 1.0, v0
	v_rcp_f32_e32 v45, v0
	v_mul_f32_e32 v0, 0xbfb8aa3b, v40
	v_exp_f32_e32 v0, v0
	v_pk_mul_f32 v[38:39], v[44:45], v[42:43]
	s_nop 0
	v_cvt_pk_bf16_f32 v32, v38, v39
	v_and_b32_e32 v39, 0xffff0000, v33
	v_add_f32_e32 v0, 1.0, v0
	v_rcp_f32_e32 v42, v0
	v_mul_f32_e32 v0, 0xbfb8aa3b, v39
	v_exp_f32_e32 v0, v0
	v_lshlrev_b32_e32 v38, 16, v41
	v_and_b32_e32 v41, 0xffff0000, v41
	v_pk_mul_f32 v[40:41], v[38:39], v[40:41]
	v_add_f32_e32 v0, 1.0, v0
	v_rcp_f32_e32 v43, v0
	v_lshlrev_b32_e32 v0, 11, v208
	v_pk_mul_f32 v[38:39], v[42:43], v[40:41]
	s_nop 0
	v_cvt_pk_bf16_f32 v33, v38, v39
	v_lshl_add_u64 v[38:39], v[34:35], 0, v[0:1]
	v_lshlrev_b32_e32 v40, 16, v26
	global_store_dwordx4 v[38:39], v[30:33], off
	v_and_b32_e32 v39, 0xffff0000, v26
	v_mul_f32_e32 v26, 0xbfb8aa3b, v40
	v_exp_f32_e32 v26, v26
	v_or_b32_e32 v0, 8, v208
	v_lshl_add_u32 v30, v0, 7, v36
	ds_read_b128 v[30:33], v30 offset:51200
	v_add_f32_e32 v26, 1.0, v26
	v_rcp_f32_e32 v42, v26
	v_mul_f32_e32 v26, 0xbfb8aa3b, v39
	v_exp_f32_e32 v26, v26
	s_waitcnt lgkmcnt(0)
	v_lshlrev_b32_e32 v38, 16, v30
	v_and_b32_e32 v41, 0xffff0000, v30
	v_pk_mul_f32 v[40:41], v[38:39], v[40:41]
	v_add_f32_e32 v26, 1.0, v26
	v_rcp_f32_e32 v43, v26
	v_lshlrev_b32_e32 v30, 16, v27
	v_lshlrev_b32_e32 v0, 11, v0
	v_pk_mul_f32 v[38:39], v[42:43], v[40:41]
	s_nop 0
	v_cvt_pk_bf16_f32 v26, v38, v39
	v_and_b32_e32 v39, 0xffff0000, v27
	v_mul_f32_e32 v27, 0xbfb8aa3b, v30
	v_exp_f32_e32 v27, v27
	v_lshlrev_b32_e32 v38, 16, v31
	v_and_b32_e32 v31, 0xffff0000, v31
	v_pk_mul_f32 v[30:31], v[38:39], v[30:31]
	v_add_f32_e32 v27, 1.0, v27
	v_rcp_f32_e32 v40, v27
	v_mul_f32_e32 v27, 0xbfb8aa3b, v39
	v_exp_f32_e32 v27, v27
	v_lshlrev_b32_e32 v38, 16, v28
	v_and_b32_e32 v39, 0xffff0000, v32
	v_add_f32_e32 v27, 1.0, v27
	v_rcp_f32_e32 v41, v27
	s_nop 0
	v_pk_mul_f32 v[30:31], v[40:41], v[30:31]
	s_nop 0
	v_cvt_pk_bf16_f32 v27, v30, v31
	v_and_b32_e32 v31, 0xffff0000, v28
	v_mul_f32_e32 v28, 0xbfb8aa3b, v38
	v_exp_f32_e32 v28, v28
	v_lshlrev_b32_e32 v30, 16, v32
	v_pk_mul_f32 v[38:39], v[30:31], v[38:39]
	v_lshlrev_b32_e32 v32, 16, v29
	v_add_f32_e32 v28, 1.0, v28
	v_rcp_f32_e32 v40, v28
	v_mul_f32_e32 v28, 0xbfb8aa3b, v31
	v_exp_f32_e32 v28, v28
	s_nop 0
	v_add_f32_e32 v28, 1.0, v28
	v_rcp_f32_e32 v41, v28
	s_nop 0
	v_pk_mul_f32 v[30:31], v[40:41], v[38:39]
	s_nop 0
	v_cvt_pk_bf16_f32 v28, v30, v31
	v_and_b32_e32 v31, 0xffff0000, v29
	v_mul_f32_e32 v29, 0xbfb8aa3b, v32
	v_exp_f32_e32 v29, v29
	v_lshlrev_b32_e32 v30, 16, v33
	v_and_b32_e32 v33, 0xffff0000, v33
	v_pk_mul_f32 v[32:33], v[30:31], v[32:33]
	v_add_f32_e32 v29, 1.0, v29
	v_rcp_f32_e32 v38, v29
	v_mul_f32_e32 v29, 0xbfb8aa3b, v31
	v_exp_f32_e32 v29, v29
	s_nop 0
	v_add_f32_e32 v29, 1.0, v29
	v_rcp_f32_e32 v39, v29
	s_nop 0
	v_pk_mul_f32 v[30:31], v[38:39], v[32:33]
	s_nop 0
	v_cvt_pk_bf16_f32 v29, v30, v31
	v_lshl_add_u64 v[30:31], v[34:35], 0, v[0:1]
	v_lshlrev_b32_e32 v32, 16, v22
	global_store_dwordx4 v[30:31], v[26:29], off
	v_and_b32_e32 v31, 0xffff0000, v22
	v_mul_f32_e32 v22, 0xbfb8aa3b, v32
	v_exp_f32_e32 v22, v22
	v_or_b32_e32 v0, 16, v208
	v_lshl_add_u32 v26, v0, 7, v36
	ds_read_b128 v[26:29], v26 offset:51200
	v_add_f32_e32 v22, 1.0, v22
	v_rcp_f32_e32 v38, v22
	v_mul_f32_e32 v22, 0xbfb8aa3b, v31
	v_exp_f32_e32 v22, v22
	s_waitcnt lgkmcnt(0)
; __device__ __forceinline__ unsigned cvtpk_s(float lo,float hi){f32x2_t v={lo,hi};bf16x2_t b=__builtin_convertvector(v,bf16x2_t);return __builtin_bit_cast(unsigned,b);}
; template<int THRL,bool FIXREF,bool HALFK> __device__ __forceinline__ void attn_unit(float mref,long rowbase,int q0,const bf16*Qh,int PQ,const bf16*__restrict__ Kh_,int PK,const bf16*__restrict__ Vh_,int PV,bf16*Oh,int PO,const bf16*Gh,int PG,u32x4(&okeep)[4],int omode,float lam,float oml,const float ...
;     ...
;     else if(Gh){
;       u32x4 gv[4]; const char*gst=shm+LDS_GST+wid*4096+lane*16;
;       #pragma unroll
;       for(int i=0;i<4;++i) gv[i]=*(const u32x4*)(gst+i*1024);
;       #pragma unroll
;       for(int i=0;i<4;++i){const int row=i*8+(lane>>3),ch=lane&7; u32x4 v=*(const u32x4*)(stg+row*64+ch*8);
;         #pragma unroll
;         for(int k=0;k<4;++k){ const float g0=__uint_as_float(gv[i][k]<<16),g1=__uint_as_float(gv[i][k]&0xffff0000u),o0=__uint_as_float(v[k]<<16),o1=__uint_as_float(v[k]&0xffff0000u);
;           v[k]=cvtpk_s(o0*g0*__builtin_amdgcn_rcpf(1.f+__builtin_amdgcn_exp2f(-1.4426950408889634f*g0)),o1*g1*__builtin_amdgcn_rcpf(1.f+__builtin_amdgcn_exp2f(-1.4426950408889634f*g1))); }
;         ATTN_STORE16(Ow+(long)row*PO+ch*8,v);} }
	v_lshlrev_b32_e32 v30, 16, v26
	v_and_b32_e32 v33, 0xffff0000, v26
	v_pk_mul_f32 v[32:33], v[30:31], v[32:33]
	v_add_f32_e32 v22, 1.0, v22
	v_rcp_f32_e32 v39, v22
	v_lshlrev_b32_e32 v26, 16, v23
	v_lshlrev_b32_e32 v0, 11, v0
	v_pk_mul_f32 v[30:31], v[38:39], v[32:33]
	s_nop 0
	v_cvt_pk_bf16_f32 v22, v30, v31
	v_and_b32_e32 v31, 0xffff0000, v23
	v_mul_f32_e32 v23, 0xbfb8aa3b, v26
	v_exp_f32_e32 v23, v23
	v_lshlrev_b32_e32 v30, 16, v27
	v_and_b32_e32 v27, 0xffff0000, v27
	v_pk_mul_f32 v[26:27], v[30:31], v[26:27]
	v_add_f32_e32 v23, 1.0, v23
	v_rcp_f32_e32 v32, v23
	v_mul_f32_e32 v23, 0xbfb8aa3b, v31
	v_exp_f32_e32 v23, v23
	v_lshlrev_b32_e32 v30, 16, v24
	v_and_b32_e32 v31, 0xffff0000, v28
	v_add_f32_e32 v23, 1.0, v23
	v_rcp_f32_e32 v33, v23
	s_nop 0
	v_pk_mul_f32 v[26:27], v[32:33], v[26:27]
	s_nop 0
	v_cvt_pk_bf16_f32 v23, v26, v27
	v_and_b32_e32 v27, 0xffff0000, v24
	v_mul_f32_e32 v24, 0xbfb8aa3b, v30
	v_exp_f32_e32 v24, v24
	v_lshlrev_b32_e32 v26, 16, v28
	v_pk_mul_f32 v[30:31], v[26:27], v[30:31]
	v_lshlrev_b32_e32 v28, 16, v25
	v_add_f32_e32 v24, 1.0, v24
	v_rcp_f32_e32 v32, v24
	v_mul_f32_e32 v24, 0xbfb8aa3b, v27
	v_exp_f32_e32 v24, v24
	s_nop 0
	v_add_f32_e32 v24, 1.0, v24
	v_rcp_f32_e32 v33, v24
	s_nop 0
	v_pk_mul_f32 v[26:27], v[32:33], v[30:31]
	s_nop 0
	v_cvt_pk_bf16_f32 v24, v26, v27
	v_and_b32_e32 v27, 0xffff0000, v25
	v_mul_f32_e32 v25, 0xbfb8aa3b, v28
	v_exp_f32_e32 v25, v25
	v_lshlrev_b32_e32 v26, 16, v29
	v_and_b32_e32 v29, 0xffff0000, v29
	v_pk_mul_f32 v[28:29], v[26:27], v[28:29]
	v_add_f32_e32 v25, 1.0, v25
	v_rcp_f32_e32 v30, v25
	v_mul_f32_e32 v25, 0xbfb8aa3b, v27
	v_exp_f32_e32 v25, v25
	s_nop 0
	v_add_f32_e32 v25, 1.0, v25
	v_rcp_f32_e32 v31, v25
	s_nop 0
	v_pk_mul_f32 v[26:27], v[30:31], v[28:29]
	s_nop 0
	v_cvt_pk_bf16_f32 v25, v26, v27
	v_lshl_add_u64 v[26:27], v[34:35], 0, v[0:1]
	v_lshlrev_b32_e32 v28, 16, v18
	global_store_dwordx4 v[26:27], v[22:25], off
	v_and_b32_e32 v27, 0xffff0000, v18
	v_mul_f32_e32 v18, 0xbfb8aa3b, v28
	v_exp_f32_e32 v18, v18
	v_or_b32_e32 v0, 24, v208
	v_lshl_add_u32 v22, v0, 7, v36
	ds_read_b128 v[22:25], v22 offset:51200
	v_add_f32_e32 v18, 1.0, v18
	v_rcp_f32_e32 v30, v18
	v_mul_f32_e32 v18, 0xbfb8aa3b, v27
	v_exp_f32_e32 v18, v18
	s_waitcnt lgkmcnt(0)
	v_lshlrev_b32_e32 v26, 16, v22
	v_and_b32_e32 v29, 0xffff0000, v22
	v_pk_mul_f32 v[28:29], v[26:27], v[28:29]
	v_add_f32_e32 v18, 1.0, v18
	v_rcp_f32_e32 v31, v18
	v_lshlrev_b32_e32 v22, 16, v19
	v_lshlrev_b32_e32 v0, 11, v0
	v_pk_mul_f32 v[26:27], v[30:31], v[28:29]
	s_nop 0
	v_cvt_pk_bf16_f32 v18, v26, v27
	v_and_b32_e32 v27, 0xffff0000, v19
	v_mul_f32_e32 v19, 0xbfb8aa3b, v22
	v_exp_f32_e32 v19, v19
	v_lshlrev_b32_e32 v26, 16, v23
	v_and_b32_e32 v23, 0xffff0000, v23
	v_pk_mul_f32 v[22:23], v[26:27], v[22:23]
	v_add_f32_e32 v19, 1.0, v19
	v_rcp_f32_e32 v28, v19
	v_mul_f32_e32 v19, 0xbfb8aa3b, v27
	v_exp_f32_e32 v19, v19
	v_lshlrev_b32_e32 v26, 16, v20
	v_and_b32_e32 v27, 0xffff0000, v24
	v_add_f32_e32 v19, 1.0, v19
	v_rcp_f32_e32 v29, v19
	s_nop 0
	v_pk_mul_f32 v[22:23], v[28:29], v[22:23]
	s_nop 0
	v_cvt_pk_bf16_f32 v19, v22, v23
	v_and_b32_e32 v23, 0xffff0000, v20
	v_mul_f32_e32 v20, 0xbfb8aa3b, v26
	v_exp_f32_e32 v20, v20
	v_lshlrev_b32_e32 v22, 16, v24
	v_pk_mul_f32 v[26:27], v[22:23], v[26:27]
	v_lshlrev_b32_e32 v24, 16, v21
	v_add_f32_e32 v20, 1.0, v20
	v_rcp_f32_e32 v28, v20
	v_mul_f32_e32 v20, 0xbfb8aa3b, v23
	v_exp_f32_e32 v20, v20
	s_nop 0
	v_add_f32_e32 v20, 1.0, v20
	v_rcp_f32_e32 v29, v20
	s_nop 0
	v_pk_mul_f32 v[22:23], v[28:29], v[26:27]
	s_nop 0
	v_cvt_pk_bf16_f32 v20, v22, v23
	v_and_b32_e32 v23, 0xffff0000, v21
	v_mul_f32_e32 v21, 0xbfb8aa3b, v24
	v_exp_f32_e32 v21, v21
	v_lshlrev_b32_e32 v22, 16, v25
	v_and_b32_e32 v25, 0xffff0000, v25
	v_pk_mul_f32 v[24:25], v[22:23], v[24:25]
	v_add_f32_e32 v21, 1.0, v21
	v_rcp_f32_e32 v26, v21
	v_mul_f32_e32 v21, 0xbfb8aa3b, v23
	v_exp_f32_e32 v21, v21
	s_nop 0
	v_add_f32_e32 v21, 1.0, v21
	v_rcp_f32_e32 v27, v21
	s_nop 0
	v_pk_mul_f32 v[22:23], v[26:27], v[24:25]
	s_nop 0
	v_cvt_pk_bf16_f32 v21, v22, v23
	v_lshl_add_u64 v[22:23], v[34:35], 0, v[0:1]
	global_store_dwordx4 v[22:23], v[18:21], off
